# v22 + first 4 MFMAs of every compute segment hoisted above the segment barrier (behind the wave's own lgkmcnt wait)
# speedup vs baseline: 1.0096x; 1.0033x over previous
;     __host__ __device__ bool next(int i, Unit& u) const { const bool ok = StaticOrder::next(i, u); u.lm = 0; u.ln = 0; return ok; }
; #define PG8_STAGE(bufoff, gbase, voff) do { _Pragma("unroll") for (int _i = 0; _i < 2; ++_i) \
;         __builtin_amdgcn_global_load_lds((const unsigned*)((const char*)(gbase) + (voff)[_i]), (PG8_LAS unsigned*)(lds + (bufoff) + ldsw + _i * 8192), 16, 0, 0); } while (0)
; #define PG8_LDA(dst, b, h) do { _Pragma("unroll") for (int m = 0; m < 4; ++m) _Pragma("unroll") for (int k = 0; k < 2; ++k) dst[m][k] = *(const PG8_LAS bf16x8*)(lds + PG8_SA(b, h) + aoff + m * 2048 + k * 1024); } while (0)
; #define PG8_LDB(dst, b, h) do { _Pragma("unroll") for (int n = 0; n < 2; ++n) _Pragma("unroll") for (int k = 0; k < 2; ++k) dst[n][k] = *(const PG8_LAS bf16x8*)(lds + PG8_SB(b, h) + boff + n * 2048 + k * 1024); } while (0)
; #define PG8_WAIT_V(n) asm volatile("s_waitcnt vmcnt(" #n ")" ::: "memory")
; #define PG8_BAR __builtin_amdgcn_s_barrier()
; template <class Epi, class Sched, bool ALIGN_EPI = false, bool SP2 = false>
; __device__ __forceinline__ void gemm_phase(PG8_LAS unsigned char* lds, const Gemm g, const Sched& S, const Epi& E, const int wave_id) {
;     ...
;         const bool has_next = S.next(ui + 1, nxt);
;         const char* nA = has_next ? (const char*)g.A + (size_t)nxt.lm * tstep : cA; const char* nB = has_next ? (const char*)g.Bt + (size_t)nxt.ln * tstep : cB;
; #pragma unroll 1
;         for (int t = 0; t < nt; t += 2) {
;             const bool last = (t == nt - 2);
;             const char* a1 = cA + (size_t)(t + 1) * kstep;
;             const char* a2 = last ? nA : cA + (size_t)(t + 2) * kstep; const char* b2 = last ? nB : cB + (size_t)(t + 2) * kstep;
;             const char* a3 = a2 + kstep; const char* b3 = b2 + kstep;
;             if (last && has_next) S.a_ready(nxt);
;             if constexpr (SP2) {
;             PG8_LDB(B0, 0, 0); PG8_LDB(B1, 0, 1); PG8_SCHED; PG8_LDA(At, 0, 0); PG8_STAGE(PG8_SA(1, 1), a1 + hstep, voffA);
;             PG8_WAIT_V(8); PG8_WAIT_L(0); PG8_BAR; PG8_MMA(0, 0, At, B0); PG8_MMA(0, 1, At, B1); PG8_BAR; PG8_SCHED;
;             PG8_LDA(At, 0, 1); PG8_STAGE(PG8_SB(0, 0), b2, voffB); PG8_STAGE(PG8_SB(0, 1), b2 + hstep, voffB); PG8_STAGE(PG8_SA(0, 0), a2, voffA);
;             PG8_WAIT_V(8); PG8_WAIT_L(0); PG8_BAR; PG8_MMA(1, 0, At, B0); PG8_MMA(1, 1, At, B1); PG8_BAR; PG8_SCHED;
.LBB0_173:
	s_ashr_i32 s15, s14, 31
	s_lshl_b64 s[16:17], s[14:15], 20
	s_add_u32 s16, s49, s16
	s_addc_u32 s17, s52, s17
	s_and_b64 s[18:19], s[38:39], exec
	s_cselect_b32 s15, s17, s21
	s_cselect_b32 s41, s16, s20
	s_ashr_i32 s13, s12, 31
	s_lshl_b64 s[18:19], s[12:13], 20
	s_add_u32 s18, s47, s18
	s_addc_u32 s19, s48, s19
	s_and_b64 s[44:45], s[38:39], exec
	s_cselect_b32 s13, s19, s43
	s_cselect_b32 s72, s18, s42
	s_add_u32 s20, s20, 0x80080
	s_addc_u32 s21, s21, 0
	s_add_u32 s73, s42, 0x100
	s_addc_u32 s74, s43, 0
	s_mov_b32 s75, -2
	v_add_u32_e32 v230, 0x10000, v171
	s_add_u32 s42, s20, 0xfff80080
	s_addc_u32 s43, s21, -1
	s_add_i32 s76, 0, 0x10000
	s_cmp_eq_u32 s75, 28
	s_cselect_b32 s45, s15, s43
	s_cselect_b32 s44, s41, s42
	s_cselect_b32 s43, s13, s74
	s_cselect_b32 s42, s72, s73
	s_add_i32 s79, 0, 0x14000
	s_add_i32 m0, s56, 0xc000
	s_nop 0
	global_load_lds_dwordx4 v138, s[20:21]
	ds_read_b128 v[142:145], v230
	ds_read_b128 v[146:149], v230 offset:1024
	ds_read_b128 v[150:153], v230 offset:2048
	ds_read_b128 v[154:157], v230 offset:3072
	ds_read_b128 v[158:161], v230 offset:16384
	ds_read_b128 v[162:165], v230 offset:17408
	ds_read_b128 v[166:169], v230 offset:18432
	ds_read_b128 v[178:181], v230 offset:19456
	s_add_i32 m0, s56, 0xe000
	s_nop 0
	global_load_lds_dwordx4 v140, s[20:21]
	ds_read_b128 v[182:185], v175
	ds_read_b128 v[186:189], v175 offset:1024
	ds_read_b128 v[190:193], v175 offset:2048
	ds_read_b128 v[206:209], v175 offset:3072
	ds_read_b128 v[210:213], v175 offset:4096
	ds_read_b128 v[214:217], v175 offset:5120
	ds_read_b128 v[226:229], v175 offset:6144
	ds_read_b128 v[234:237], v175 offset:7168
	s_waitcnt lgkmcnt(0)
	s_setprio 1
	v_mfma_f32_16x16x32_bf16 v[126:129], v[142:145], v[182:185], 0
	v_mfma_f32_16x16x32_bf16 v[118:121], v[150:153], v[182:185], 0
	v_mfma_f32_16x16x32_bf16 v[110:113], v[142:145], v[190:193], 0
	v_mfma_f32_16x16x32_bf16 v[102:105], v[150:153], v[190:193], 0
	s_waitcnt vmcnt(8)
	s_barrier
	v_mfma_f32_16x16x32_bf16 v[94:97], v[142:145], v[210:213], 0
	v_mfma_f32_16x16x32_bf16 v[86:89], v[150:153], v[210:213], 0
	v_mfma_f32_16x16x32_bf16 v[78:81], v[142:145], v[226:229], 0
	v_mfma_f32_16x16x32_bf16 v[70:73], v[150:153], v[226:229], 0
	v_mfma_f32_16x16x32_bf16 v[126:129], v[146:149], v[186:189], v[126:129]
	v_mfma_f32_16x16x32_bf16 v[118:121], v[154:157], v[186:189], v[118:121]
	v_mfma_f32_16x16x32_bf16 v[110:113], v[146:149], v[206:209], v[110:113]
	v_mfma_f32_16x16x32_bf16 v[102:105], v[154:157], v[206:209], v[102:105]
	v_mfma_f32_16x16x32_bf16 v[94:97], v[146:149], v[214:217], v[94:97]
	v_mfma_f32_16x16x32_bf16 v[86:89], v[154:157], v[214:217], v[86:89]
	v_mfma_f32_16x16x32_bf16 v[78:81], v[146:149], v[234:237], v[78:81]
	v_mfma_f32_16x16x32_bf16 v[70:73], v[154:157], v[234:237], v[70:73]
	s_setprio 0
	s_setprio 1
	v_mfma_f32_16x16x32_bf16 v[122:125], v[158:161], v[182:185], 0
	v_mfma_f32_16x16x32_bf16 v[114:117], v[166:169], v[182:185], 0
	v_mfma_f32_16x16x32_bf16 v[106:109], v[158:161], v[190:193], 0
	v_mfma_f32_16x16x32_bf16 v[98:101], v[166:169], v[190:193], 0
	v_mfma_f32_16x16x32_bf16 v[90:93], v[158:161], v[210:213], 0
	v_mfma_f32_16x16x32_bf16 v[82:85], v[166:169], v[210:213], 0
	v_mfma_f32_16x16x32_bf16 v[74:77], v[158:161], v[226:229], 0
	v_mfma_f32_16x16x32_bf16 v[66:69], v[166:169], v[226:229], 0
	v_mfma_f32_16x16x32_bf16 v[122:125], v[162:165], v[186:189], v[122:125]
	v_mfma_f32_16x16x32_bf16 v[114:117], v[178:181], v[186:189], v[114:117]
	v_mfma_f32_16x16x32_bf16 v[106:109], v[162:165], v[206:209], v[106:109]
	v_mfma_f32_16x16x32_bf16 v[98:101], v[178:181], v[206:209], v[98:101]
	v_mfma_f32_16x16x32_bf16 v[90:93], v[162:165], v[214:217], v[90:93]
	v_mfma_f32_16x16x32_bf16 v[82:85], v[178:181], v[214:217], v[82:85]
	v_mfma_f32_16x16x32_bf16 v[74:77], v[162:165], v[234:237], v[74:77]
	v_mfma_f32_16x16x32_bf16 v[66:69], v[178:181], v[234:237], v[66:69]
	s_setprio 0
	s_barrier
	s_add_i32 s76, s76, s53
	s_mov_b32 m0, s76
	s_nop 0
	global_load_lds_dwordx4 v132, s[42:43]
	ds_read_b128 v[182:185], v175 offset:16384
	ds_read_b128 v[186:189], v175 offset:17408
	s_add_i32 m0, s76, 0x2000
	s_add_u32 s76, s42, 0x80000
	s_addc_u32 s77, s43, 0
	s_add_i32 s79, s79, s53
	global_load_lds_dwordx4 v136, s[42:43]
	ds_read_b128 v[190:193], v175 offset:18432
	ds_read_b128 v[206:209], v175 offset:19456
	s_mov_b32 m0, s79
	s_nop 0
	global_load_lds_dwordx4 v132, s[76:77]
	ds_read_b128 v[210:213], v175 offset:20480
	ds_read_b128 v[214:217], v175 offset:21504
	s_add_i32 m0, s79, 0x2000
	s_nop 0
	global_load_lds_dwordx4 v136, s[76:77]
	ds_read_b128 v[226:229], v175 offset:22528
	ds_read_b128 v[234:237], v175 offset:23552
	s_mov_b32 m0, s56
	s_nop 0
	global_load_lds_dwordx4 v130, s[44:45]
	s_mov_b32 m0, s57
	s_nop 0
	global_load_lds_dwordx4 v134, s[44:45]
	s_waitcnt lgkmcnt(0)
	s_setprio 1
	v_mfma_f32_16x16x32_bf16 v[62:65], v[142:145], v[182:185], 0
	v_mfma_f32_16x16x32_bf16 v[54:57], v[150:153], v[182:185], 0
	v_mfma_f32_16x16x32_bf16 v[46:49], v[142:145], v[190:193], 0
	v_mfma_f32_16x16x32_bf16 v[38:41], v[150:153], v[190:193], 0
	s_waitcnt vmcnt(8)
	s_barrier
; #define PG8_STAGE(bufoff, gbase, voff) do { _Pragma("unroll") for (int _i = 0; _i < 2; ++_i) \
;         __builtin_amdgcn_global_load_lds((const unsigned*)((const char*)(gbase) + (voff)[_i]), (PG8_LAS unsigned*)(lds + (bufoff) + ldsw + _i * 8192), 16, 0, 0); } while (0)
; #define PG8_LDA(dst, b, h) do { _Pragma("unroll") for (int m = 0; m < 4; ++m) _Pragma("unroll") for (int k = 0; k < 2; ++k) dst[m][k] = *(const PG8_LAS bf16x8*)(lds + PG8_SA(b, h) + aoff + m * 2048 + k * 1024); } while (0)
; #define PG8_LDB(dst, b, h) do { _Pragma("unroll") for (int n = 0; n < 2; ++n) _Pragma("unroll") for (int k = 0; k < 2; ++k) dst[n][k] = *(const PG8_LAS bf16x8*)(lds + PG8_SB(b, h) + boff + n * 2048 + k * 1024); } while (0)
; #define PG8_MMA(ai, bj, At, Bt) do { __builtin_amdgcn_s_setprio(1); _Pragma("unroll") for (int m = 0; m < 4; ++m) _Pragma("unroll") for (int n = 0; n < 2; ++n) _Pragma("unroll") for (int k = 0; k < 2; ++k) \
;         acc[ai][bj][m][n] = __builtin_amdgcn_mfma_f32_16x16x32_bf16(Bt[n][k], At[m][k], acc[ai][bj][m][n], 0, 0, 0); __builtin_amdgcn_s_setprio(0); } while (0)
; #define PG8_WAIT_V(n) asm volatile("s_waitcnt vmcnt(" #n ")" ::: "memory")
; #define PG8_WAIT_L(n) asm volatile("s_waitcnt lgkmcnt(" #n ")" ::: "memory")
; #define PG8_BAR __builtin_amdgcn_s_barrier()
; #define PG8_SCHED __builtin_amdgcn_sched_barrier(0)
; template <class Epi, class Sched, bool ALIGN_EPI = false, bool SP2 = false>
; __device__ __forceinline__ void gemm_phase(PG8_LAS unsigned char* lds, const Gemm g, const Sched& S, const Epi& E, const int wave_id) {
;     ...
;             PG8_WAIT_V(8); PG8_WAIT_L(0); PG8_BAR; PG8_MMA(0, 0, At, B0); PG8_MMA(0, 1, At, B1); PG8_BAR; PG8_SCHED;
;             PG8_LDA(At, 0, 1); PG8_STAGE(PG8_SB(0, 0), b2, voffB); PG8_STAGE(PG8_SB(0, 1), b2 + hstep, voffB); PG8_STAGE(PG8_SA(0, 0), a2, voffA);
;             PG8_WAIT_V(8); PG8_WAIT_L(0); PG8_BAR; PG8_MMA(1, 0, At, B0); PG8_MMA(1, 1, At, B1); PG8_BAR; PG8_SCHED;
;             PG8_LDB(B0, 1, 0); PG8_LDB(B1, 1, 1); PG8_SCHED; PG8_LDA(At, 1, 0); PG8_STAGE(PG8_SA(0, 1), a2 + hstep, voffA);
;             PG8_WAIT_V(8); PG8_WAIT_L(0); PG8_BAR; PG8_MMA(0, 0, At, B0); PG8_MMA(0, 1, At, B1); PG8_BAR; PG8_SCHED;
	v_mfma_f32_16x16x32_bf16 v[30:33], v[142:145], v[210:213], 0
	v_mfma_f32_16x16x32_bf16 v[22:25], v[150:153], v[210:213], 0
	v_mfma_f32_16x16x32_bf16 v[14:17], v[142:145], v[226:229], 0
	v_mfma_f32_16x16x32_bf16 v[6:9], v[150:153], v[226:229], 0
	v_mfma_f32_16x16x32_bf16 v[62:65], v[146:149], v[186:189], v[62:65]
	v_mfma_f32_16x16x32_bf16 v[54:57], v[154:157], v[186:189], v[54:57]
	v_mfma_f32_16x16x32_bf16 v[46:49], v[146:149], v[206:209], v[46:49]
	v_mfma_f32_16x16x32_bf16 v[38:41], v[154:157], v[206:209], v[38:41]
	v_mfma_f32_16x16x32_bf16 v[30:33], v[146:149], v[214:217], v[30:33]
	v_mfma_f32_16x16x32_bf16 v[22:25], v[154:157], v[214:217], v[22:25]
	v_mfma_f32_16x16x32_bf16 v[14:17], v[146:149], v[234:237], v[14:17]
	v_mfma_f32_16x16x32_bf16 v[6:9], v[154:157], v[234:237], v[6:9]
	s_setprio 0
	s_setprio 1
	v_mfma_f32_16x16x32_bf16 v[58:61], v[158:161], v[182:185], 0
	v_mfma_f32_16x16x32_bf16 v[50:53], v[166:169], v[182:185], 0
	v_mfma_f32_16x16x32_bf16 v[42:45], v[158:161], v[190:193], 0
	v_mfma_f32_16x16x32_bf16 v[34:37], v[166:169], v[190:193], 0
	v_mfma_f32_16x16x32_bf16 v[26:29], v[158:161], v[210:213], 0
	v_mfma_f32_16x16x32_bf16 v[18:21], v[166:169], v[210:213], 0
	v_mfma_f32_16x16x32_bf16 v[10:13], v[158:161], v[226:229], 0
	v_mfma_f32_16x16x32_bf16 v[2:5], v[166:169], v[226:229], 0
	v_mfma_f32_16x16x32_bf16 v[58:61], v[162:165], v[186:189], v[58:61]
	v_mfma_f32_16x16x32_bf16 v[50:53], v[178:181], v[186:189], v[50:53]
	v_mfma_f32_16x16x32_bf16 v[42:45], v[162:165], v[206:209], v[42:45]
	v_mfma_f32_16x16x32_bf16 v[34:37], v[178:181], v[206:209], v[34:37]
	v_mfma_f32_16x16x32_bf16 v[26:29], v[162:165], v[214:217], v[26:29]
	v_mfma_f32_16x16x32_bf16 v[18:21], v[178:181], v[214:217], v[18:21]
	v_mfma_f32_16x16x32_bf16 v[10:13], v[162:165], v[234:237], v[10:13]
	v_mfma_f32_16x16x32_bf16 v[2:5], v[178:181], v[234:237], v[2:5]
	s_setprio 0
	s_barrier
	s_add_i32 s76, 0, 0x18000
	s_add_i32 s77, 0, 0x1c000
	s_add_u32 s44, s44, 0x80000
	s_addc_u32 s45, s45, 0
	s_mov_b32 m0, s64
	s_nop 0
	global_load_lds_dwordx4 v130, s[44:45]
	ds_read_b128 v[142:145], v230 offset:32768
	ds_read_b128 v[146:149], v230 offset:33792
	ds_read_b128 v[150:153], v230 offset:34816
	ds_read_b128 v[154:157], v230 offset:35840
	ds_read_b128 v[158:161], v230 offset:49152
	ds_read_b128 v[162:165], v230 offset:50176
	ds_read_b128 v[166:169], v230 offset:51200
	ds_read_b128 v[178:181], v230 offset:52224
	s_mov_b32 m0, s65
	s_nop 0
	global_load_lds_dwordx4 v134, s[44:45]
	ds_read_b128 v[182:185], v175 offset:32768
	ds_read_b128 v[186:189], v175 offset:33792
	ds_read_b128 v[190:193], v175 offset:34816
	ds_read_b128 v[206:209], v175 offset:35840
	ds_read_b128 v[210:213], v175 offset:36864
	ds_read_b128 v[214:217], v175 offset:37888
	ds_read_b128 v[226:229], v175 offset:38912
	ds_read_b128 v[234:237], v175 offset:39936
	s_waitcnt lgkmcnt(0)
	s_setprio 1
	v_mfma_f32_16x16x32_bf16 v[126:129], v[142:145], v[182:185], v[126:129]
	v_mfma_f32_16x16x32_bf16 v[118:121], v[150:153], v[182:185], v[118:121]
	v_mfma_f32_16x16x32_bf16 v[110:113], v[142:145], v[190:193], v[110:113]
	v_mfma_f32_16x16x32_bf16 v[102:105], v[150:153], v[190:193], v[102:105]
	s_waitcnt vmcnt(8)
	s_barrier
	v_mfma_f32_16x16x32_bf16 v[94:97], v[142:145], v[210:213], v[94:97]
	v_mfma_f32_16x16x32_bf16 v[86:89], v[150:153], v[210:213], v[86:89]
	v_mfma_f32_16x16x32_bf16 v[78:81], v[142:145], v[226:229], v[78:81]
	v_mfma_f32_16x16x32_bf16 v[70:73], v[150:153], v[226:229], v[70:73]
	v_mfma_f32_16x16x32_bf16 v[126:129], v[146:149], v[186:189], v[126:129]
	v_mfma_f32_16x16x32_bf16 v[118:121], v[154:157], v[186:189], v[118:121]
	v_mfma_f32_16x16x32_bf16 v[110:113], v[146:149], v[206:209], v[110:113]
	v_mfma_f32_16x16x32_bf16 v[102:105], v[154:157], v[206:209], v[102:105]
	v_mfma_f32_16x16x32_bf16 v[94:97], v[146:149], v[214:217], v[94:97]
	v_mfma_f32_16x16x32_bf16 v[86:89], v[154:157], v[214:217], v[86:89]
	v_mfma_f32_16x16x32_bf16 v[78:81], v[146:149], v[234:237], v[78:81]
	v_mfma_f32_16x16x32_bf16 v[70:73], v[154:157], v[234:237], v[70:73]
	s_setprio 0
	s_setprio 1
	v_mfma_f32_16x16x32_bf16 v[122:125], v[158:161], v[182:185], v[122:125]
	v_mfma_f32_16x16x32_bf16 v[114:117], v[166:169], v[182:185], v[114:117]
	v_mfma_f32_16x16x32_bf16 v[106:109], v[158:161], v[190:193], v[106:109]
	v_mfma_f32_16x16x32_bf16 v[98:101], v[166:169], v[190:193], v[98:101]
	v_mfma_f32_16x16x32_bf16 v[90:93], v[158:161], v[210:213], v[90:93]
	v_mfma_f32_16x16x32_bf16 v[82:85], v[166:169], v[210:213], v[82:85]
	v_mfma_f32_16x16x32_bf16 v[74:77], v[158:161], v[226:229], v[74:77]
	v_mfma_f32_16x16x32_bf16 v[66:69], v[166:169], v[226:229], v[66:69]
	v_mfma_f32_16x16x32_bf16 v[122:125], v[162:165], v[186:189], v[122:125]
	v_mfma_f32_16x16x32_bf16 v[114:117], v[178:181], v[186:189], v[114:117]
	v_mfma_f32_16x16x32_bf16 v[106:109], v[162:165], v[206:209], v[106:109]
	v_mfma_f32_16x16x32_bf16 v[98:101], v[178:181], v[206:209], v[98:101]
	v_mfma_f32_16x16x32_bf16 v[90:93], v[162:165], v[214:217], v[90:93]
	v_mfma_f32_16x16x32_bf16 v[82:85], v[178:181], v[214:217], v[82:85]
	v_mfma_f32_16x16x32_bf16 v[74:77], v[162:165], v[234:237], v[74:77]
	v_mfma_f32_16x16x32_bf16 v[66:69], v[178:181], v[234:237], v[66:69]
	s_setprio 0
	s_barrier
; #define PG8_STAGE(bufoff, gbase, voff) do { _Pragma("unroll") for (int _i = 0; _i < 2; ++_i) \
;         __builtin_amdgcn_global_load_lds((const unsigned*)((const char*)(gbase) + (voff)[_i]), (PG8_LAS unsigned*)(lds + (bufoff) + ldsw + _i * 8192), 16, 0, 0); } while (0)
; #define PG8_LDA(dst, b, h) do { _Pragma("unroll") for (int m = 0; m < 4; ++m) _Pragma("unroll") for (int k = 0; k < 2; ++k) dst[m][k] = *(const PG8_LAS bf16x8*)(lds + PG8_SA(b, h) + aoff + m * 2048 + k * 1024); } while (0)
; #define PG8_LDB(dst, b, h) do { _Pragma("unroll") for (int n = 0; n < 2; ++n) _Pragma("unroll") for (int k = 0; k < 2; ++k) dst[n][k] = *(const PG8_LAS bf16x8*)(lds + PG8_SB(b, h) + boff + n * 2048 + k * 1024); } while (0)
; #define PG8_WAIT_V(n) asm volatile("s_waitcnt vmcnt(" #n ")" ::: "memory")
; #define PG8_WAIT_L(n) asm volatile("s_waitcnt lgkmcnt(" #n ")" ::: "memory")
; #define PG8_BAR __builtin_amdgcn_s_barrier()
; #define PG8_SCHED __builtin_amdgcn_sched_barrier(0)
; template <class Epi, class Sched, bool ALIGN_EPI = false, bool SP2 = false>
; __device__ __forceinline__ void gemm_phase(PG8_LAS unsigned char* lds, const Gemm g, const Sched& S, const Epi& E, const int wave_id) {
;     ...
;         for (int t = 0; t < nt; t += 2) {
;             const bool last = (t == nt - 2);
;             const char* a1 = cA + (size_t)(t + 1) * kstep;
;             const char* a2 = last ? nA : cA + (size_t)(t + 2) * kstep; const char* b2 = last ? nB : cB + (size_t)(t + 2) * kstep;
;             const char* a3 = a2 + kstep; const char* b3 = b2 + kstep;
;             if (last && has_next) S.a_ready(nxt);
;             if constexpr (SP2) {
;             PG8_LDB(B0, 0, 0); PG8_LDB(B1, 0, 1); PG8_SCHED; PG8_LDA(At, 0, 0); PG8_STAGE(PG8_SA(1, 1), a1 + hstep, voffA);
;             PG8_WAIT_V(8); PG8_WAIT_L(0); PG8_BAR; PG8_MMA(0, 0, At, B0); PG8_MMA(0, 1, At, B1); PG8_BAR; PG8_SCHED;
;     ...
;             PG8_LDB(B0, 1, 0); PG8_LDB(B1, 1, 1); PG8_SCHED; PG8_LDA(At, 1, 0); PG8_STAGE(PG8_SA(0, 1), a2 + hstep, voffA);
;             PG8_WAIT_V(8); PG8_WAIT_L(0); PG8_BAR; PG8_MMA(0, 0, At, B0); PG8_MMA(0, 1, At, B1); PG8_BAR; PG8_SCHED;
;             PG8_LDA(At, 1, 1); PG8_STAGE(PG8_SB(1, 0), b3, voffB); PG8_STAGE(PG8_SB(1, 1), b3 + hstep, voffB); PG8_STAGE(PG8_SA(1, 0), a3, voffA);
;             PG8_WAIT_V(8); PG8_WAIT_L(0); PG8_BAR; PG8_MMA(1, 0, At, B0); PG8_MMA(1, 1, At, B1); PG8_BAR; PG8_SCHED;
	s_add_u32 vcc_lo, s44, 0xfff80080
	s_addc_u32 vcc_hi, s45, -1
	s_mov_b32 m0, s68
	s_nop 0
	global_load_lds_dwordx4 v130, vcc
	ds_read_b128 v[182:185], v175 offset:49152
	ds_read_b128 v[186:189], v175 offset:50176
	s_mov_b32 m0, s69
	s_add_i32 s44, s76, s53
	global_load_lds_dwordx4 v134, vcc
	ds_read_b128 v[190:193], v175 offset:51200
	ds_read_b128 v[206:209], v175 offset:52224
	s_add_u32 vcc_lo, s42, 0x80
	s_addc_u32 vcc_hi, s43, 0
	s_mov_b32 m0, s44
	s_nop 0
	global_load_lds_dwordx4 v132, vcc
	ds_read_b128 v[210:213], v175 offset:53248
	ds_read_b128 v[214:217], v175 offset:54272
	s_add_i32 m0, s44, 0x2000
	s_add_u32 s42, s42, 0x80080
	s_addc_u32 s43, s43, 0
	global_load_lds_dwordx4 v136, vcc
	ds_read_b128 v[226:229], v175 offset:55296
	ds_read_b128 v[234:237], v175 offset:56320
	s_add_i32 s44, s77, s53
	s_mov_b32 m0, s44
	s_nop 0
	global_load_lds_dwordx4 v132, s[42:43]
	s_add_i32 m0, s44, 0x2000
	s_nop 0
	global_load_lds_dwordx4 v136, s[42:43]
	s_waitcnt lgkmcnt(0)
	s_setprio 1
	v_mfma_f32_16x16x32_bf16 v[62:65], v[142:145], v[182:185], v[62:65]
	v_mfma_f32_16x16x32_bf16 v[54:57], v[150:153], v[182:185], v[54:57]
	v_mfma_f32_16x16x32_bf16 v[46:49], v[142:145], v[190:193], v[46:49]
	v_mfma_f32_16x16x32_bf16 v[38:41], v[150:153], v[190:193], v[38:41]
	s_waitcnt vmcnt(8)
	s_barrier
	v_mfma_f32_16x16x32_bf16 v[30:33], v[142:145], v[210:213], v[30:33]
	v_mfma_f32_16x16x32_bf16 v[22:25], v[150:153], v[210:213], v[22:25]
	v_mfma_f32_16x16x32_bf16 v[14:17], v[142:145], v[226:229], v[14:17]
	v_mfma_f32_16x16x32_bf16 v[6:9], v[150:153], v[226:229], v[6:9]
	v_mfma_f32_16x16x32_bf16 v[62:65], v[146:149], v[186:189], v[62:65]
	v_mfma_f32_16x16x32_bf16 v[54:57], v[154:157], v[186:189], v[54:57]
	v_mfma_f32_16x16x32_bf16 v[46:49], v[146:149], v[206:209], v[46:49]
	v_mfma_f32_16x16x32_bf16 v[38:41], v[154:157], v[206:209], v[38:41]
	v_mfma_f32_16x16x32_bf16 v[30:33], v[146:149], v[214:217], v[30:33]
	v_mfma_f32_16x16x32_bf16 v[22:25], v[154:157], v[214:217], v[22:25]
	v_mfma_f32_16x16x32_bf16 v[14:17], v[146:149], v[234:237], v[14:17]
	v_mfma_f32_16x16x32_bf16 v[6:9], v[154:157], v[234:237], v[6:9]
	s_setprio 0
	s_setprio 1
	v_mfma_f32_16x16x32_bf16 v[58:61], v[158:161], v[182:185], v[58:61]
	v_mfma_f32_16x16x32_bf16 v[50:53], v[166:169], v[182:185], v[50:53]
	v_mfma_f32_16x16x32_bf16 v[42:45], v[158:161], v[190:193], v[42:45]
	v_mfma_f32_16x16x32_bf16 v[34:37], v[166:169], v[190:193], v[34:37]
	v_mfma_f32_16x16x32_bf16 v[26:29], v[158:161], v[210:213], v[26:29]
	v_mfma_f32_16x16x32_bf16 v[18:21], v[166:169], v[210:213], v[18:21]
	v_mfma_f32_16x16x32_bf16 v[10:13], v[158:161], v[226:229], v[10:13]
	v_mfma_f32_16x16x32_bf16 v[2:5], v[166:169], v[226:229], v[2:5]
	v_mfma_f32_16x16x32_bf16 v[58:61], v[162:165], v[186:189], v[58:61]
	v_mfma_f32_16x16x32_bf16 v[50:53], v[178:181], v[186:189], v[50:53]
	v_mfma_f32_16x16x32_bf16 v[42:45], v[162:165], v[206:209], v[42:45]
	v_mfma_f32_16x16x32_bf16 v[34:37], v[178:181], v[206:209], v[34:37]
	v_mfma_f32_16x16x32_bf16 v[26:29], v[162:165], v[214:217], v[26:29]
	v_mfma_f32_16x16x32_bf16 v[18:21], v[178:181], v[214:217], v[18:21]
	v_mfma_f32_16x16x32_bf16 v[10:13], v[162:165], v[234:237], v[10:13]
	v_mfma_f32_16x16x32_bf16 v[2:5], v[178:181], v[234:237], v[2:5]
	s_setprio 0
	s_barrier
	s_add_i32 s75, s75, 2
	s_add_u32 s20, s20, 0x100
	s_addc_u32 s21, s21, 0
	s_add_u32 s73, s73, 0x100
	s_addc_u32 s74, s74, 0
	s_cmp_gt_u32 s75, 29
	s_cbranch_scc1 .Lpeel_exit_g1
.LBB0_174:
	s_add_u32 s42, s20, 0xfff80080
	s_addc_u32 s43, s21, -1
	s_add_i32 s76, 0, 0x10000
	s_cmp_eq_u32 s75, 28
	s_cselect_b32 s45, s15, s43
	s_cselect_b32 s44, s41, s42
	s_cselect_b32 s43, s13, s74
	s_cselect_b32 s42, s72, s73
	s_add_i32 s79, 0, 0x14000
	s_add_i32 m0, s56, 0xc000
	s_nop 0
	global_load_lds_dwordx4 v138, s[20:21]
	ds_read_b128 v[142:145], v230
	ds_read_b128 v[146:149], v230 offset:1024
	ds_read_b128 v[150:153], v230 offset:2048
	ds_read_b128 v[154:157], v230 offset:3072
	ds_read_b128 v[158:161], v230 offset:16384
	ds_read_b128 v[162:165], v230 offset:17408
	ds_read_b128 v[166:169], v230 offset:18432
	ds_read_b128 v[178:181], v230 offset:19456
	s_add_i32 m0, s56, 0xe000
	s_nop 0
	global_load_lds_dwordx4 v140, s[20:21]
	ds_read_b128 v[182:185], v175
	ds_read_b128 v[186:189], v175 offset:1024
	ds_read_b128 v[190:193], v175 offset:2048
	ds_read_b128 v[206:209], v175 offset:3072
	ds_read_b128 v[210:213], v175 offset:4096
	ds_read_b128 v[214:217], v175 offset:5120
	ds_read_b128 v[226:229], v175 offset:6144
	ds_read_b128 v[234:237], v175 offset:7168
	s_waitcnt lgkmcnt(0)
	s_setprio 1
	v_mfma_f32_16x16x32_bf16 v[126:129], v[142:145], v[182:185], v[126:129]
	v_mfma_f32_16x16x32_bf16 v[118:121], v[150:153], v[182:185], v[118:121]
	v_mfma_f32_16x16x32_bf16 v[110:113], v[142:145], v[190:193], v[110:113]
	v_mfma_f32_16x16x32_bf16 v[102:105], v[150:153], v[190:193], v[102:105]
	s_waitcnt vmcnt(8)
	s_barrier
; #define PG8_STAGE(bufoff, gbase, voff) do { _Pragma("unroll") for (int _i = 0; _i < 2; ++_i) \
;         __builtin_amdgcn_global_load_lds((const unsigned*)((const char*)(gbase) + (voff)[_i]), (PG8_LAS unsigned*)(lds + (bufoff) + ldsw + _i * 8192), 16, 0, 0); } while (0)
; #define PG8_LDA(dst, b, h) do { _Pragma("unroll") for (int m = 0; m < 4; ++m) _Pragma("unroll") for (int k = 0; k < 2; ++k) dst[m][k] = *(const PG8_LAS bf16x8*)(lds + PG8_SA(b, h) + aoff + m * 2048 + k * 1024); } while (0)
; #define PG8_LDB(dst, b, h) do { _Pragma("unroll") for (int n = 0; n < 2; ++n) _Pragma("unroll") for (int k = 0; k < 2; ++k) dst[n][k] = *(const PG8_LAS bf16x8*)(lds + PG8_SB(b, h) + boff + n * 2048 + k * 1024); } while (0)
; #define PG8_MMA(ai, bj, At, Bt) do { __builtin_amdgcn_s_setprio(1); _Pragma("unroll") for (int m = 0; m < 4; ++m) _Pragma("unroll") for (int n = 0; n < 2; ++n) _Pragma("unroll") for (int k = 0; k < 2; ++k) \
;         acc[ai][bj][m][n] = __builtin_amdgcn_mfma_f32_16x16x32_bf16(Bt[n][k], At[m][k], acc[ai][bj][m][n], 0, 0, 0); __builtin_amdgcn_s_setprio(0); } while (0)
; #define PG8_WAIT_V(n) asm volatile("s_waitcnt vmcnt(" #n ")" ::: "memory")
; #define PG8_WAIT_L(n) asm volatile("s_waitcnt lgkmcnt(" #n ")" ::: "memory")
; #define PG8_BAR __builtin_amdgcn_s_barrier()
; #define PG8_SCHED __builtin_amdgcn_sched_barrier(0)
; template <class Epi, class Sched, bool ALIGN_EPI = false, bool SP2 = false>
; __device__ __forceinline__ void gemm_phase(PG8_LAS unsigned char* lds, const Gemm g, const Sched& S, const Epi& E, const int wave_id) {
;     ...
;             PG8_LDB(B0, 0, 0); PG8_LDB(B1, 0, 1); PG8_SCHED; PG8_LDA(At, 0, 0); PG8_STAGE(PG8_SA(1, 1), a1 + hstep, voffA);
;             PG8_WAIT_V(8); PG8_WAIT_L(0); PG8_BAR; PG8_MMA(0, 0, At, B0); PG8_MMA(0, 1, At, B1); PG8_BAR; PG8_SCHED;
;             PG8_LDA(At, 0, 1); PG8_STAGE(PG8_SB(0, 0), b2, voffB); PG8_STAGE(PG8_SB(0, 1), b2 + hstep, voffB); PG8_STAGE(PG8_SA(0, 0), a2, voffA);
;             PG8_WAIT_V(8); PG8_WAIT_L(0); PG8_BAR; PG8_MMA(1, 0, At, B0); PG8_MMA(1, 1, At, B1); PG8_BAR; PG8_SCHED;
	v_mfma_f32_16x16x32_bf16 v[94:97], v[142:145], v[210:213], v[94:97]
	v_mfma_f32_16x16x32_bf16 v[86:89], v[150:153], v[210:213], v[86:89]
	v_mfma_f32_16x16x32_bf16 v[78:81], v[142:145], v[226:229], v[78:81]
	v_mfma_f32_16x16x32_bf16 v[70:73], v[150:153], v[226:229], v[70:73]
	v_mfma_f32_16x16x32_bf16 v[126:129], v[146:149], v[186:189], v[126:129]
	v_mfma_f32_16x16x32_bf16 v[118:121], v[154:157], v[186:189], v[118:121]
	v_mfma_f32_16x16x32_bf16 v[110:113], v[146:149], v[206:209], v[110:113]
	v_mfma_f32_16x16x32_bf16 v[102:105], v[154:157], v[206:209], v[102:105]
	v_mfma_f32_16x16x32_bf16 v[94:97], v[146:149], v[214:217], v[94:97]
	v_mfma_f32_16x16x32_bf16 v[86:89], v[154:157], v[214:217], v[86:89]
	v_mfma_f32_16x16x32_bf16 v[78:81], v[146:149], v[234:237], v[78:81]
	v_mfma_f32_16x16x32_bf16 v[70:73], v[154:157], v[234:237], v[70:73]
	s_setprio 0
	s_setprio 1
	v_mfma_f32_16x16x32_bf16 v[122:125], v[158:161], v[182:185], v[122:125]
	v_mfma_f32_16x16x32_bf16 v[114:117], v[166:169], v[182:185], v[114:117]
	v_mfma_f32_16x16x32_bf16 v[106:109], v[158:161], v[190:193], v[106:109]
	v_mfma_f32_16x16x32_bf16 v[98:101], v[166:169], v[190:193], v[98:101]
	v_mfma_f32_16x16x32_bf16 v[90:93], v[158:161], v[210:213], v[90:93]
	v_mfma_f32_16x16x32_bf16 v[82:85], v[166:169], v[210:213], v[82:85]
	v_mfma_f32_16x16x32_bf16 v[74:77], v[158:161], v[226:229], v[74:77]
	v_mfma_f32_16x16x32_bf16 v[66:69], v[166:169], v[226:229], v[66:69]
	v_mfma_f32_16x16x32_bf16 v[122:125], v[162:165], v[186:189], v[122:125]
	v_mfma_f32_16x16x32_bf16 v[114:117], v[178:181], v[186:189], v[114:117]
	v_mfma_f32_16x16x32_bf16 v[106:109], v[162:165], v[206:209], v[106:109]
	v_mfma_f32_16x16x32_bf16 v[98:101], v[178:181], v[206:209], v[98:101]
	v_mfma_f32_16x16x32_bf16 v[90:93], v[162:165], v[214:217], v[90:93]
	v_mfma_f32_16x16x32_bf16 v[82:85], v[178:181], v[214:217], v[82:85]
	v_mfma_f32_16x16x32_bf16 v[74:77], v[162:165], v[234:237], v[74:77]
	v_mfma_f32_16x16x32_bf16 v[66:69], v[178:181], v[234:237], v[66:69]
	s_setprio 0
	s_barrier
	s_add_i32 s76, s76, s53
	s_mov_b32 m0, s76
	s_nop 0
	global_load_lds_dwordx4 v132, s[42:43]
	ds_read_b128 v[182:185], v175 offset:16384
	ds_read_b128 v[186:189], v175 offset:17408
	s_add_i32 m0, s76, 0x2000
	s_add_u32 s76, s42, 0x80000
	s_addc_u32 s77, s43, 0
	s_add_i32 s79, s79, s53
	global_load_lds_dwordx4 v136, s[42:43]
	ds_read_b128 v[190:193], v175 offset:18432
	ds_read_b128 v[206:209], v175 offset:19456
	s_mov_b32 m0, s79
	s_nop 0
	global_load_lds_dwordx4 v132, s[76:77]
	ds_read_b128 v[210:213], v175 offset:20480
	ds_read_b128 v[214:217], v175 offset:21504
	s_add_i32 m0, s79, 0x2000
	s_nop 0
	global_load_lds_dwordx4 v136, s[76:77]
	ds_read_b128 v[226:229], v175 offset:22528
	ds_read_b128 v[234:237], v175 offset:23552
	s_mov_b32 m0, s56
	s_nop 0
	global_load_lds_dwordx4 v130, s[44:45]
	s_mov_b32 m0, s57
	s_nop 0
	global_load_lds_dwordx4 v134, s[44:45]
	s_waitcnt lgkmcnt(0)
	s_setprio 1
	v_mfma_f32_16x16x32_bf16 v[62:65], v[142:145], v[182:185], v[62:65]
	v_mfma_f32_16x16x32_bf16 v[54:57], v[150:153], v[182:185], v[54:57]
	v_mfma_f32_16x16x32_bf16 v[46:49], v[142:145], v[190:193], v[46:49]
	v_mfma_f32_16x16x32_bf16 v[38:41], v[150:153], v[190:193], v[38:41]
	s_waitcnt vmcnt(8)
	s_barrier
	v_mfma_f32_16x16x32_bf16 v[30:33], v[142:145], v[210:213], v[30:33]
	v_mfma_f32_16x16x32_bf16 v[22:25], v[150:153], v[210:213], v[22:25]
	v_mfma_f32_16x16x32_bf16 v[14:17], v[142:145], v[226:229], v[14:17]
	v_mfma_f32_16x16x32_bf16 v[6:9], v[150:153], v[226:229], v[6:9]
	v_mfma_f32_16x16x32_bf16 v[62:65], v[146:149], v[186:189], v[62:65]
	v_mfma_f32_16x16x32_bf16 v[54:57], v[154:157], v[186:189], v[54:57]
	v_mfma_f32_16x16x32_bf16 v[46:49], v[146:149], v[206:209], v[46:49]
	v_mfma_f32_16x16x32_bf16 v[38:41], v[154:157], v[206:209], v[38:41]
	v_mfma_f32_16x16x32_bf16 v[30:33], v[146:149], v[214:217], v[30:33]
	v_mfma_f32_16x16x32_bf16 v[22:25], v[154:157], v[214:217], v[22:25]
	v_mfma_f32_16x16x32_bf16 v[14:17], v[146:149], v[234:237], v[14:17]
	v_mfma_f32_16x16x32_bf16 v[6:9], v[154:157], v[234:237], v[6:9]
	s_setprio 0
	s_setprio 1
	v_mfma_f32_16x16x32_bf16 v[58:61], v[158:161], v[182:185], v[58:61]
	v_mfma_f32_16x16x32_bf16 v[50:53], v[166:169], v[182:185], v[50:53]
	v_mfma_f32_16x16x32_bf16 v[42:45], v[158:161], v[190:193], v[42:45]
	v_mfma_f32_16x16x32_bf16 v[34:37], v[166:169], v[190:193], v[34:37]
	v_mfma_f32_16x16x32_bf16 v[26:29], v[158:161], v[210:213], v[26:29]
	v_mfma_f32_16x16x32_bf16 v[18:21], v[166:169], v[210:213], v[18:21]
	v_mfma_f32_16x16x32_bf16 v[10:13], v[158:161], v[226:229], v[10:13]
	v_mfma_f32_16x16x32_bf16 v[2:5], v[166:169], v[226:229], v[2:5]
	v_mfma_f32_16x16x32_bf16 v[58:61], v[162:165], v[186:189], v[58:61]
	v_mfma_f32_16x16x32_bf16 v[50:53], v[178:181], v[186:189], v[50:53]
	v_mfma_f32_16x16x32_bf16 v[42:45], v[162:165], v[206:209], v[42:45]
	v_mfma_f32_16x16x32_bf16 v[34:37], v[178:181], v[206:209], v[34:37]
	v_mfma_f32_16x16x32_bf16 v[26:29], v[162:165], v[214:217], v[26:29]
	v_mfma_f32_16x16x32_bf16 v[18:21], v[178:181], v[214:217], v[18:21]
	v_mfma_f32_16x16x32_bf16 v[10:13], v[162:165], v[234:237], v[10:13]
	v_mfma_f32_16x16x32_bf16 v[2:5], v[178:181], v[234:237], v[2:5]
	s_setprio 0
	s_barrier
; #define PG8_STAGE(bufoff, gbase, voff) do { _Pragma("unroll") for (int _i = 0; _i < 2; ++_i) \
;         __builtin_amdgcn_global_load_lds((const unsigned*)((const char*)(gbase) + (voff)[_i]), (PG8_LAS unsigned*)(lds + (bufoff) + ldsw + _i * 8192), 16, 0, 0); } while (0)
; #define PG8_LDA(dst, b, h) do { _Pragma("unroll") for (int m = 0; m < 4; ++m) _Pragma("unroll") for (int k = 0; k < 2; ++k) dst[m][k] = *(const PG8_LAS bf16x8*)(lds + PG8_SA(b, h) + aoff + m * 2048 + k * 1024); } while (0)
; #define PG8_LDB(dst, b, h) do { _Pragma("unroll") for (int n = 0; n < 2; ++n) _Pragma("unroll") for (int k = 0; k < 2; ++k) dst[n][k] = *(const PG8_LAS bf16x8*)(lds + PG8_SB(b, h) + boff + n * 2048 + k * 1024); } while (0)
; #define PG8_MMA(ai, bj, At, Bt) do { __builtin_amdgcn_s_setprio(1); _Pragma("unroll") for (int m = 0; m < 4; ++m) _Pragma("unroll") for (int n = 0; n < 2; ++n) _Pragma("unroll") for (int k = 0; k < 2; ++k) \
;         acc[ai][bj][m][n] = __builtin_amdgcn_mfma_f32_16x16x32_bf16(Bt[n][k], At[m][k], acc[ai][bj][m][n], 0, 0, 0); __builtin_amdgcn_s_setprio(0); } while (0)
; #define PG8_WAIT_V(n) asm volatile("s_waitcnt vmcnt(" #n ")" ::: "memory")
; #define PG8_WAIT_L(n) asm volatile("s_waitcnt lgkmcnt(" #n ")" ::: "memory")
; #define PG8_BAR __builtin_amdgcn_s_barrier()
; #define PG8_SCHED __builtin_amdgcn_sched_barrier(0)
; template <class Epi, class Sched, bool ALIGN_EPI = false, bool SP2 = false>
; __device__ __forceinline__ void gemm_phase(PG8_LAS unsigned char* lds, const Gemm g, const Sched& S, const Epi& E, const int wave_id) {
;     ...
;             PG8_LDB(B0, 1, 0); PG8_LDB(B1, 1, 1); PG8_SCHED; PG8_LDA(At, 1, 0); PG8_STAGE(PG8_SA(0, 1), a2 + hstep, voffA);
;             PG8_WAIT_V(8); PG8_WAIT_L(0); PG8_BAR; PG8_MMA(0, 0, At, B0); PG8_MMA(0, 1, At, B1); PG8_BAR; PG8_SCHED;
;             PG8_LDA(At, 1, 1); PG8_STAGE(PG8_SB(1, 0), b3, voffB); PG8_STAGE(PG8_SB(1, 1), b3 + hstep, voffB); PG8_STAGE(PG8_SA(1, 0), a3, voffA);
;             PG8_WAIT_V(8); PG8_WAIT_L(0); PG8_BAR; PG8_MMA(1, 0, At, B0); PG8_MMA(1, 1, At, B1); PG8_BAR; PG8_SCHED;
	s_add_i32 s76, 0, 0x18000
	s_add_i32 s77, 0, 0x1c000
	s_add_u32 s44, s44, 0x80000
	s_addc_u32 s45, s45, 0
	s_mov_b32 m0, s64
	s_nop 0
	global_load_lds_dwordx4 v130, s[44:45]
	ds_read_b128 v[142:145], v230 offset:32768
	ds_read_b128 v[146:149], v230 offset:33792
	ds_read_b128 v[150:153], v230 offset:34816
	ds_read_b128 v[154:157], v230 offset:35840
	ds_read_b128 v[158:161], v230 offset:49152
	ds_read_b128 v[162:165], v230 offset:50176
	ds_read_b128 v[166:169], v230 offset:51200
	ds_read_b128 v[178:181], v230 offset:52224
	s_mov_b32 m0, s65
	s_nop 0
	global_load_lds_dwordx4 v134, s[44:45]
	ds_read_b128 v[182:185], v175 offset:32768
	ds_read_b128 v[186:189], v175 offset:33792
	ds_read_b128 v[190:193], v175 offset:34816
	ds_read_b128 v[206:209], v175 offset:35840
	ds_read_b128 v[210:213], v175 offset:36864
	ds_read_b128 v[214:217], v175 offset:37888
	ds_read_b128 v[226:229], v175 offset:38912
	ds_read_b128 v[234:237], v175 offset:39936
	s_waitcnt lgkmcnt(0)
	s_setprio 1
	v_mfma_f32_16x16x32_bf16 v[126:129], v[142:145], v[182:185], v[126:129]
	v_mfma_f32_16x16x32_bf16 v[118:121], v[150:153], v[182:185], v[118:121]
	v_mfma_f32_16x16x32_bf16 v[110:113], v[142:145], v[190:193], v[110:113]
	v_mfma_f32_16x16x32_bf16 v[102:105], v[150:153], v[190:193], v[102:105]
	s_waitcnt vmcnt(8)
	s_barrier
	v_mfma_f32_16x16x32_bf16 v[94:97], v[142:145], v[210:213], v[94:97]
	v_mfma_f32_16x16x32_bf16 v[86:89], v[150:153], v[210:213], v[86:89]
	v_mfma_f32_16x16x32_bf16 v[78:81], v[142:145], v[226:229], v[78:81]
	v_mfma_f32_16x16x32_bf16 v[70:73], v[150:153], v[226:229], v[70:73]
	v_mfma_f32_16x16x32_bf16 v[126:129], v[146:149], v[186:189], v[126:129]
	v_mfma_f32_16x16x32_bf16 v[118:121], v[154:157], v[186:189], v[118:121]
	v_mfma_f32_16x16x32_bf16 v[110:113], v[146:149], v[206:209], v[110:113]
	v_mfma_f32_16x16x32_bf16 v[102:105], v[154:157], v[206:209], v[102:105]
	v_mfma_f32_16x16x32_bf16 v[94:97], v[146:149], v[214:217], v[94:97]
	v_mfma_f32_16x16x32_bf16 v[86:89], v[154:157], v[214:217], v[86:89]
	v_mfma_f32_16x16x32_bf16 v[78:81], v[146:149], v[234:237], v[78:81]
	v_mfma_f32_16x16x32_bf16 v[70:73], v[154:157], v[234:237], v[70:73]
	s_setprio 0
	s_setprio 1
	v_mfma_f32_16x16x32_bf16 v[122:125], v[158:161], v[182:185], v[122:125]
	v_mfma_f32_16x16x32_bf16 v[114:117], v[166:169], v[182:185], v[114:117]
	v_mfma_f32_16x16x32_bf16 v[106:109], v[158:161], v[190:193], v[106:109]
	v_mfma_f32_16x16x32_bf16 v[98:101], v[166:169], v[190:193], v[98:101]
	v_mfma_f32_16x16x32_bf16 v[90:93], v[158:161], v[210:213], v[90:93]
	v_mfma_f32_16x16x32_bf16 v[82:85], v[166:169], v[210:213], v[82:85]
	v_mfma_f32_16x16x32_bf16 v[74:77], v[158:161], v[226:229], v[74:77]
	v_mfma_f32_16x16x32_bf16 v[66:69], v[166:169], v[226:229], v[66:69]
	v_mfma_f32_16x16x32_bf16 v[122:125], v[162:165], v[186:189], v[122:125]
	v_mfma_f32_16x16x32_bf16 v[114:117], v[178:181], v[186:189], v[114:117]
	v_mfma_f32_16x16x32_bf16 v[106:109], v[162:165], v[206:209], v[106:109]
	v_mfma_f32_16x16x32_bf16 v[98:101], v[178:181], v[206:209], v[98:101]
	v_mfma_f32_16x16x32_bf16 v[90:93], v[162:165], v[214:217], v[90:93]
	v_mfma_f32_16x16x32_bf16 v[82:85], v[178:181], v[214:217], v[82:85]
	v_mfma_f32_16x16x32_bf16 v[74:77], v[162:165], v[234:237], v[74:77]
	v_mfma_f32_16x16x32_bf16 v[66:69], v[178:181], v[234:237], v[66:69]
	s_setprio 0
	s_barrier
	s_add_u32 vcc_lo, s44, 0xfff80080
	s_addc_u32 vcc_hi, s45, -1
	s_mov_b32 m0, s68
	s_nop 0
	global_load_lds_dwordx4 v130, vcc
	ds_read_b128 v[182:185], v175 offset:49152
	ds_read_b128 v[186:189], v175 offset:50176
	s_mov_b32 m0, s69
	s_add_i32 s44, s76, s53
	global_load_lds_dwordx4 v134, vcc
	ds_read_b128 v[190:193], v175 offset:51200
	ds_read_b128 v[206:209], v175 offset:52224
	s_add_u32 vcc_lo, s42, 0x80
	s_addc_u32 vcc_hi, s43, 0
	s_mov_b32 m0, s44
	s_nop 0
	global_load_lds_dwordx4 v132, vcc
	ds_read_b128 v[210:213], v175 offset:53248
	ds_read_b128 v[214:217], v175 offset:54272
	s_add_i32 m0, s44, 0x2000
	s_add_u32 s42, s42, 0x80080
	s_addc_u32 s43, s43, 0
	global_load_lds_dwordx4 v136, vcc
	ds_read_b128 v[226:229], v175 offset:55296
	ds_read_b128 v[234:237], v175 offset:56320
	s_add_i32 s44, s77, s53
	s_mov_b32 m0, s44
	s_nop 0
	global_load_lds_dwordx4 v132, s[42:43]
	s_add_i32 m0, s44, 0x2000
	s_nop 0
	global_load_lds_dwordx4 v136, s[42:43]
	s_waitcnt lgkmcnt(0)
	s_setprio 1
	v_mfma_f32_16x16x32_bf16 v[62:65], v[142:145], v[182:185], v[62:65]
	v_mfma_f32_16x16x32_bf16 v[54:57], v[150:153], v[182:185], v[54:57]
	v_mfma_f32_16x16x32_bf16 v[46:49], v[142:145], v[190:193], v[46:49]
	v_mfma_f32_16x16x32_bf16 v[38:41], v[150:153], v[190:193], v[38:41]
	s_waitcnt vmcnt(8)
	s_barrier
	v_mfma_f32_16x16x32_bf16 v[30:33], v[142:145], v[210:213], v[30:33]
	v_mfma_f32_16x16x32_bf16 v[22:25], v[150:153], v[210:213], v[22:25]
	v_mfma_f32_16x16x32_bf16 v[14:17], v[142:145], v[226:229], v[14:17]
	v_mfma_f32_16x16x32_bf16 v[6:9], v[150:153], v[226:229], v[6:9]
	v_mfma_f32_16x16x32_bf16 v[62:65], v[146:149], v[186:189], v[62:65]
	v_mfma_f32_16x16x32_bf16 v[54:57], v[154:157], v[186:189], v[54:57]
	v_mfma_f32_16x16x32_bf16 v[46:49], v[146:149], v[206:209], v[46:49]
	v_mfma_f32_16x16x32_bf16 v[38:41], v[154:157], v[206:209], v[38:41]
	v_mfma_f32_16x16x32_bf16 v[30:33], v[146:149], v[214:217], v[30:33]
	v_mfma_f32_16x16x32_bf16 v[22:25], v[154:157], v[214:217], v[22:25]
	v_mfma_f32_16x16x32_bf16 v[14:17], v[146:149], v[234:237], v[14:17]
	v_mfma_f32_16x16x32_bf16 v[6:9], v[154:157], v[234:237], v[6:9]
	s_setprio 0
	s_setprio 1
	v_mfma_f32_16x16x32_bf16 v[58:61], v[158:161], v[182:185], v[58:61]
	v_mfma_f32_16x16x32_bf16 v[50:53], v[166:169], v[182:185], v[50:53]
	v_mfma_f32_16x16x32_bf16 v[42:45], v[158:161], v[190:193], v[42:45]
	v_mfma_f32_16x16x32_bf16 v[34:37], v[166:169], v[190:193], v[34:37]
	v_mfma_f32_16x16x32_bf16 v[26:29], v[158:161], v[210:213], v[26:29]
	v_mfma_f32_16x16x32_bf16 v[18:21], v[166:169], v[210:213], v[18:21]
	v_mfma_f32_16x16x32_bf16 v[10:13], v[158:161], v[226:229], v[10:13]
	v_mfma_f32_16x16x32_bf16 v[2:5], v[166:169], v[226:229], v[2:5]
	v_mfma_f32_16x16x32_bf16 v[58:61], v[162:165], v[186:189], v[58:61]
	v_mfma_f32_16x16x32_bf16 v[50:53], v[178:181], v[186:189], v[50:53]
	v_mfma_f32_16x16x32_bf16 v[42:45], v[162:165], v[206:209], v[42:45]
	v_mfma_f32_16x16x32_bf16 v[34:37], v[178:181], v[206:209], v[34:37]
	v_mfma_f32_16x16x32_bf16 v[26:29], v[162:165], v[214:217], v[26:29]
	v_mfma_f32_16x16x32_bf16 v[18:21], v[178:181], v[214:217], v[18:21]
	v_mfma_f32_16x16x32_bf16 v[10:13], v[162:165], v[234:237], v[10:13]
	v_mfma_f32_16x16x32_bf16 v[2:5], v[178:181], v[234:237], v[2:5]
	s_setprio 0
	s_barrier
	s_add_i32 s75, s75, 2
	s_add_u32 s20, s20, 0x100
	s_addc_u32 s21, s21, 0
	s_add_u32 s73, s73, 0x100
	s_addc_u32 s74, s74, 0
	s_cmp_gt_u32 s75, 29
	s_cbranch_scc0 .LBB0_174

;     __host__ __device__ bool next(int i, Unit& u) const { const bool ok = StaticOrder::next(i, u); u.lm = 0; u.ln = 0; return ok; }
; #define PG8_STAGE(bufoff, gbase, voff) do { _Pragma("unroll") for (int _i = 0; _i < 2; ++_i) \
;         __builtin_amdgcn_global_load_lds((const unsigned*)((const char*)(gbase) + (voff)[_i]), (PG8_LAS unsigned*)(lds + (bufoff) + ldsw + _i * 8192), 16, 0, 0); } while (0)
; #define PG8_LDA(dst, b, h) do { _Pragma("unroll") for (int m = 0; m < 4; ++m) _Pragma("unroll") for (int k = 0; k < 2; ++k) dst[m][k] = *(const PG8_LAS bf16x8*)(lds + PG8_SA(b, h) + aoff + m * 2048 + k * 1024); } while (0)
; #define PG8_LDB(dst, b, h) do { _Pragma("unroll") for (int n = 0; n < 2; ++n) _Pragma("unroll") for (int k = 0; k < 2; ++k) dst[n][k] = *(const PG8_LAS bf16x8*)(lds + PG8_SB(b, h) + boff + n * 2048 + k * 1024); } while (0)
; #define PG8_WAIT_V(n) asm volatile("s_waitcnt vmcnt(" #n ")" ::: "memory")
; #define PG8_BAR __builtin_amdgcn_s_barrier()
; template <class Epi, class Sched, bool ALIGN_EPI = false, bool SP2 = false>
; __device__ __forceinline__ void gemm_phase(PG8_LAS unsigned char* lds, const Gemm g, const Sched& S, const Epi& E, const int wave_id) {
;     ...
;         const bool has_next = S.next(ui + 1, nxt);
;         const char* nA = has_next ? (const char*)g.A + (size_t)nxt.lm * tstep : cA; const char* nB = has_next ? (const char*)g.Bt + (size_t)nxt.ln * tstep : cB;
; #pragma unroll 1
;         for (int t = 0; t < nt; t += 2) {
;             const bool last = (t == nt - 2);
;             const char* a1 = cA + (size_t)(t + 1) * kstep;
;             const char* a2 = last ? nA : cA + (size_t)(t + 2) * kstep; const char* b2 = last ? nB : cB + (size_t)(t + 2) * kstep;
;             const char* a3 = a2 + kstep; const char* b3 = b2 + kstep;
;             if (last && has_next) S.a_ready(nxt);
;             if constexpr (SP2) {
;             PG8_LDB(B0, 0, 0); PG8_LDB(B1, 0, 1); PG8_SCHED; PG8_LDA(At, 0, 0); PG8_STAGE(PG8_SA(1, 1), a1 + hstep, voffA);
;             PG8_WAIT_V(8); PG8_WAIT_L(0); PG8_BAR; PG8_MMA(0, 0, At, B0); PG8_MMA(0, 1, At, B1); PG8_BAR; PG8_SCHED;
;             PG8_LDA(At, 0, 1); PG8_STAGE(PG8_SB(0, 0), b2, voffB); PG8_STAGE(PG8_SB(0, 1), b2 + hstep, voffB); PG8_STAGE(PG8_SA(0, 0), a2, voffA);
;             PG8_WAIT_V(8); PG8_WAIT_L(0); PG8_BAR; PG8_MMA(1, 0, At, B0); PG8_MMA(1, 1, At, B1); PG8_BAR; PG8_SCHED;
.LBB0_523:
	s_ashr_i32 s15, s14, 31
	s_lshl_b64 s[16:17], s[14:15], 20
	s_add_u32 s16, s47, s16
	s_addc_u32 s17, s48, s17
	s_and_b64 s[18:19], s[38:39], exec
	s_cselect_b32 s15, s17, s41
	s_cselect_b32 s21, s16, s40
	s_ashr_i32 s13, s12, 31
	s_lshl_b64 s[18:19], s[12:13], 20
	s_add_u32 s18, s49, s18
	s_addc_u32 s19, s52, s19
	s_and_b64 s[44:45], s[38:39], exec
	s_cselect_b32 s13, s19, s43
	s_cselect_b32 s73, s18, s42
	s_add_u32 s40, s40, 0x80080
	s_addc_u32 s41, s41, 0
	s_add_u32 s74, s42, 0x100
	s_addc_u32 s75, s43, 0
	s_mov_b32 s76, -2
	v_add_u32_e32 v226, 0x10000, v218
	s_add_u32 s42, s40, 0xfff80080
	s_addc_u32 s43, s41, -1
	s_add_i32 s77, 0, 0x10000
	s_cmp_eq_u32 s76, 28
	s_cselect_b32 s45, s15, s43
	s_cselect_b32 s44, s21, s42
	s_cselect_b32 s43, s13, s75
	s_cselect_b32 s42, s73, s74
	s_add_i32 s79, 0, 0x14000
	s_add_i32 m0, s56, 0xc000
	s_nop 0
	global_load_lds_dwordx4 v210, s[40:41]
	ds_read_b128 v[118:121], v226
	ds_read_b128 v[122:125], v226 offset:1024
	ds_read_b128 v[130:133], v226 offset:2048
	ds_read_b128 v[134:137], v226 offset:3072
	ds_read_b128 v[146:149], v226 offset:16384
	ds_read_b128 v[150:153], v226 offset:17408
	ds_read_b128 v[154:157], v226 offset:18432
	ds_read_b128 v[158:161], v226 offset:19456
	s_add_i32 m0, s56, 0xe000
	s_nop 0
	global_load_lds_dwordx4 v212, s[40:41]
	ds_read_b128 v[162:165], v222
	ds_read_b128 v[166:169], v222 offset:1024
	ds_read_b128 v[170:173], v222 offset:2048
	ds_read_b128 v[174:177], v222 offset:3072
	ds_read_b128 v[178:181], v222 offset:4096
	ds_read_b128 v[182:185], v222 offset:5120
	ds_read_b128 v[186:189], v222 offset:6144
	ds_read_b128 v[214:217], v222 offset:7168
	s_waitcnt lgkmcnt(0)
	s_setprio 1
	v_mfma_f32_16x16x32_bf16 v[142:145], v[118:121], v[162:165], 0
	v_mfma_f32_16x16x32_bf16 v[138:141], v[130:133], v[162:165], 0
	v_mfma_f32_16x16x32_bf16 v[110:113], v[118:121], v[170:173], 0
	v_mfma_f32_16x16x32_bf16 v[106:109], v[130:133], v[170:173], 0
	s_waitcnt vmcnt(8)
	s_barrier
	v_mfma_f32_16x16x32_bf16 v[94:97], v[118:121], v[178:181], 0
	v_mfma_f32_16x16x32_bf16 v[90:93], v[130:133], v[178:181], 0
	v_mfma_f32_16x16x32_bf16 v[78:81], v[118:121], v[186:189], 0
	v_mfma_f32_16x16x32_bf16 v[74:77], v[130:133], v[186:189], 0
	v_mfma_f32_16x16x32_bf16 v[142:145], v[122:125], v[166:169], v[142:145]
	v_mfma_f32_16x16x32_bf16 v[138:141], v[134:137], v[166:169], v[138:141]
	v_mfma_f32_16x16x32_bf16 v[110:113], v[122:125], v[174:177], v[110:113]
	v_mfma_f32_16x16x32_bf16 v[106:109], v[134:137], v[174:177], v[106:109]
	v_mfma_f32_16x16x32_bf16 v[94:97], v[122:125], v[182:185], v[94:97]
	v_mfma_f32_16x16x32_bf16 v[90:93], v[134:137], v[182:185], v[90:93]
	v_mfma_f32_16x16x32_bf16 v[78:81], v[122:125], v[214:217], v[78:81]
	v_mfma_f32_16x16x32_bf16 v[74:77], v[134:137], v[214:217], v[74:77]
	s_setprio 0
	s_setprio 1
	v_mfma_f32_16x16x32_bf16 v[126:129], v[146:149], v[162:165], 0
	v_mfma_f32_16x16x32_bf16 v[114:117], v[154:157], v[162:165], 0
	v_mfma_f32_16x16x32_bf16 v[102:105], v[146:149], v[170:173], 0
	v_mfma_f32_16x16x32_bf16 v[98:101], v[154:157], v[170:173], 0
	v_mfma_f32_16x16x32_bf16 v[86:89], v[146:149], v[178:181], 0
	v_mfma_f32_16x16x32_bf16 v[82:85], v[154:157], v[178:181], 0
	v_mfma_f32_16x16x32_bf16 v[70:73], v[146:149], v[186:189], 0
	v_mfma_f32_16x16x32_bf16 v[66:69], v[154:157], v[186:189], 0
	v_mfma_f32_16x16x32_bf16 v[126:129], v[150:153], v[166:169], v[126:129]
	v_mfma_f32_16x16x32_bf16 v[114:117], v[158:161], v[166:169], v[114:117]
	v_mfma_f32_16x16x32_bf16 v[102:105], v[150:153], v[174:177], v[102:105]
	v_mfma_f32_16x16x32_bf16 v[98:101], v[158:161], v[174:177], v[98:101]
	v_mfma_f32_16x16x32_bf16 v[86:89], v[150:153], v[182:185], v[86:89]
	v_mfma_f32_16x16x32_bf16 v[82:85], v[158:161], v[182:185], v[82:85]
	v_mfma_f32_16x16x32_bf16 v[70:73], v[150:153], v[214:217], v[70:73]
	v_mfma_f32_16x16x32_bf16 v[66:69], v[158:161], v[214:217], v[66:69]
	s_setprio 0
	s_barrier
	s_add_i32 s77, s77, s53
	s_mov_b32 m0, s77
	s_nop 0
	global_load_lds_dwordx4 v192, s[42:43]
	ds_read_b128 v[162:165], v222 offset:16384
	ds_read_b128 v[166:169], v222 offset:17408
	s_add_i32 m0, s77, 0x2000
	s_add_u32 s80, s42, 0x80000
	s_addc_u32 s81, s43, 0
	s_add_i32 s77, s79, s53
	global_load_lds_dwordx4 v208, s[42:43]
	ds_read_b128 v[170:173], v222 offset:18432
	ds_read_b128 v[174:177], v222 offset:19456
	s_mov_b32 m0, s77
	s_nop 0
	global_load_lds_dwordx4 v192, s[80:81]
	ds_read_b128 v[178:181], v222 offset:20480
	ds_read_b128 v[182:185], v222 offset:21504
	s_add_i32 m0, s77, 0x2000
	s_nop 0
	global_load_lds_dwordx4 v208, s[80:81]
	ds_read_b128 v[186:189], v222 offset:22528
	ds_read_b128 v[214:217], v222 offset:23552
	s_mov_b32 m0, s56
	s_nop 0
	global_load_lds_dwordx4 v190, s[44:45]
	s_mov_b32 m0, s57
	s_nop 0
	global_load_lds_dwordx4 v206, s[44:45]
	s_waitcnt lgkmcnt(0)
	s_setprio 1
	v_mfma_f32_16x16x32_bf16 v[62:65], v[118:121], v[162:165], 0
	v_mfma_f32_16x16x32_bf16 v[58:61], v[130:133], v[162:165], 0
	v_mfma_f32_16x16x32_bf16 v[46:49], v[118:121], v[170:173], 0
	v_mfma_f32_16x16x32_bf16 v[42:45], v[130:133], v[170:173], 0
	s_waitcnt vmcnt(8)
	s_barrier
; #define PG8_STAGE(bufoff, gbase, voff) do { _Pragma("unroll") for (int _i = 0; _i < 2; ++_i) \
;         __builtin_amdgcn_global_load_lds((const unsigned*)((const char*)(gbase) + (voff)[_i]), (PG8_LAS unsigned*)(lds + (bufoff) + ldsw + _i * 8192), 16, 0, 0); } while (0)
; #define PG8_LDA(dst, b, h) do { _Pragma("unroll") for (int m = 0; m < 4; ++m) _Pragma("unroll") for (int k = 0; k < 2; ++k) dst[m][k] = *(const PG8_LAS bf16x8*)(lds + PG8_SA(b, h) + aoff + m * 2048 + k * 1024); } while (0)
; #define PG8_LDB(dst, b, h) do { _Pragma("unroll") for (int n = 0; n < 2; ++n) _Pragma("unroll") for (int k = 0; k < 2; ++k) dst[n][k] = *(const PG8_LAS bf16x8*)(lds + PG8_SB(b, h) + boff + n * 2048 + k * 1024); } while (0)
; #define PG8_MMA(ai, bj, At, Bt) do { __builtin_amdgcn_s_setprio(1); _Pragma("unroll") for (int m = 0; m < 4; ++m) _Pragma("unroll") for (int n = 0; n < 2; ++n) _Pragma("unroll") for (int k = 0; k < 2; ++k) \
;         acc[ai][bj][m][n] = __builtin_amdgcn_mfma_f32_16x16x32_bf16(Bt[n][k], At[m][k], acc[ai][bj][m][n], 0, 0, 0); __builtin_amdgcn_s_setprio(0); } while (0)
; #define PG8_WAIT_V(n) asm volatile("s_waitcnt vmcnt(" #n ")" ::: "memory")
; #define PG8_WAIT_L(n) asm volatile("s_waitcnt lgkmcnt(" #n ")" ::: "memory")
; #define PG8_BAR __builtin_amdgcn_s_barrier()
; #define PG8_SCHED __builtin_amdgcn_sched_barrier(0)
; template <class Epi, class Sched, bool ALIGN_EPI = false, bool SP2 = false>
; __device__ __forceinline__ void gemm_phase(PG8_LAS unsigned char* lds, const Gemm g, const Sched& S, const Epi& E, const int wave_id) {
;     ...
;             PG8_WAIT_V(8); PG8_WAIT_L(0); PG8_BAR; PG8_MMA(0, 0, At, B0); PG8_MMA(0, 1, At, B1); PG8_BAR; PG8_SCHED;
;             PG8_LDA(At, 0, 1); PG8_STAGE(PG8_SB(0, 0), b2, voffB); PG8_STAGE(PG8_SB(0, 1), b2 + hstep, voffB); PG8_STAGE(PG8_SA(0, 0), a2, voffA);
;             PG8_WAIT_V(8); PG8_WAIT_L(0); PG8_BAR; PG8_MMA(1, 0, At, B0); PG8_MMA(1, 1, At, B1); PG8_BAR; PG8_SCHED;
;             PG8_LDB(B0, 1, 0); PG8_LDB(B1, 1, 1); PG8_SCHED; PG8_LDA(At, 1, 0); PG8_STAGE(PG8_SA(0, 1), a2 + hstep, voffA);
;             PG8_WAIT_V(8); PG8_WAIT_L(0); PG8_BAR; PG8_MMA(0, 0, At, B0); PG8_MMA(0, 1, At, B1); PG8_BAR; PG8_SCHED;
	v_mfma_f32_16x16x32_bf16 v[30:33], v[118:121], v[178:181], 0
	v_mfma_f32_16x16x32_bf16 v[26:29], v[130:133], v[178:181], 0
	v_mfma_f32_16x16x32_bf16 v[14:17], v[118:121], v[186:189], 0
	v_mfma_f32_16x16x32_bf16 v[10:13], v[130:133], v[186:189], 0
	v_mfma_f32_16x16x32_bf16 v[62:65], v[122:125], v[166:169], v[62:65]
	v_mfma_f32_16x16x32_bf16 v[58:61], v[134:137], v[166:169], v[58:61]
	v_mfma_f32_16x16x32_bf16 v[46:49], v[122:125], v[174:177], v[46:49]
	v_mfma_f32_16x16x32_bf16 v[42:45], v[134:137], v[174:177], v[42:45]
	v_mfma_f32_16x16x32_bf16 v[30:33], v[122:125], v[182:185], v[30:33]
	v_mfma_f32_16x16x32_bf16 v[26:29], v[134:137], v[182:185], v[26:29]
	v_mfma_f32_16x16x32_bf16 v[14:17], v[122:125], v[214:217], v[14:17]
	v_mfma_f32_16x16x32_bf16 v[10:13], v[134:137], v[214:217], v[10:13]
	s_setprio 0
	s_setprio 1
	v_mfma_f32_16x16x32_bf16 v[54:57], v[146:149], v[162:165], 0
	v_mfma_f32_16x16x32_bf16 v[50:53], v[154:157], v[162:165], 0
	v_mfma_f32_16x16x32_bf16 v[38:41], v[146:149], v[170:173], 0
	v_mfma_f32_16x16x32_bf16 v[34:37], v[154:157], v[170:173], 0
	v_mfma_f32_16x16x32_bf16 v[22:25], v[146:149], v[178:181], 0
	v_mfma_f32_16x16x32_bf16 v[18:21], v[154:157], v[178:181], 0
	v_mfma_f32_16x16x32_bf16 v[6:9], v[146:149], v[186:189], 0
	v_mfma_f32_16x16x32_bf16 v[2:5], v[154:157], v[186:189], 0
	v_mfma_f32_16x16x32_bf16 v[54:57], v[150:153], v[166:169], v[54:57]
	v_mfma_f32_16x16x32_bf16 v[50:53], v[158:161], v[166:169], v[50:53]
	v_mfma_f32_16x16x32_bf16 v[38:41], v[150:153], v[174:177], v[38:41]
	v_mfma_f32_16x16x32_bf16 v[34:37], v[158:161], v[174:177], v[34:37]
	v_mfma_f32_16x16x32_bf16 v[22:25], v[150:153], v[182:185], v[22:25]
	v_mfma_f32_16x16x32_bf16 v[18:21], v[158:161], v[182:185], v[18:21]
	v_mfma_f32_16x16x32_bf16 v[6:9], v[150:153], v[214:217], v[6:9]
	v_mfma_f32_16x16x32_bf16 v[2:5], v[158:161], v[214:217], v[2:5]
	s_setprio 0
	s_barrier
	s_add_i32 s77, 0, 0x18000
	s_add_i32 s79, 0, 0x1c000
	s_add_u32 s44, s44, 0x80000
	s_addc_u32 s45, s45, 0
	s_mov_b32 m0, s64
	s_nop 0
	global_load_lds_dwordx4 v190, s[44:45]
	ds_read_b128 v[118:121], v226 offset:32768
	ds_read_b128 v[122:125], v226 offset:33792
	ds_read_b128 v[130:133], v226 offset:34816
	ds_read_b128 v[134:137], v226 offset:35840
	ds_read_b128 v[146:149], v226 offset:49152
	ds_read_b128 v[150:153], v226 offset:50176
	ds_read_b128 v[154:157], v226 offset:51200
	ds_read_b128 v[158:161], v226 offset:52224
	s_mov_b32 m0, s65
	s_nop 0
	global_load_lds_dwordx4 v206, s[44:45]
	ds_read_b128 v[162:165], v222 offset:32768
	ds_read_b128 v[166:169], v222 offset:33792
	ds_read_b128 v[170:173], v222 offset:34816
	ds_read_b128 v[174:177], v222 offset:35840
	ds_read_b128 v[178:181], v222 offset:36864
	ds_read_b128 v[182:185], v222 offset:37888
	ds_read_b128 v[186:189], v222 offset:38912
	ds_read_b128 v[214:217], v222 offset:39936
	s_waitcnt lgkmcnt(0)
	s_setprio 1
	v_mfma_f32_16x16x32_bf16 v[142:145], v[118:121], v[162:165], v[142:145]
	v_mfma_f32_16x16x32_bf16 v[138:141], v[130:133], v[162:165], v[138:141]
	v_mfma_f32_16x16x32_bf16 v[110:113], v[118:121], v[170:173], v[110:113]
	v_mfma_f32_16x16x32_bf16 v[106:109], v[130:133], v[170:173], v[106:109]
	s_waitcnt vmcnt(8)
	s_barrier
	v_mfma_f32_16x16x32_bf16 v[94:97], v[118:121], v[178:181], v[94:97]
	v_mfma_f32_16x16x32_bf16 v[90:93], v[130:133], v[178:181], v[90:93]
	v_mfma_f32_16x16x32_bf16 v[78:81], v[118:121], v[186:189], v[78:81]
	v_mfma_f32_16x16x32_bf16 v[74:77], v[130:133], v[186:189], v[74:77]
	v_mfma_f32_16x16x32_bf16 v[142:145], v[122:125], v[166:169], v[142:145]
	v_mfma_f32_16x16x32_bf16 v[138:141], v[134:137], v[166:169], v[138:141]
	v_mfma_f32_16x16x32_bf16 v[110:113], v[122:125], v[174:177], v[110:113]
	v_mfma_f32_16x16x32_bf16 v[106:109], v[134:137], v[174:177], v[106:109]
	v_mfma_f32_16x16x32_bf16 v[94:97], v[122:125], v[182:185], v[94:97]
	v_mfma_f32_16x16x32_bf16 v[90:93], v[134:137], v[182:185], v[90:93]
	v_mfma_f32_16x16x32_bf16 v[78:81], v[122:125], v[214:217], v[78:81]
	v_mfma_f32_16x16x32_bf16 v[74:77], v[134:137], v[214:217], v[74:77]
	s_setprio 0
	s_setprio 1
	v_mfma_f32_16x16x32_bf16 v[126:129], v[146:149], v[162:165], v[126:129]
	v_mfma_f32_16x16x32_bf16 v[114:117], v[154:157], v[162:165], v[114:117]
	v_mfma_f32_16x16x32_bf16 v[102:105], v[146:149], v[170:173], v[102:105]
	v_mfma_f32_16x16x32_bf16 v[98:101], v[154:157], v[170:173], v[98:101]
	v_mfma_f32_16x16x32_bf16 v[86:89], v[146:149], v[178:181], v[86:89]
	v_mfma_f32_16x16x32_bf16 v[82:85], v[154:157], v[178:181], v[82:85]
	v_mfma_f32_16x16x32_bf16 v[70:73], v[146:149], v[186:189], v[70:73]
	v_mfma_f32_16x16x32_bf16 v[66:69], v[154:157], v[186:189], v[66:69]
	v_mfma_f32_16x16x32_bf16 v[126:129], v[150:153], v[166:169], v[126:129]
	v_mfma_f32_16x16x32_bf16 v[114:117], v[158:161], v[166:169], v[114:117]
	v_mfma_f32_16x16x32_bf16 v[102:105], v[150:153], v[174:177], v[102:105]
	v_mfma_f32_16x16x32_bf16 v[98:101], v[158:161], v[174:177], v[98:101]
	v_mfma_f32_16x16x32_bf16 v[86:89], v[150:153], v[182:185], v[86:89]
	v_mfma_f32_16x16x32_bf16 v[82:85], v[158:161], v[182:185], v[82:85]
	v_mfma_f32_16x16x32_bf16 v[70:73], v[150:153], v[214:217], v[70:73]
	v_mfma_f32_16x16x32_bf16 v[66:69], v[158:161], v[214:217], v[66:69]
	s_setprio 0
	s_barrier
; #define PG8_STAGE(bufoff, gbase, voff) do { _Pragma("unroll") for (int _i = 0; _i < 2; ++_i) \
;         __builtin_amdgcn_global_load_lds((const unsigned*)((const char*)(gbase) + (voff)[_i]), (PG8_LAS unsigned*)(lds + (bufoff) + ldsw + _i * 8192), 16, 0, 0); } while (0)
; #define PG8_LDA(dst, b, h) do { _Pragma("unroll") for (int m = 0; m < 4; ++m) _Pragma("unroll") for (int k = 0; k < 2; ++k) dst[m][k] = *(const PG8_LAS bf16x8*)(lds + PG8_SA(b, h) + aoff + m * 2048 + k * 1024); } while (0)
; #define PG8_LDB(dst, b, h) do { _Pragma("unroll") for (int n = 0; n < 2; ++n) _Pragma("unroll") for (int k = 0; k < 2; ++k) dst[n][k] = *(const PG8_LAS bf16x8*)(lds + PG8_SB(b, h) + boff + n * 2048 + k * 1024); } while (0)
; #define PG8_WAIT_V(n) asm volatile("s_waitcnt vmcnt(" #n ")" ::: "memory")
; #define PG8_WAIT_L(n) asm volatile("s_waitcnt lgkmcnt(" #n ")" ::: "memory")
; #define PG8_BAR __builtin_amdgcn_s_barrier()
; #define PG8_SCHED __builtin_amdgcn_sched_barrier(0)
; template <class Epi, class Sched, bool ALIGN_EPI = false, bool SP2 = false>
; __device__ __forceinline__ void gemm_phase(PG8_LAS unsigned char* lds, const Gemm g, const Sched& S, const Epi& E, const int wave_id) {
;     ...
;         for (int t = 0; t < nt; t += 2) {
;             const bool last = (t == nt - 2);
;             const char* a1 = cA + (size_t)(t + 1) * kstep;
;             const char* a2 = last ? nA : cA + (size_t)(t + 2) * kstep; const char* b2 = last ? nB : cB + (size_t)(t + 2) * kstep;
;             const char* a3 = a2 + kstep; const char* b3 = b2 + kstep;
;             if (last && has_next) S.a_ready(nxt);
;             if constexpr (SP2) {
;             PG8_LDB(B0, 0, 0); PG8_LDB(B1, 0, 1); PG8_SCHED; PG8_LDA(At, 0, 0); PG8_STAGE(PG8_SA(1, 1), a1 + hstep, voffA);
;             PG8_WAIT_V(8); PG8_WAIT_L(0); PG8_BAR; PG8_MMA(0, 0, At, B0); PG8_MMA(0, 1, At, B1); PG8_BAR; PG8_SCHED;
;     ...
;             PG8_LDB(B0, 1, 0); PG8_LDB(B1, 1, 1); PG8_SCHED; PG8_LDA(At, 1, 0); PG8_STAGE(PG8_SA(0, 1), a2 + hstep, voffA);
;             PG8_WAIT_V(8); PG8_WAIT_L(0); PG8_BAR; PG8_MMA(0, 0, At, B0); PG8_MMA(0, 1, At, B1); PG8_BAR; PG8_SCHED;
;             PG8_LDA(At, 1, 1); PG8_STAGE(PG8_SB(1, 0), b3, voffB); PG8_STAGE(PG8_SB(1, 1), b3 + hstep, voffB); PG8_STAGE(PG8_SA(1, 0), a3, voffA);
;             PG8_WAIT_V(8); PG8_WAIT_L(0); PG8_BAR; PG8_MMA(1, 0, At, B0); PG8_MMA(1, 1, At, B1); PG8_BAR; PG8_SCHED;
	s_add_u32 vcc_lo, s44, 0xfff80080
	s_addc_u32 vcc_hi, s45, -1
	s_mov_b32 m0, s70
	s_nop 0
	global_load_lds_dwordx4 v190, vcc
	ds_read_b128 v[162:165], v222 offset:49152
	ds_read_b128 v[166:169], v222 offset:50176
	s_mov_b32 m0, s71
	s_add_i32 s44, s77, s53
	global_load_lds_dwordx4 v206, vcc
	ds_read_b128 v[170:173], v222 offset:51200
	ds_read_b128 v[174:177], v222 offset:52224
	s_add_u32 vcc_lo, s42, 0x80
	s_addc_u32 vcc_hi, s43, 0
	s_mov_b32 m0, s44
	s_nop 0
	global_load_lds_dwordx4 v192, vcc
	ds_read_b128 v[178:181], v222 offset:53248
	ds_read_b128 v[182:185], v222 offset:54272
	s_add_i32 m0, s44, 0x2000
	s_add_u32 s42, s42, 0x80080
	s_addc_u32 s43, s43, 0
	global_load_lds_dwordx4 v208, vcc
	ds_read_b128 v[186:189], v222 offset:55296
	ds_read_b128 v[214:217], v222 offset:56320
	s_add_i32 s44, s79, s53
	s_mov_b32 m0, s44
	s_nop 0
	global_load_lds_dwordx4 v192, s[42:43]
	s_add_i32 m0, s44, 0x2000
	s_nop 0
	global_load_lds_dwordx4 v208, s[42:43]
	s_waitcnt lgkmcnt(0)
	s_setprio 1
	v_mfma_f32_16x16x32_bf16 v[62:65], v[118:121], v[162:165], v[62:65]
	v_mfma_f32_16x16x32_bf16 v[58:61], v[130:133], v[162:165], v[58:61]
	v_mfma_f32_16x16x32_bf16 v[46:49], v[118:121], v[170:173], v[46:49]
	v_mfma_f32_16x16x32_bf16 v[42:45], v[130:133], v[170:173], v[42:45]
	s_waitcnt vmcnt(8)
	s_barrier
	v_mfma_f32_16x16x32_bf16 v[30:33], v[118:121], v[178:181], v[30:33]
	v_mfma_f32_16x16x32_bf16 v[26:29], v[130:133], v[178:181], v[26:29]
	v_mfma_f32_16x16x32_bf16 v[14:17], v[118:121], v[186:189], v[14:17]
	v_mfma_f32_16x16x32_bf16 v[10:13], v[130:133], v[186:189], v[10:13]
	v_mfma_f32_16x16x32_bf16 v[62:65], v[122:125], v[166:169], v[62:65]
	v_mfma_f32_16x16x32_bf16 v[58:61], v[134:137], v[166:169], v[58:61]
	v_mfma_f32_16x16x32_bf16 v[46:49], v[122:125], v[174:177], v[46:49]
	v_mfma_f32_16x16x32_bf16 v[42:45], v[134:137], v[174:177], v[42:45]
	v_mfma_f32_16x16x32_bf16 v[30:33], v[122:125], v[182:185], v[30:33]
	v_mfma_f32_16x16x32_bf16 v[26:29], v[134:137], v[182:185], v[26:29]
	v_mfma_f32_16x16x32_bf16 v[14:17], v[122:125], v[214:217], v[14:17]
	v_mfma_f32_16x16x32_bf16 v[10:13], v[134:137], v[214:217], v[10:13]
	s_setprio 0
	s_setprio 1
	v_mfma_f32_16x16x32_bf16 v[54:57], v[146:149], v[162:165], v[54:57]
	v_mfma_f32_16x16x32_bf16 v[50:53], v[154:157], v[162:165], v[50:53]
	v_mfma_f32_16x16x32_bf16 v[38:41], v[146:149], v[170:173], v[38:41]
	v_mfma_f32_16x16x32_bf16 v[34:37], v[154:157], v[170:173], v[34:37]
	v_mfma_f32_16x16x32_bf16 v[22:25], v[146:149], v[178:181], v[22:25]
	v_mfma_f32_16x16x32_bf16 v[18:21], v[154:157], v[178:181], v[18:21]
	v_mfma_f32_16x16x32_bf16 v[6:9], v[146:149], v[186:189], v[6:9]
	v_mfma_f32_16x16x32_bf16 v[2:5], v[154:157], v[186:189], v[2:5]
	v_mfma_f32_16x16x32_bf16 v[54:57], v[150:153], v[166:169], v[54:57]
	v_mfma_f32_16x16x32_bf16 v[50:53], v[158:161], v[166:169], v[50:53]
	v_mfma_f32_16x16x32_bf16 v[38:41], v[150:153], v[174:177], v[38:41]
	v_mfma_f32_16x16x32_bf16 v[34:37], v[158:161], v[174:177], v[34:37]
	v_mfma_f32_16x16x32_bf16 v[22:25], v[150:153], v[182:185], v[22:25]
	v_mfma_f32_16x16x32_bf16 v[18:21], v[158:161], v[182:185], v[18:21]
	v_mfma_f32_16x16x32_bf16 v[6:9], v[150:153], v[214:217], v[6:9]
	v_mfma_f32_16x16x32_bf16 v[2:5], v[158:161], v[214:217], v[2:5]
	s_setprio 0
	s_barrier
	s_add_i32 s76, s76, 2
	s_add_u32 s40, s40, 0x100
	s_addc_u32 s41, s41, 0
	s_add_u32 s74, s74, 0x100
	s_addc_u32 s75, s75, 0
	s_cmp_gt_u32 s76, 29
	s_cbranch_scc1 .Lpeel_exit_g2
.LBB0_524:
	s_add_u32 s42, s40, 0xfff80080
	s_addc_u32 s43, s41, -1
	s_add_i32 s77, 0, 0x10000
	s_cmp_eq_u32 s76, 28
	s_cselect_b32 s45, s15, s43
	s_cselect_b32 s44, s21, s42
	s_cselect_b32 s43, s13, s75
	s_cselect_b32 s42, s73, s74
	s_add_i32 s79, 0, 0x14000
	s_add_i32 m0, s56, 0xc000
	s_nop 0
	global_load_lds_dwordx4 v210, s[40:41]
	ds_read_b128 v[118:121], v226
	ds_read_b128 v[122:125], v226 offset:1024
	ds_read_b128 v[130:133], v226 offset:2048
	ds_read_b128 v[134:137], v226 offset:3072
	ds_read_b128 v[146:149], v226 offset:16384
	ds_read_b128 v[150:153], v226 offset:17408
	ds_read_b128 v[154:157], v226 offset:18432
	ds_read_b128 v[158:161], v226 offset:19456
	s_add_i32 m0, s56, 0xe000
	s_nop 0
	global_load_lds_dwordx4 v212, s[40:41]
	ds_read_b128 v[162:165], v222
	ds_read_b128 v[166:169], v222 offset:1024
	ds_read_b128 v[170:173], v222 offset:2048
	ds_read_b128 v[174:177], v222 offset:3072
	ds_read_b128 v[178:181], v222 offset:4096
	ds_read_b128 v[182:185], v222 offset:5120
	ds_read_b128 v[186:189], v222 offset:6144
	ds_read_b128 v[214:217], v222 offset:7168
	s_waitcnt lgkmcnt(0)
	s_setprio 1
	v_mfma_f32_16x16x32_bf16 v[142:145], v[118:121], v[162:165], v[142:145]
	v_mfma_f32_16x16x32_bf16 v[138:141], v[130:133], v[162:165], v[138:141]
	v_mfma_f32_16x16x32_bf16 v[110:113], v[118:121], v[170:173], v[110:113]
	v_mfma_f32_16x16x32_bf16 v[106:109], v[130:133], v[170:173], v[106:109]
	s_waitcnt vmcnt(8)
	s_barrier
; #define PG8_STAGE(bufoff, gbase, voff) do { _Pragma("unroll") for (int _i = 0; _i < 2; ++_i) \
;         __builtin_amdgcn_global_load_lds((const unsigned*)((const char*)(gbase) + (voff)[_i]), (PG8_LAS unsigned*)(lds + (bufoff) + ldsw + _i * 8192), 16, 0, 0); } while (0)
; #define PG8_LDA(dst, b, h) do { _Pragma("unroll") for (int m = 0; m < 4; ++m) _Pragma("unroll") for (int k = 0; k < 2; ++k) dst[m][k] = *(const PG8_LAS bf16x8*)(lds + PG8_SA(b, h) + aoff + m * 2048 + k * 1024); } while (0)
; #define PG8_LDB(dst, b, h) do { _Pragma("unroll") for (int n = 0; n < 2; ++n) _Pragma("unroll") for (int k = 0; k < 2; ++k) dst[n][k] = *(const PG8_LAS bf16x8*)(lds + PG8_SB(b, h) + boff + n * 2048 + k * 1024); } while (0)
; #define PG8_MMA(ai, bj, At, Bt) do { __builtin_amdgcn_s_setprio(1); _Pragma("unroll") for (int m = 0; m < 4; ++m) _Pragma("unroll") for (int n = 0; n < 2; ++n) _Pragma("unroll") for (int k = 0; k < 2; ++k) \
;         acc[ai][bj][m][n] = __builtin_amdgcn_mfma_f32_16x16x32_bf16(Bt[n][k], At[m][k], acc[ai][bj][m][n], 0, 0, 0); __builtin_amdgcn_s_setprio(0); } while (0)
; #define PG8_WAIT_V(n) asm volatile("s_waitcnt vmcnt(" #n ")" ::: "memory")
; #define PG8_WAIT_L(n) asm volatile("s_waitcnt lgkmcnt(" #n ")" ::: "memory")
; #define PG8_BAR __builtin_amdgcn_s_barrier()
; #define PG8_SCHED __builtin_amdgcn_sched_barrier(0)
; template <class Epi, class Sched, bool ALIGN_EPI = false, bool SP2 = false>
; __device__ __forceinline__ void gemm_phase(PG8_LAS unsigned char* lds, const Gemm g, const Sched& S, const Epi& E, const int wave_id) {
;     ...
;             PG8_LDB(B0, 0, 0); PG8_LDB(B1, 0, 1); PG8_SCHED; PG8_LDA(At, 0, 0); PG8_STAGE(PG8_SA(1, 1), a1 + hstep, voffA);
;             PG8_WAIT_V(8); PG8_WAIT_L(0); PG8_BAR; PG8_MMA(0, 0, At, B0); PG8_MMA(0, 1, At, B1); PG8_BAR; PG8_SCHED;
;             PG8_LDA(At, 0, 1); PG8_STAGE(PG8_SB(0, 0), b2, voffB); PG8_STAGE(PG8_SB(0, 1), b2 + hstep, voffB); PG8_STAGE(PG8_SA(0, 0), a2, voffA);
;             PG8_WAIT_V(8); PG8_WAIT_L(0); PG8_BAR; PG8_MMA(1, 0, At, B0); PG8_MMA(1, 1, At, B1); PG8_BAR; PG8_SCHED;
	v_mfma_f32_16x16x32_bf16 v[94:97], v[118:121], v[178:181], v[94:97]
	v_mfma_f32_16x16x32_bf16 v[90:93], v[130:133], v[178:181], v[90:93]
	v_mfma_f32_16x16x32_bf16 v[78:81], v[118:121], v[186:189], v[78:81]
	v_mfma_f32_16x16x32_bf16 v[74:77], v[130:133], v[186:189], v[74:77]
	v_mfma_f32_16x16x32_bf16 v[142:145], v[122:125], v[166:169], v[142:145]
	v_mfma_f32_16x16x32_bf16 v[138:141], v[134:137], v[166:169], v[138:141]
	v_mfma_f32_16x16x32_bf16 v[110:113], v[122:125], v[174:177], v[110:113]
	v_mfma_f32_16x16x32_bf16 v[106:109], v[134:137], v[174:177], v[106:109]
	v_mfma_f32_16x16x32_bf16 v[94:97], v[122:125], v[182:185], v[94:97]
	v_mfma_f32_16x16x32_bf16 v[90:93], v[134:137], v[182:185], v[90:93]
	v_mfma_f32_16x16x32_bf16 v[78:81], v[122:125], v[214:217], v[78:81]
	v_mfma_f32_16x16x32_bf16 v[74:77], v[134:137], v[214:217], v[74:77]
	s_setprio 0
	s_setprio 1
	v_mfma_f32_16x16x32_bf16 v[126:129], v[146:149], v[162:165], v[126:129]
	v_mfma_f32_16x16x32_bf16 v[114:117], v[154:157], v[162:165], v[114:117]
	v_mfma_f32_16x16x32_bf16 v[102:105], v[146:149], v[170:173], v[102:105]
	v_mfma_f32_16x16x32_bf16 v[98:101], v[154:157], v[170:173], v[98:101]
	v_mfma_f32_16x16x32_bf16 v[86:89], v[146:149], v[178:181], v[86:89]
	v_mfma_f32_16x16x32_bf16 v[82:85], v[154:157], v[178:181], v[82:85]
	v_mfma_f32_16x16x32_bf16 v[70:73], v[146:149], v[186:189], v[70:73]
	v_mfma_f32_16x16x32_bf16 v[66:69], v[154:157], v[186:189], v[66:69]
	v_mfma_f32_16x16x32_bf16 v[126:129], v[150:153], v[166:169], v[126:129]
	v_mfma_f32_16x16x32_bf16 v[114:117], v[158:161], v[166:169], v[114:117]
	v_mfma_f32_16x16x32_bf16 v[102:105], v[150:153], v[174:177], v[102:105]
	v_mfma_f32_16x16x32_bf16 v[98:101], v[158:161], v[174:177], v[98:101]
	v_mfma_f32_16x16x32_bf16 v[86:89], v[150:153], v[182:185], v[86:89]
	v_mfma_f32_16x16x32_bf16 v[82:85], v[158:161], v[182:185], v[82:85]
	v_mfma_f32_16x16x32_bf16 v[70:73], v[150:153], v[214:217], v[70:73]
	v_mfma_f32_16x16x32_bf16 v[66:69], v[158:161], v[214:217], v[66:69]
	s_setprio 0
	s_barrier
	s_add_i32 s77, s77, s53
	s_mov_b32 m0, s77
	s_nop 0
	global_load_lds_dwordx4 v192, s[42:43]
	ds_read_b128 v[162:165], v222 offset:16384
	ds_read_b128 v[166:169], v222 offset:17408
	s_add_i32 m0, s77, 0x2000
	s_add_u32 s80, s42, 0x80000
	s_addc_u32 s81, s43, 0
	s_add_i32 s77, s79, s53
	global_load_lds_dwordx4 v208, s[42:43]
	ds_read_b128 v[170:173], v222 offset:18432
	ds_read_b128 v[174:177], v222 offset:19456
	s_mov_b32 m0, s77
	s_nop 0
	global_load_lds_dwordx4 v192, s[80:81]
	ds_read_b128 v[178:181], v222 offset:20480
	ds_read_b128 v[182:185], v222 offset:21504
	s_add_i32 m0, s77, 0x2000
	s_nop 0
	global_load_lds_dwordx4 v208, s[80:81]
	ds_read_b128 v[186:189], v222 offset:22528
	ds_read_b128 v[214:217], v222 offset:23552
	s_mov_b32 m0, s56
	s_nop 0
	global_load_lds_dwordx4 v190, s[44:45]
	s_mov_b32 m0, s57
	s_nop 0
	global_load_lds_dwordx4 v206, s[44:45]
	s_waitcnt lgkmcnt(0)
	s_setprio 1
	v_mfma_f32_16x16x32_bf16 v[62:65], v[118:121], v[162:165], v[62:65]
	v_mfma_f32_16x16x32_bf16 v[58:61], v[130:133], v[162:165], v[58:61]
	v_mfma_f32_16x16x32_bf16 v[46:49], v[118:121], v[170:173], v[46:49]
	v_mfma_f32_16x16x32_bf16 v[42:45], v[130:133], v[170:173], v[42:45]
	s_waitcnt vmcnt(8)
	s_barrier
	v_mfma_f32_16x16x32_bf16 v[30:33], v[118:121], v[178:181], v[30:33]
	v_mfma_f32_16x16x32_bf16 v[26:29], v[130:133], v[178:181], v[26:29]
	v_mfma_f32_16x16x32_bf16 v[14:17], v[118:121], v[186:189], v[14:17]
	v_mfma_f32_16x16x32_bf16 v[10:13], v[130:133], v[186:189], v[10:13]
	v_mfma_f32_16x16x32_bf16 v[62:65], v[122:125], v[166:169], v[62:65]
	v_mfma_f32_16x16x32_bf16 v[58:61], v[134:137], v[166:169], v[58:61]
	v_mfma_f32_16x16x32_bf16 v[46:49], v[122:125], v[174:177], v[46:49]
	v_mfma_f32_16x16x32_bf16 v[42:45], v[134:137], v[174:177], v[42:45]
	v_mfma_f32_16x16x32_bf16 v[30:33], v[122:125], v[182:185], v[30:33]
	v_mfma_f32_16x16x32_bf16 v[26:29], v[134:137], v[182:185], v[26:29]
	v_mfma_f32_16x16x32_bf16 v[14:17], v[122:125], v[214:217], v[14:17]
	v_mfma_f32_16x16x32_bf16 v[10:13], v[134:137], v[214:217], v[10:13]
	s_setprio 0
	s_setprio 1
	v_mfma_f32_16x16x32_bf16 v[54:57], v[146:149], v[162:165], v[54:57]
	v_mfma_f32_16x16x32_bf16 v[50:53], v[154:157], v[162:165], v[50:53]
	v_mfma_f32_16x16x32_bf16 v[38:41], v[146:149], v[170:173], v[38:41]
	v_mfma_f32_16x16x32_bf16 v[34:37], v[154:157], v[170:173], v[34:37]
	v_mfma_f32_16x16x32_bf16 v[22:25], v[146:149], v[178:181], v[22:25]
	v_mfma_f32_16x16x32_bf16 v[18:21], v[154:157], v[178:181], v[18:21]
	v_mfma_f32_16x16x32_bf16 v[6:9], v[146:149], v[186:189], v[6:9]
	v_mfma_f32_16x16x32_bf16 v[2:5], v[154:157], v[186:189], v[2:5]
	v_mfma_f32_16x16x32_bf16 v[54:57], v[150:153], v[166:169], v[54:57]
	v_mfma_f32_16x16x32_bf16 v[50:53], v[158:161], v[166:169], v[50:53]
	v_mfma_f32_16x16x32_bf16 v[38:41], v[150:153], v[174:177], v[38:41]
	v_mfma_f32_16x16x32_bf16 v[34:37], v[158:161], v[174:177], v[34:37]
	v_mfma_f32_16x16x32_bf16 v[22:25], v[150:153], v[182:185], v[22:25]
	v_mfma_f32_16x16x32_bf16 v[18:21], v[158:161], v[182:185], v[18:21]
	v_mfma_f32_16x16x32_bf16 v[6:9], v[150:153], v[214:217], v[6:9]
	v_mfma_f32_16x16x32_bf16 v[2:5], v[158:161], v[214:217], v[2:5]
	s_setprio 0
	s_barrier
; #define PG8_STAGE(bufoff, gbase, voff) do { _Pragma("unroll") for (int _i = 0; _i < 2; ++_i) \
;         __builtin_amdgcn_global_load_lds((const unsigned*)((const char*)(gbase) + (voff)[_i]), (PG8_LAS unsigned*)(lds + (bufoff) + ldsw + _i * 8192), 16, 0, 0); } while (0)
; #define PG8_LDA(dst, b, h) do { _Pragma("unroll") for (int m = 0; m < 4; ++m) _Pragma("unroll") for (int k = 0; k < 2; ++k) dst[m][k] = *(const PG8_LAS bf16x8*)(lds + PG8_SA(b, h) + aoff + m * 2048 + k * 1024); } while (0)
; #define PG8_LDB(dst, b, h) do { _Pragma("unroll") for (int n = 0; n < 2; ++n) _Pragma("unroll") for (int k = 0; k < 2; ++k) dst[n][k] = *(const PG8_LAS bf16x8*)(lds + PG8_SB(b, h) + boff + n * 2048 + k * 1024); } while (0)
; #define PG8_MMA(ai, bj, At, Bt) do { __builtin_amdgcn_s_setprio(1); _Pragma("unroll") for (int m = 0; m < 4; ++m) _Pragma("unroll") for (int n = 0; n < 2; ++n) _Pragma("unroll") for (int k = 0; k < 2; ++k) \
;         acc[ai][bj][m][n] = __builtin_amdgcn_mfma_f32_16x16x32_bf16(Bt[n][k], At[m][k], acc[ai][bj][m][n], 0, 0, 0); __builtin_amdgcn_s_setprio(0); } while (0)
; #define PG8_WAIT_V(n) asm volatile("s_waitcnt vmcnt(" #n ")" ::: "memory")
; #define PG8_WAIT_L(n) asm volatile("s_waitcnt lgkmcnt(" #n ")" ::: "memory")
; #define PG8_BAR __builtin_amdgcn_s_barrier()
; #define PG8_SCHED __builtin_amdgcn_sched_barrier(0)
; template <class Epi, class Sched, bool ALIGN_EPI = false, bool SP2 = false>
; __device__ __forceinline__ void gemm_phase(PG8_LAS unsigned char* lds, const Gemm g, const Sched& S, const Epi& E, const int wave_id) {
;     ...
;             PG8_LDB(B0, 1, 0); PG8_LDB(B1, 1, 1); PG8_SCHED; PG8_LDA(At, 1, 0); PG8_STAGE(PG8_SA(0, 1), a2 + hstep, voffA);
;             PG8_WAIT_V(8); PG8_WAIT_L(0); PG8_BAR; PG8_MMA(0, 0, At, B0); PG8_MMA(0, 1, At, B1); PG8_BAR; PG8_SCHED;
;             PG8_LDA(At, 1, 1); PG8_STAGE(PG8_SB(1, 0), b3, voffB); PG8_STAGE(PG8_SB(1, 1), b3 + hstep, voffB); PG8_STAGE(PG8_SA(1, 0), a3, voffA);
;             PG8_WAIT_V(8); PG8_WAIT_L(0); PG8_BAR; PG8_MMA(1, 0, At, B0); PG8_MMA(1, 1, At, B1); PG8_BAR; PG8_SCHED;
	s_add_i32 s77, 0, 0x18000
	s_add_i32 s79, 0, 0x1c000
	s_add_u32 s44, s44, 0x80000
	s_addc_u32 s45, s45, 0
	s_mov_b32 m0, s64
	s_nop 0
	global_load_lds_dwordx4 v190, s[44:45]
	ds_read_b128 v[118:121], v226 offset:32768
	ds_read_b128 v[122:125], v226 offset:33792
	ds_read_b128 v[130:133], v226 offset:34816
	ds_read_b128 v[134:137], v226 offset:35840
	ds_read_b128 v[146:149], v226 offset:49152
	ds_read_b128 v[150:153], v226 offset:50176
	ds_read_b128 v[154:157], v226 offset:51200
	ds_read_b128 v[158:161], v226 offset:52224
	s_mov_b32 m0, s65
	s_nop 0
	global_load_lds_dwordx4 v206, s[44:45]
	ds_read_b128 v[162:165], v222 offset:32768
	ds_read_b128 v[166:169], v222 offset:33792
	ds_read_b128 v[170:173], v222 offset:34816
	ds_read_b128 v[174:177], v222 offset:35840
	ds_read_b128 v[178:181], v222 offset:36864
	ds_read_b128 v[182:185], v222 offset:37888
	ds_read_b128 v[186:189], v222 offset:38912
	ds_read_b128 v[214:217], v222 offset:39936
	s_waitcnt lgkmcnt(0)
	s_setprio 1
	v_mfma_f32_16x16x32_bf16 v[142:145], v[118:121], v[162:165], v[142:145]
	v_mfma_f32_16x16x32_bf16 v[138:141], v[130:133], v[162:165], v[138:141]
	v_mfma_f32_16x16x32_bf16 v[110:113], v[118:121], v[170:173], v[110:113]
	v_mfma_f32_16x16x32_bf16 v[106:109], v[130:133], v[170:173], v[106:109]
	s_waitcnt vmcnt(8)
	s_barrier
	v_mfma_f32_16x16x32_bf16 v[94:97], v[118:121], v[178:181], v[94:97]
	v_mfma_f32_16x16x32_bf16 v[90:93], v[130:133], v[178:181], v[90:93]
	v_mfma_f32_16x16x32_bf16 v[78:81], v[118:121], v[186:189], v[78:81]
	v_mfma_f32_16x16x32_bf16 v[74:77], v[130:133], v[186:189], v[74:77]
	v_mfma_f32_16x16x32_bf16 v[142:145], v[122:125], v[166:169], v[142:145]
	v_mfma_f32_16x16x32_bf16 v[138:141], v[134:137], v[166:169], v[138:141]
	v_mfma_f32_16x16x32_bf16 v[110:113], v[122:125], v[174:177], v[110:113]
	v_mfma_f32_16x16x32_bf16 v[106:109], v[134:137], v[174:177], v[106:109]
	v_mfma_f32_16x16x32_bf16 v[94:97], v[122:125], v[182:185], v[94:97]
	v_mfma_f32_16x16x32_bf16 v[90:93], v[134:137], v[182:185], v[90:93]
	v_mfma_f32_16x16x32_bf16 v[78:81], v[122:125], v[214:217], v[78:81]
	v_mfma_f32_16x16x32_bf16 v[74:77], v[134:137], v[214:217], v[74:77]
	s_setprio 0
	s_setprio 1
	v_mfma_f32_16x16x32_bf16 v[126:129], v[146:149], v[162:165], v[126:129]
	v_mfma_f32_16x16x32_bf16 v[114:117], v[154:157], v[162:165], v[114:117]
	v_mfma_f32_16x16x32_bf16 v[102:105], v[146:149], v[170:173], v[102:105]
	v_mfma_f32_16x16x32_bf16 v[98:101], v[154:157], v[170:173], v[98:101]
	v_mfma_f32_16x16x32_bf16 v[86:89], v[146:149], v[178:181], v[86:89]
	v_mfma_f32_16x16x32_bf16 v[82:85], v[154:157], v[178:181], v[82:85]
	v_mfma_f32_16x16x32_bf16 v[70:73], v[146:149], v[186:189], v[70:73]
	v_mfma_f32_16x16x32_bf16 v[66:69], v[154:157], v[186:189], v[66:69]
	v_mfma_f32_16x16x32_bf16 v[126:129], v[150:153], v[166:169], v[126:129]
	v_mfma_f32_16x16x32_bf16 v[114:117], v[158:161], v[166:169], v[114:117]
	v_mfma_f32_16x16x32_bf16 v[102:105], v[150:153], v[174:177], v[102:105]
	v_mfma_f32_16x16x32_bf16 v[98:101], v[158:161], v[174:177], v[98:101]
	v_mfma_f32_16x16x32_bf16 v[86:89], v[150:153], v[182:185], v[86:89]
	v_mfma_f32_16x16x32_bf16 v[82:85], v[158:161], v[182:185], v[82:85]
	v_mfma_f32_16x16x32_bf16 v[70:73], v[150:153], v[214:217], v[70:73]
	v_mfma_f32_16x16x32_bf16 v[66:69], v[158:161], v[214:217], v[66:69]
	s_setprio 0
	s_barrier
	s_add_u32 vcc_lo, s44, 0xfff80080
	s_addc_u32 vcc_hi, s45, -1
	s_mov_b32 m0, s70
	s_nop 0
	global_load_lds_dwordx4 v190, vcc
	ds_read_b128 v[162:165], v222 offset:49152
	ds_read_b128 v[166:169], v222 offset:50176
	s_mov_b32 m0, s71
	s_add_i32 s44, s77, s53
	global_load_lds_dwordx4 v206, vcc
	ds_read_b128 v[170:173], v222 offset:51200
	ds_read_b128 v[174:177], v222 offset:52224
	s_add_u32 vcc_lo, s42, 0x80
	s_addc_u32 vcc_hi, s43, 0
	s_mov_b32 m0, s44
	s_nop 0
	global_load_lds_dwordx4 v192, vcc
	ds_read_b128 v[178:181], v222 offset:53248
	ds_read_b128 v[182:185], v222 offset:54272
	s_add_i32 m0, s44, 0x2000
	s_add_u32 s42, s42, 0x80080
	s_addc_u32 s43, s43, 0
	global_load_lds_dwordx4 v208, vcc
	ds_read_b128 v[186:189], v222 offset:55296
	ds_read_b128 v[214:217], v222 offset:56320
	s_add_i32 s44, s79, s53
	s_mov_b32 m0, s44
	s_nop 0
	global_load_lds_dwordx4 v192, s[42:43]
	s_add_i32 m0, s44, 0x2000
	s_nop 0
	global_load_lds_dwordx4 v208, s[42:43]
	s_waitcnt lgkmcnt(0)
	s_setprio 1
	v_mfma_f32_16x16x32_bf16 v[62:65], v[118:121], v[162:165], v[62:65]
	v_mfma_f32_16x16x32_bf16 v[58:61], v[130:133], v[162:165], v[58:61]
	v_mfma_f32_16x16x32_bf16 v[46:49], v[118:121], v[170:173], v[46:49]
	v_mfma_f32_16x16x32_bf16 v[42:45], v[130:133], v[170:173], v[42:45]
	s_waitcnt vmcnt(8)
	s_barrier
	v_mfma_f32_16x16x32_bf16 v[30:33], v[118:121], v[178:181], v[30:33]
	v_mfma_f32_16x16x32_bf16 v[26:29], v[130:133], v[178:181], v[26:29]
	v_mfma_f32_16x16x32_bf16 v[14:17], v[118:121], v[186:189], v[14:17]
	v_mfma_f32_16x16x32_bf16 v[10:13], v[130:133], v[186:189], v[10:13]
	v_mfma_f32_16x16x32_bf16 v[62:65], v[122:125], v[166:169], v[62:65]
	v_mfma_f32_16x16x32_bf16 v[58:61], v[134:137], v[166:169], v[58:61]
	v_mfma_f32_16x16x32_bf16 v[46:49], v[122:125], v[174:177], v[46:49]
	v_mfma_f32_16x16x32_bf16 v[42:45], v[134:137], v[174:177], v[42:45]
	v_mfma_f32_16x16x32_bf16 v[30:33], v[122:125], v[182:185], v[30:33]
	v_mfma_f32_16x16x32_bf16 v[26:29], v[134:137], v[182:185], v[26:29]
	v_mfma_f32_16x16x32_bf16 v[14:17], v[122:125], v[214:217], v[14:17]
	v_mfma_f32_16x16x32_bf16 v[10:13], v[134:137], v[214:217], v[10:13]
	s_setprio 0
	s_setprio 1
	v_mfma_f32_16x16x32_bf16 v[54:57], v[146:149], v[162:165], v[54:57]
	v_mfma_f32_16x16x32_bf16 v[50:53], v[154:157], v[162:165], v[50:53]
	v_mfma_f32_16x16x32_bf16 v[38:41], v[146:149], v[170:173], v[38:41]
	v_mfma_f32_16x16x32_bf16 v[34:37], v[154:157], v[170:173], v[34:37]
	v_mfma_f32_16x16x32_bf16 v[22:25], v[146:149], v[178:181], v[22:25]
	v_mfma_f32_16x16x32_bf16 v[18:21], v[154:157], v[178:181], v[18:21]
	v_mfma_f32_16x16x32_bf16 v[6:9], v[146:149], v[186:189], v[6:9]
	v_mfma_f32_16x16x32_bf16 v[2:5], v[154:157], v[186:189], v[2:5]
	v_mfma_f32_16x16x32_bf16 v[54:57], v[150:153], v[166:169], v[54:57]
	v_mfma_f32_16x16x32_bf16 v[50:53], v[158:161], v[166:169], v[50:53]
	v_mfma_f32_16x16x32_bf16 v[38:41], v[150:153], v[174:177], v[38:41]
	v_mfma_f32_16x16x32_bf16 v[34:37], v[158:161], v[174:177], v[34:37]
	v_mfma_f32_16x16x32_bf16 v[22:25], v[150:153], v[182:185], v[22:25]
	v_mfma_f32_16x16x32_bf16 v[18:21], v[158:161], v[182:185], v[18:21]
	v_mfma_f32_16x16x32_bf16 v[6:9], v[150:153], v[214:217], v[6:9]
	v_mfma_f32_16x16x32_bf16 v[2:5], v[158:161], v[214:217], v[2:5]
	s_setprio 0
	s_barrier
	s_add_i32 s76, s76, 2
	s_add_u32 s40, s40, 0x100
	s_addc_u32 s41, s41, 0
	s_add_u32 s74, s74, 0x100
	s_addc_u32 s75, s75, 0
	s_cmp_gt_u32 s76, 29
	s_cbranch_scc0 .LBB0_524

;     __host__ __device__ bool next(int i, Unit& u) const { const bool ok = StaticOrder::next(i, u); u.lm = 0; u.ln = 0; return ok; }
; #define PG8_STAGE(bufoff, gbase, voff) do { _Pragma("unroll") for (int _i = 0; _i < 2; ++_i) \
;         __builtin_amdgcn_global_load_lds((const unsigned*)((const char*)(gbase) + (voff)[_i]), (PG8_LAS unsigned*)(lds + (bufoff) + ldsw + _i * 8192), 16, 0, 0); } while (0)
; #define PG8_LDA(dst, b, h) do { _Pragma("unroll") for (int m = 0; m < 4; ++m) _Pragma("unroll") for (int k = 0; k < 2; ++k) dst[m][k] = *(const PG8_LAS bf16x8*)(lds + PG8_SA(b, h) + aoff + m * 2048 + k * 1024); } while (0)
; #define PG8_LDB(dst, b, h) do { _Pragma("unroll") for (int n = 0; n < 2; ++n) _Pragma("unroll") for (int k = 0; k < 2; ++k) dst[n][k] = *(const PG8_LAS bf16x8*)(lds + PG8_SB(b, h) + boff + n * 2048 + k * 1024); } while (0)
; #define PG8_WAIT_V(n) asm volatile("s_waitcnt vmcnt(" #n ")" ::: "memory")
; #define PG8_BAR __builtin_amdgcn_s_barrier()
; template <class Epi, class Sched, bool ALIGN_EPI = false, bool SP2 = false>
; __device__ __forceinline__ void gemm_phase(PG8_LAS unsigned char* lds, const Gemm g, const Sched& S, const Epi& E, const int wave_id) {
;     ...
;         const bool has_next = S.next(ui + 1, nxt);
;         const char* nA = has_next ? (const char*)g.A + (size_t)nxt.lm * tstep : cA; const char* nB = has_next ? (const char*)g.Bt + (size_t)nxt.ln * tstep : cB;
; #pragma unroll 1
;         for (int t = 0; t < nt; t += 2) {
;             const bool last = (t == nt - 2);
;             const char* a1 = cA + (size_t)(t + 1) * kstep;
;             const char* a2 = last ? nA : cA + (size_t)(t + 2) * kstep; const char* b2 = last ? nB : cB + (size_t)(t + 2) * kstep;
;             const char* a3 = a2 + kstep; const char* b3 = b2 + kstep;
;             if (last && has_next) S.a_ready(nxt);
;             if constexpr (SP2) {
;             PG8_LDB(B0, 0, 0); PG8_LDB(B1, 0, 1); PG8_SCHED; PG8_LDA(At, 0, 0); PG8_STAGE(PG8_SA(1, 1), a1 + hstep, voffA);
;             PG8_WAIT_V(8); PG8_WAIT_L(0); PG8_BAR; PG8_MMA(0, 0, At, B0); PG8_MMA(0, 1, At, B1); PG8_BAR; PG8_SCHED;
;             PG8_LDA(At, 0, 1); PG8_STAGE(PG8_SB(0, 0), b2, voffB); PG8_STAGE(PG8_SB(0, 1), b2 + hstep, voffB); PG8_STAGE(PG8_SA(0, 0), a2, voffA);
;             PG8_WAIT_V(8); PG8_WAIT_L(0); PG8_BAR; PG8_MMA(1, 0, At, B0); PG8_MMA(1, 1, At, B1); PG8_BAR; PG8_SCHED;
.LBB0_640:
	s_ashr_i32 s15, s14, 31
	s_lshl_b64 s[16:17], s[14:15], 20
	s_add_u32 s16, s47, s16
	s_addc_u32 s17, s48, s17
	s_and_b64 s[18:19], s[38:39], exec
	s_cselect_b32 s15, s17, s21
	s_cselect_b32 s71, s16, s20
	s_ashr_i32 s13, s12, 31
	s_lshl_b64 s[18:19], s[12:13], 20
	s_add_u32 s18, s49, s18
	s_addc_u32 s19, s52, s19
	s_and_b64 s[44:45], s[38:39], exec
	s_cselect_b32 s13, s19, s43
	s_cselect_b32 s72, s18, s42
	s_add_u32 s20, s20, 0x80080
	s_addc_u32 s21, s21, 0
	s_add_u32 s73, s42, 0x100
	s_addc_u32 s74, s43, 0
	s_mov_b32 s75, -2
	v_add_u32_e32 v144, 0x10000, v147
	s_add_u32 s42, s20, 0xfff80080
	s_addc_u32 s43, s21, -1
	s_add_i32 s76, 0, 0x10000
	s_cmp_eq_u32 s75, 28
	s_cselect_b32 s45, s15, s43
	s_cselect_b32 s44, s71, s42
	s_cselect_b32 s43, s13, s74
	s_cselect_b32 s42, s72, s73
	s_add_i32 s79, 0, 0x14000
	s_add_i32 m0, s53, 0xc000
	s_nop 0
	global_load_lds_dwordx4 v138, s[20:21]
	ds_read_b128 v[158:161], v144
	ds_read_b128 v[162:165], v144 offset:1024
	ds_read_b128 v[166:169], v144 offset:2048
	ds_read_b128 v[170:173], v144 offset:3072
	ds_read_b128 v[174:177], v144 offset:16384
	ds_read_b128 v[178:181], v144 offset:17408
	ds_read_b128 v[182:185], v144 offset:18432
	ds_read_b128 v[186:189], v144 offset:19456
	s_add_i32 m0, s53, 0xe000
	s_nop 0
	global_load_lds_dwordx4 v140, s[20:21]
	ds_read_b128 v[190:193], v155
	ds_read_b128 v[206:209], v155 offset:1024
	ds_read_b128 v[210:213], v155 offset:2048
	ds_read_b128 v[214:217], v155 offset:3072
	ds_read_b128 v[226:229], v155 offset:4096
	ds_read_b128 v[234:237], v155 offset:5120
	ds_read_b128 v[238:241], v155 offset:6144
	ds_read_b128 v[242:245], v155 offset:7168
	s_waitcnt lgkmcnt(0)
	s_setprio 1
	v_mfma_f32_16x16x32_bf16 v[126:129], v[158:161], v[190:193], 0
	v_mfma_f32_16x16x32_bf16 v[118:121], v[166:169], v[190:193], 0
	v_mfma_f32_16x16x32_bf16 v[110:113], v[158:161], v[210:213], 0
	v_mfma_f32_16x16x32_bf16 v[102:105], v[166:169], v[210:213], 0
	s_waitcnt vmcnt(8)
	s_barrier
	v_mfma_f32_16x16x32_bf16 v[94:97], v[158:161], v[226:229], 0
	v_mfma_f32_16x16x32_bf16 v[86:89], v[166:169], v[226:229], 0
	v_mfma_f32_16x16x32_bf16 v[78:81], v[158:161], v[238:241], 0
	v_mfma_f32_16x16x32_bf16 v[70:73], v[166:169], v[238:241], 0
	v_mfma_f32_16x16x32_bf16 v[126:129], v[162:165], v[206:209], v[126:129]
	v_mfma_f32_16x16x32_bf16 v[118:121], v[170:173], v[206:209], v[118:121]
	v_mfma_f32_16x16x32_bf16 v[110:113], v[162:165], v[214:217], v[110:113]
	v_mfma_f32_16x16x32_bf16 v[102:105], v[170:173], v[214:217], v[102:105]
	v_mfma_f32_16x16x32_bf16 v[94:97], v[162:165], v[234:237], v[94:97]
	v_mfma_f32_16x16x32_bf16 v[86:89], v[170:173], v[234:237], v[86:89]
	v_mfma_f32_16x16x32_bf16 v[78:81], v[162:165], v[242:245], v[78:81]
	v_mfma_f32_16x16x32_bf16 v[70:73], v[170:173], v[242:245], v[70:73]
	s_setprio 0
	s_setprio 1
	v_mfma_f32_16x16x32_bf16 v[122:125], v[174:177], v[190:193], 0
	v_mfma_f32_16x16x32_bf16 v[114:117], v[182:185], v[190:193], 0
	v_mfma_f32_16x16x32_bf16 v[106:109], v[174:177], v[210:213], 0
	v_mfma_f32_16x16x32_bf16 v[98:101], v[182:185], v[210:213], 0
	v_mfma_f32_16x16x32_bf16 v[90:93], v[174:177], v[226:229], 0
	v_mfma_f32_16x16x32_bf16 v[82:85], v[182:185], v[226:229], 0
	v_mfma_f32_16x16x32_bf16 v[74:77], v[174:177], v[238:241], 0
	v_mfma_f32_16x16x32_bf16 v[66:69], v[182:185], v[238:241], 0
	v_mfma_f32_16x16x32_bf16 v[122:125], v[178:181], v[206:209], v[122:125]
	v_mfma_f32_16x16x32_bf16 v[114:117], v[186:189], v[206:209], v[114:117]
	v_mfma_f32_16x16x32_bf16 v[106:109], v[178:181], v[214:217], v[106:109]
	v_mfma_f32_16x16x32_bf16 v[98:101], v[186:189], v[214:217], v[98:101]
	v_mfma_f32_16x16x32_bf16 v[90:93], v[178:181], v[234:237], v[90:93]
	v_mfma_f32_16x16x32_bf16 v[82:85], v[186:189], v[234:237], v[82:85]
	v_mfma_f32_16x16x32_bf16 v[74:77], v[178:181], v[242:245], v[74:77]
	v_mfma_f32_16x16x32_bf16 v[66:69], v[186:189], v[242:245], v[66:69]
	s_setprio 0
	s_barrier
	s_add_i32 s76, s76, s41
	s_mov_b32 m0, s76
	s_nop 0
	global_load_lds_dwordx4 v132, s[42:43]
	ds_read_b128 v[190:193], v155 offset:16384
	ds_read_b128 v[206:209], v155 offset:17408
	s_add_i32 m0, s76, 0x2000
	s_add_u32 s76, s42, 0x80000
	s_addc_u32 s77, s43, 0
	s_add_i32 s79, s79, s41
	global_load_lds_dwordx4 v136, s[42:43]
	ds_read_b128 v[210:213], v155 offset:18432
	ds_read_b128 v[214:217], v155 offset:19456
	s_mov_b32 m0, s79
	s_nop 0
	global_load_lds_dwordx4 v132, s[76:77]
	ds_read_b128 v[226:229], v155 offset:20480
	ds_read_b128 v[234:237], v155 offset:21504
	s_add_i32 m0, s79, 0x2000
	s_nop 0
	global_load_lds_dwordx4 v136, s[76:77]
	ds_read_b128 v[238:241], v155 offset:22528
	ds_read_b128 v[242:245], v155 offset:23552
	s_mov_b32 m0, s53
	s_nop 0
	global_load_lds_dwordx4 v130, s[44:45]
	s_mov_b32 m0, s56
	s_nop 0
	global_load_lds_dwordx4 v134, s[44:45]
	s_waitcnt lgkmcnt(0)
	s_setprio 1
	v_mfma_f32_16x16x32_bf16 v[62:65], v[158:161], v[190:193], 0
	v_mfma_f32_16x16x32_bf16 v[54:57], v[166:169], v[190:193], 0
	v_mfma_f32_16x16x32_bf16 v[46:49], v[158:161], v[210:213], 0
	v_mfma_f32_16x16x32_bf16 v[38:41], v[166:169], v[210:213], 0
	s_waitcnt vmcnt(8)
	s_barrier
; #define PG8_STAGE(bufoff, gbase, voff) do { _Pragma("unroll") for (int _i = 0; _i < 2; ++_i) \
;         __builtin_amdgcn_global_load_lds((const unsigned*)((const char*)(gbase) + (voff)[_i]), (PG8_LAS unsigned*)(lds + (bufoff) + ldsw + _i * 8192), 16, 0, 0); } while (0)
; #define PG8_LDA(dst, b, h) do { _Pragma("unroll") for (int m = 0; m < 4; ++m) _Pragma("unroll") for (int k = 0; k < 2; ++k) dst[m][k] = *(const PG8_LAS bf16x8*)(lds + PG8_SA(b, h) + aoff + m * 2048 + k * 1024); } while (0)
; #define PG8_LDB(dst, b, h) do { _Pragma("unroll") for (int n = 0; n < 2; ++n) _Pragma("unroll") for (int k = 0; k < 2; ++k) dst[n][k] = *(const PG8_LAS bf16x8*)(lds + PG8_SB(b, h) + boff + n * 2048 + k * 1024); } while (0)
; #define PG8_MMA(ai, bj, At, Bt) do { __builtin_amdgcn_s_setprio(1); _Pragma("unroll") for (int m = 0; m < 4; ++m) _Pragma("unroll") for (int n = 0; n < 2; ++n) _Pragma("unroll") for (int k = 0; k < 2; ++k) \
;         acc[ai][bj][m][n] = __builtin_amdgcn_mfma_f32_16x16x32_bf16(Bt[n][k], At[m][k], acc[ai][bj][m][n], 0, 0, 0); __builtin_amdgcn_s_setprio(0); } while (0)
; #define PG8_WAIT_V(n) asm volatile("s_waitcnt vmcnt(" #n ")" ::: "memory")
; #define PG8_WAIT_L(n) asm volatile("s_waitcnt lgkmcnt(" #n ")" ::: "memory")
; #define PG8_BAR __builtin_amdgcn_s_barrier()
; #define PG8_SCHED __builtin_amdgcn_sched_barrier(0)
; template <class Epi, class Sched, bool ALIGN_EPI = false, bool SP2 = false>
; __device__ __forceinline__ void gemm_phase(PG8_LAS unsigned char* lds, const Gemm g, const Sched& S, const Epi& E, const int wave_id) {
;     ...
;             PG8_WAIT_V(8); PG8_WAIT_L(0); PG8_BAR; PG8_MMA(0, 0, At, B0); PG8_MMA(0, 1, At, B1); PG8_BAR; PG8_SCHED;
;             PG8_LDA(At, 0, 1); PG8_STAGE(PG8_SB(0, 0), b2, voffB); PG8_STAGE(PG8_SB(0, 1), b2 + hstep, voffB); PG8_STAGE(PG8_SA(0, 0), a2, voffA);
;             PG8_WAIT_V(8); PG8_WAIT_L(0); PG8_BAR; PG8_MMA(1, 0, At, B0); PG8_MMA(1, 1, At, B1); PG8_BAR; PG8_SCHED;
;             PG8_LDB(B0, 1, 0); PG8_LDB(B1, 1, 1); PG8_SCHED; PG8_LDA(At, 1, 0); PG8_STAGE(PG8_SA(0, 1), a2 + hstep, voffA);
;             PG8_WAIT_V(8); PG8_WAIT_L(0); PG8_BAR; PG8_MMA(0, 0, At, B0); PG8_MMA(0, 1, At, B1); PG8_BAR; PG8_SCHED;
	v_mfma_f32_16x16x32_bf16 v[30:33], v[158:161], v[226:229], 0
	v_mfma_f32_16x16x32_bf16 v[22:25], v[166:169], v[226:229], 0
	v_mfma_f32_16x16x32_bf16 v[14:17], v[158:161], v[238:241], 0
	v_mfma_f32_16x16x32_bf16 v[6:9], v[166:169], v[238:241], 0
	v_mfma_f32_16x16x32_bf16 v[62:65], v[162:165], v[206:209], v[62:65]
	v_mfma_f32_16x16x32_bf16 v[54:57], v[170:173], v[206:209], v[54:57]
	v_mfma_f32_16x16x32_bf16 v[46:49], v[162:165], v[214:217], v[46:49]
	v_mfma_f32_16x16x32_bf16 v[38:41], v[170:173], v[214:217], v[38:41]
	v_mfma_f32_16x16x32_bf16 v[30:33], v[162:165], v[234:237], v[30:33]
	v_mfma_f32_16x16x32_bf16 v[22:25], v[170:173], v[234:237], v[22:25]
	v_mfma_f32_16x16x32_bf16 v[14:17], v[162:165], v[242:245], v[14:17]
	v_mfma_f32_16x16x32_bf16 v[6:9], v[170:173], v[242:245], v[6:9]
	s_setprio 0
	s_setprio 1
	v_mfma_f32_16x16x32_bf16 v[58:61], v[174:177], v[190:193], 0
	v_mfma_f32_16x16x32_bf16 v[50:53], v[182:185], v[190:193], 0
	v_mfma_f32_16x16x32_bf16 v[42:45], v[174:177], v[210:213], 0
	v_mfma_f32_16x16x32_bf16 v[34:37], v[182:185], v[210:213], 0
	v_mfma_f32_16x16x32_bf16 v[26:29], v[174:177], v[226:229], 0
	v_mfma_f32_16x16x32_bf16 v[18:21], v[182:185], v[226:229], 0
	v_mfma_f32_16x16x32_bf16 v[10:13], v[174:177], v[238:241], 0
	v_mfma_f32_16x16x32_bf16 v[2:5], v[182:185], v[238:241], 0
	v_mfma_f32_16x16x32_bf16 v[58:61], v[178:181], v[206:209], v[58:61]
	v_mfma_f32_16x16x32_bf16 v[50:53], v[186:189], v[206:209], v[50:53]
	v_mfma_f32_16x16x32_bf16 v[42:45], v[178:181], v[214:217], v[42:45]
	v_mfma_f32_16x16x32_bf16 v[34:37], v[186:189], v[214:217], v[34:37]
	v_mfma_f32_16x16x32_bf16 v[26:29], v[178:181], v[234:237], v[26:29]
	v_mfma_f32_16x16x32_bf16 v[18:21], v[186:189], v[234:237], v[18:21]
	v_mfma_f32_16x16x32_bf16 v[10:13], v[178:181], v[242:245], v[10:13]
	v_mfma_f32_16x16x32_bf16 v[2:5], v[186:189], v[242:245], v[2:5]
	s_setprio 0
	s_barrier
	s_add_i32 s76, 0, 0x18000
	s_add_i32 s77, 0, 0x1c000
	s_add_u32 s44, s44, 0x80000
	s_addc_u32 s45, s45, 0
	s_mov_b32 m0, s57
	s_nop 0
	global_load_lds_dwordx4 v130, s[44:45]
	ds_read_b128 v[158:161], v144 offset:32768
	ds_read_b128 v[162:165], v144 offset:33792
	ds_read_b128 v[166:169], v144 offset:34816
	ds_read_b128 v[170:173], v144 offset:35840
	ds_read_b128 v[174:177], v144 offset:49152
	ds_read_b128 v[178:181], v144 offset:50176
	ds_read_b128 v[182:185], v144 offset:51200
	ds_read_b128 v[186:189], v144 offset:52224
	s_mov_b32 m0, s64
	s_nop 0
	global_load_lds_dwordx4 v134, s[44:45]
	ds_read_b128 v[190:193], v155 offset:32768
	ds_read_b128 v[206:209], v155 offset:33792
	ds_read_b128 v[210:213], v155 offset:34816
	ds_read_b128 v[214:217], v155 offset:35840
	ds_read_b128 v[226:229], v155 offset:36864
	ds_read_b128 v[234:237], v155 offset:37888
	ds_read_b128 v[238:241], v155 offset:38912
	ds_read_b128 v[242:245], v155 offset:39936
	s_waitcnt lgkmcnt(0)
	s_setprio 1
	v_mfma_f32_16x16x32_bf16 v[126:129], v[158:161], v[190:193], v[126:129]
	v_mfma_f32_16x16x32_bf16 v[118:121], v[166:169], v[190:193], v[118:121]
	v_mfma_f32_16x16x32_bf16 v[110:113], v[158:161], v[210:213], v[110:113]
	v_mfma_f32_16x16x32_bf16 v[102:105], v[166:169], v[210:213], v[102:105]
	s_waitcnt vmcnt(8)
	s_barrier
	v_mfma_f32_16x16x32_bf16 v[94:97], v[158:161], v[226:229], v[94:97]
	v_mfma_f32_16x16x32_bf16 v[86:89], v[166:169], v[226:229], v[86:89]
	v_mfma_f32_16x16x32_bf16 v[78:81], v[158:161], v[238:241], v[78:81]
	v_mfma_f32_16x16x32_bf16 v[70:73], v[166:169], v[238:241], v[70:73]
	v_mfma_f32_16x16x32_bf16 v[126:129], v[162:165], v[206:209], v[126:129]
	v_mfma_f32_16x16x32_bf16 v[118:121], v[170:173], v[206:209], v[118:121]
	v_mfma_f32_16x16x32_bf16 v[110:113], v[162:165], v[214:217], v[110:113]
	v_mfma_f32_16x16x32_bf16 v[102:105], v[170:173], v[214:217], v[102:105]
	v_mfma_f32_16x16x32_bf16 v[94:97], v[162:165], v[234:237], v[94:97]
	v_mfma_f32_16x16x32_bf16 v[86:89], v[170:173], v[234:237], v[86:89]
	v_mfma_f32_16x16x32_bf16 v[78:81], v[162:165], v[242:245], v[78:81]
	v_mfma_f32_16x16x32_bf16 v[70:73], v[170:173], v[242:245], v[70:73]
	s_setprio 0
	s_setprio 1
	v_mfma_f32_16x16x32_bf16 v[122:125], v[174:177], v[190:193], v[122:125]
	v_mfma_f32_16x16x32_bf16 v[114:117], v[182:185], v[190:193], v[114:117]
	v_mfma_f32_16x16x32_bf16 v[106:109], v[174:177], v[210:213], v[106:109]
	v_mfma_f32_16x16x32_bf16 v[98:101], v[182:185], v[210:213], v[98:101]
	v_mfma_f32_16x16x32_bf16 v[90:93], v[174:177], v[226:229], v[90:93]
	v_mfma_f32_16x16x32_bf16 v[82:85], v[182:185], v[226:229], v[82:85]
	v_mfma_f32_16x16x32_bf16 v[74:77], v[174:177], v[238:241], v[74:77]
	v_mfma_f32_16x16x32_bf16 v[66:69], v[182:185], v[238:241], v[66:69]
	v_mfma_f32_16x16x32_bf16 v[122:125], v[178:181], v[206:209], v[122:125]
	v_mfma_f32_16x16x32_bf16 v[114:117], v[186:189], v[206:209], v[114:117]
	v_mfma_f32_16x16x32_bf16 v[106:109], v[178:181], v[214:217], v[106:109]
	v_mfma_f32_16x16x32_bf16 v[98:101], v[186:189], v[214:217], v[98:101]
	v_mfma_f32_16x16x32_bf16 v[90:93], v[178:181], v[234:237], v[90:93]
	v_mfma_f32_16x16x32_bf16 v[82:85], v[186:189], v[234:237], v[82:85]
	v_mfma_f32_16x16x32_bf16 v[74:77], v[178:181], v[242:245], v[74:77]
	v_mfma_f32_16x16x32_bf16 v[66:69], v[186:189], v[242:245], v[66:69]
	s_setprio 0
	s_barrier
; #define PG8_STAGE(bufoff, gbase, voff) do { _Pragma("unroll") for (int _i = 0; _i < 2; ++_i) \
;         __builtin_amdgcn_global_load_lds((const unsigned*)((const char*)(gbase) + (voff)[_i]), (PG8_LAS unsigned*)(lds + (bufoff) + ldsw + _i * 8192), 16, 0, 0); } while (0)
; #define PG8_LDA(dst, b, h) do { _Pragma("unroll") for (int m = 0; m < 4; ++m) _Pragma("unroll") for (int k = 0; k < 2; ++k) dst[m][k] = *(const PG8_LAS bf16x8*)(lds + PG8_SA(b, h) + aoff + m * 2048 + k * 1024); } while (0)
; #define PG8_WAIT_V(n) asm volatile("s_waitcnt vmcnt(" #n ")" ::: "memory")
; #define PG8_WAIT_L(n) asm volatile("s_waitcnt lgkmcnt(" #n ")" ::: "memory")
; #define PG8_BAR __builtin_amdgcn_s_barrier()
; template <class Epi, class Sched, bool ALIGN_EPI = false, bool SP2 = false>
; __device__ __forceinline__ void gemm_phase(PG8_LAS unsigned char* lds, const Gemm g, const Sched& S, const Epi& E, const int wave_id) {
;     ...
;         for (int t = 0; t < nt; t += 2) {
;             const bool last = (t == nt - 2);
;             const char* a1 = cA + (size_t)(t + 1) * kstep;
;             const char* a2 = last ? nA : cA + (size_t)(t + 2) * kstep; const char* b2 = last ? nB : cB + (size_t)(t + 2) * kstep;
;             const char* a3 = a2 + kstep; const char* b3 = b2 + kstep;
;             if (last && has_next) S.a_ready(nxt);
;             if constexpr (SP2) {
;             PG8_LDB(B0, 0, 0); PG8_LDB(B1, 0, 1); PG8_SCHED; PG8_LDA(At, 0, 0); PG8_STAGE(PG8_SA(1, 1), a1 + hstep, voffA);
;             PG8_WAIT_V(8); PG8_WAIT_L(0); PG8_BAR; PG8_MMA(0, 0, At, B0); PG8_MMA(0, 1, At, B1); PG8_BAR; PG8_SCHED;
;             PG8_LDA(At, 0, 1); PG8_STAGE(PG8_SB(0, 0), b2, voffB); PG8_STAGE(PG8_SB(0, 1), b2 + hstep, voffB); PG8_STAGE(PG8_SA(0, 0), a2, voffA);
;             PG8_WAIT_V(8); PG8_WAIT_L(0); PG8_BAR; PG8_MMA(1, 0, At, B0); PG8_MMA(1, 1, At, B1); PG8_BAR; PG8_SCHED;
;             PG8_LDB(B0, 1, 0); PG8_LDB(B1, 1, 1); PG8_SCHED; PG8_LDA(At, 1, 0); PG8_STAGE(PG8_SA(0, 1), a2 + hstep, voffA);
;             PG8_WAIT_V(8); PG8_WAIT_L(0); PG8_BAR; PG8_MMA(0, 0, At, B0); PG8_MMA(0, 1, At, B1); PG8_BAR; PG8_SCHED;
;             PG8_LDA(At, 1, 1); PG8_STAGE(PG8_SB(1, 0), b3, voffB); PG8_STAGE(PG8_SB(1, 1), b3 + hstep, voffB); PG8_STAGE(PG8_SA(1, 0), a3, voffA);
;             PG8_WAIT_V(8); PG8_WAIT_L(0); PG8_BAR; PG8_MMA(1, 0, At, B0); PG8_MMA(1, 1, At, B1); PG8_BAR; PG8_SCHED;
	s_add_u32 vcc_lo, s44, 0xfff80080
	s_addc_u32 vcc_hi, s45, -1
	s_mov_b32 m0, s65
	s_nop 0
	global_load_lds_dwordx4 v130, vcc
	ds_read_b128 v[190:193], v155 offset:49152
	ds_read_b128 v[206:209], v155 offset:50176
	s_mov_b32 m0, s68
	s_add_i32 s44, s76, s41
	global_load_lds_dwordx4 v134, vcc
	ds_read_b128 v[210:213], v155 offset:51200
	ds_read_b128 v[214:217], v155 offset:52224
	s_add_u32 vcc_lo, s42, 0x80
	s_addc_u32 vcc_hi, s43, 0
	s_mov_b32 m0, s44
	s_nop 0
	global_load_lds_dwordx4 v132, vcc
	ds_read_b128 v[226:229], v155 offset:53248
	ds_read_b128 v[234:237], v155 offset:54272
	s_add_i32 m0, s44, 0x2000
	s_add_u32 s42, s42, 0x80080
	s_addc_u32 s43, s43, 0
	global_load_lds_dwordx4 v136, vcc
	ds_read_b128 v[238:241], v155 offset:55296
	ds_read_b128 v[242:245], v155 offset:56320
	s_add_i32 s44, s77, s41
	s_mov_b32 m0, s44
	s_nop 0
	global_load_lds_dwordx4 v132, s[42:43]
	s_add_i32 m0, s44, 0x2000
	s_nop 0
	global_load_lds_dwordx4 v136, s[42:43]
	s_waitcnt lgkmcnt(0)
	s_setprio 1
	v_mfma_f32_16x16x32_bf16 v[62:65], v[158:161], v[190:193], v[62:65]
	v_mfma_f32_16x16x32_bf16 v[54:57], v[166:169], v[190:193], v[54:57]
	v_mfma_f32_16x16x32_bf16 v[46:49], v[158:161], v[210:213], v[46:49]
	v_mfma_f32_16x16x32_bf16 v[38:41], v[166:169], v[210:213], v[38:41]
	s_waitcnt vmcnt(8)
	s_barrier
	v_mfma_f32_16x16x32_bf16 v[30:33], v[158:161], v[226:229], v[30:33]
	v_mfma_f32_16x16x32_bf16 v[22:25], v[166:169], v[226:229], v[22:25]
	v_mfma_f32_16x16x32_bf16 v[14:17], v[158:161], v[238:241], v[14:17]
	v_mfma_f32_16x16x32_bf16 v[6:9], v[166:169], v[238:241], v[6:9]
	v_mfma_f32_16x16x32_bf16 v[62:65], v[162:165], v[206:209], v[62:65]
	v_mfma_f32_16x16x32_bf16 v[54:57], v[170:173], v[206:209], v[54:57]
	v_mfma_f32_16x16x32_bf16 v[46:49], v[162:165], v[214:217], v[46:49]
	v_mfma_f32_16x16x32_bf16 v[38:41], v[170:173], v[214:217], v[38:41]
	v_mfma_f32_16x16x32_bf16 v[30:33], v[162:165], v[234:237], v[30:33]
	v_mfma_f32_16x16x32_bf16 v[22:25], v[170:173], v[234:237], v[22:25]
	v_mfma_f32_16x16x32_bf16 v[14:17], v[162:165], v[242:245], v[14:17]
	v_mfma_f32_16x16x32_bf16 v[6:9], v[170:173], v[242:245], v[6:9]
	s_setprio 0
	s_setprio 1
	v_mfma_f32_16x16x32_bf16 v[58:61], v[174:177], v[190:193], v[58:61]
	v_mfma_f32_16x16x32_bf16 v[50:53], v[182:185], v[190:193], v[50:53]
	v_mfma_f32_16x16x32_bf16 v[42:45], v[174:177], v[210:213], v[42:45]
	v_mfma_f32_16x16x32_bf16 v[34:37], v[182:185], v[210:213], v[34:37]
	v_mfma_f32_16x16x32_bf16 v[26:29], v[174:177], v[226:229], v[26:29]
	v_mfma_f32_16x16x32_bf16 v[18:21], v[182:185], v[226:229], v[18:21]
	v_mfma_f32_16x16x32_bf16 v[10:13], v[174:177], v[238:241], v[10:13]
	v_mfma_f32_16x16x32_bf16 v[2:5], v[182:185], v[238:241], v[2:5]
	v_mfma_f32_16x16x32_bf16 v[58:61], v[178:181], v[206:209], v[58:61]
	v_mfma_f32_16x16x32_bf16 v[50:53], v[186:189], v[206:209], v[50:53]
	v_mfma_f32_16x16x32_bf16 v[42:45], v[178:181], v[214:217], v[42:45]
	v_mfma_f32_16x16x32_bf16 v[34:37], v[186:189], v[214:217], v[34:37]
	v_mfma_f32_16x16x32_bf16 v[26:29], v[178:181], v[234:237], v[26:29]
	v_mfma_f32_16x16x32_bf16 v[18:21], v[186:189], v[234:237], v[18:21]
	v_mfma_f32_16x16x32_bf16 v[10:13], v[178:181], v[242:245], v[10:13]
	v_mfma_f32_16x16x32_bf16 v[2:5], v[186:189], v[242:245], v[2:5]
	s_setprio 0
	s_barrier
	s_add_i32 s75, s75, 2
	s_add_u32 s20, s20, 0x100
	s_addc_u32 s21, s21, 0
	s_add_u32 s73, s73, 0x100
	s_addc_u32 s74, s74, 0
	s_cmp_gt_u32 s75, 29
	s_cbranch_scc1 .Lpeel_exit_g3
.LBB0_641:
	s_add_u32 s42, s20, 0xfff80080
	s_addc_u32 s43, s21, -1
	s_add_i32 s76, 0, 0x10000
	s_cmp_eq_u32 s75, 28
	s_cselect_b32 s45, s15, s43
	s_cselect_b32 s44, s71, s42
	s_cselect_b32 s43, s13, s74
	s_cselect_b32 s42, s72, s73
	s_add_i32 s79, 0, 0x14000
	s_add_i32 m0, s53, 0xc000
	s_nop 0
	global_load_lds_dwordx4 v138, s[20:21]
	ds_read_b128 v[158:161], v144
	ds_read_b128 v[162:165], v144 offset:1024
	ds_read_b128 v[166:169], v144 offset:2048
	ds_read_b128 v[170:173], v144 offset:3072
	ds_read_b128 v[174:177], v144 offset:16384
	ds_read_b128 v[178:181], v144 offset:17408
	ds_read_b128 v[182:185], v144 offset:18432
	ds_read_b128 v[186:189], v144 offset:19456
	s_add_i32 m0, s53, 0xe000
	s_nop 0
	global_load_lds_dwordx4 v140, s[20:21]
	ds_read_b128 v[190:193], v155
	ds_read_b128 v[206:209], v155 offset:1024
	ds_read_b128 v[210:213], v155 offset:2048
	ds_read_b128 v[214:217], v155 offset:3072
	ds_read_b128 v[226:229], v155 offset:4096
	ds_read_b128 v[234:237], v155 offset:5120
	ds_read_b128 v[238:241], v155 offset:6144
	ds_read_b128 v[242:245], v155 offset:7168
	s_waitcnt lgkmcnt(0)
	s_setprio 1
	v_mfma_f32_16x16x32_bf16 v[126:129], v[158:161], v[190:193], v[126:129]
	v_mfma_f32_16x16x32_bf16 v[118:121], v[166:169], v[190:193], v[118:121]
	v_mfma_f32_16x16x32_bf16 v[110:113], v[158:161], v[210:213], v[110:113]
	v_mfma_f32_16x16x32_bf16 v[102:105], v[166:169], v[210:213], v[102:105]
	s_waitcnt vmcnt(8)
	s_barrier
; #define PG8_STAGE(bufoff, gbase, voff) do { _Pragma("unroll") for (int _i = 0; _i < 2; ++_i) \
;         __builtin_amdgcn_global_load_lds((const unsigned*)((const char*)(gbase) + (voff)[_i]), (PG8_LAS unsigned*)(lds + (bufoff) + ldsw + _i * 8192), 16, 0, 0); } while (0)
; #define PG8_LDA(dst, b, h) do { _Pragma("unroll") for (int m = 0; m < 4; ++m) _Pragma("unroll") for (int k = 0; k < 2; ++k) dst[m][k] = *(const PG8_LAS bf16x8*)(lds + PG8_SA(b, h) + aoff + m * 2048 + k * 1024); } while (0)
; #define PG8_LDB(dst, b, h) do { _Pragma("unroll") for (int n = 0; n < 2; ++n) _Pragma("unroll") for (int k = 0; k < 2; ++k) dst[n][k] = *(const PG8_LAS bf16x8*)(lds + PG8_SB(b, h) + boff + n * 2048 + k * 1024); } while (0)
; #define PG8_MMA(ai, bj, At, Bt) do { __builtin_amdgcn_s_setprio(1); _Pragma("unroll") for (int m = 0; m < 4; ++m) _Pragma("unroll") for (int n = 0; n < 2; ++n) _Pragma("unroll") for (int k = 0; k < 2; ++k) \
;         acc[ai][bj][m][n] = __builtin_amdgcn_mfma_f32_16x16x32_bf16(Bt[n][k], At[m][k], acc[ai][bj][m][n], 0, 0, 0); __builtin_amdgcn_s_setprio(0); } while (0)
; #define PG8_WAIT_V(n) asm volatile("s_waitcnt vmcnt(" #n ")" ::: "memory")
; #define PG8_WAIT_L(n) asm volatile("s_waitcnt lgkmcnt(" #n ")" ::: "memory")
; #define PG8_BAR __builtin_amdgcn_s_barrier()
; #define PG8_SCHED __builtin_amdgcn_sched_barrier(0)
; template <class Epi, class Sched, bool ALIGN_EPI = false, bool SP2 = false>
; __device__ __forceinline__ void gemm_phase(PG8_LAS unsigned char* lds, const Gemm g, const Sched& S, const Epi& E, const int wave_id) {
;     ...
;             PG8_LDB(B0, 0, 0); PG8_LDB(B1, 0, 1); PG8_SCHED; PG8_LDA(At, 0, 0); PG8_STAGE(PG8_SA(1, 1), a1 + hstep, voffA);
;             PG8_WAIT_V(8); PG8_WAIT_L(0); PG8_BAR; PG8_MMA(0, 0, At, B0); PG8_MMA(0, 1, At, B1); PG8_BAR; PG8_SCHED;
;             PG8_LDA(At, 0, 1); PG8_STAGE(PG8_SB(0, 0), b2, voffB); PG8_STAGE(PG8_SB(0, 1), b2 + hstep, voffB); PG8_STAGE(PG8_SA(0, 0), a2, voffA);
;             PG8_WAIT_V(8); PG8_WAIT_L(0); PG8_BAR; PG8_MMA(1, 0, At, B0); PG8_MMA(1, 1, At, B1); PG8_BAR; PG8_SCHED;
	v_mfma_f32_16x16x32_bf16 v[94:97], v[158:161], v[226:229], v[94:97]
	v_mfma_f32_16x16x32_bf16 v[86:89], v[166:169], v[226:229], v[86:89]
	v_mfma_f32_16x16x32_bf16 v[78:81], v[158:161], v[238:241], v[78:81]
	v_mfma_f32_16x16x32_bf16 v[70:73], v[166:169], v[238:241], v[70:73]
	v_mfma_f32_16x16x32_bf16 v[126:129], v[162:165], v[206:209], v[126:129]
	v_mfma_f32_16x16x32_bf16 v[118:121], v[170:173], v[206:209], v[118:121]
	v_mfma_f32_16x16x32_bf16 v[110:113], v[162:165], v[214:217], v[110:113]
	v_mfma_f32_16x16x32_bf16 v[102:105], v[170:173], v[214:217], v[102:105]
	v_mfma_f32_16x16x32_bf16 v[94:97], v[162:165], v[234:237], v[94:97]
	v_mfma_f32_16x16x32_bf16 v[86:89], v[170:173], v[234:237], v[86:89]
	v_mfma_f32_16x16x32_bf16 v[78:81], v[162:165], v[242:245], v[78:81]
	v_mfma_f32_16x16x32_bf16 v[70:73], v[170:173], v[242:245], v[70:73]
	s_setprio 0
	s_setprio 1
	v_mfma_f32_16x16x32_bf16 v[122:125], v[174:177], v[190:193], v[122:125]
	v_mfma_f32_16x16x32_bf16 v[114:117], v[182:185], v[190:193], v[114:117]
	v_mfma_f32_16x16x32_bf16 v[106:109], v[174:177], v[210:213], v[106:109]
	v_mfma_f32_16x16x32_bf16 v[98:101], v[182:185], v[210:213], v[98:101]
	v_mfma_f32_16x16x32_bf16 v[90:93], v[174:177], v[226:229], v[90:93]
	v_mfma_f32_16x16x32_bf16 v[82:85], v[182:185], v[226:229], v[82:85]
	v_mfma_f32_16x16x32_bf16 v[74:77], v[174:177], v[238:241], v[74:77]
	v_mfma_f32_16x16x32_bf16 v[66:69], v[182:185], v[238:241], v[66:69]
	v_mfma_f32_16x16x32_bf16 v[122:125], v[178:181], v[206:209], v[122:125]
	v_mfma_f32_16x16x32_bf16 v[114:117], v[186:189], v[206:209], v[114:117]
	v_mfma_f32_16x16x32_bf16 v[106:109], v[178:181], v[214:217], v[106:109]
	v_mfma_f32_16x16x32_bf16 v[98:101], v[186:189], v[214:217], v[98:101]
	v_mfma_f32_16x16x32_bf16 v[90:93], v[178:181], v[234:237], v[90:93]
	v_mfma_f32_16x16x32_bf16 v[82:85], v[186:189], v[234:237], v[82:85]
	v_mfma_f32_16x16x32_bf16 v[74:77], v[178:181], v[242:245], v[74:77]
	v_mfma_f32_16x16x32_bf16 v[66:69], v[186:189], v[242:245], v[66:69]
	s_setprio 0
	s_barrier
	s_add_i32 s76, s76, s41
	s_mov_b32 m0, s76
	s_nop 0
	global_load_lds_dwordx4 v132, s[42:43]
	ds_read_b128 v[190:193], v155 offset:16384
	ds_read_b128 v[206:209], v155 offset:17408
	s_add_i32 m0, s76, 0x2000
	s_add_u32 s76, s42, 0x80000
	s_addc_u32 s77, s43, 0
	s_add_i32 s79, s79, s41
	global_load_lds_dwordx4 v136, s[42:43]
	ds_read_b128 v[210:213], v155 offset:18432
	ds_read_b128 v[214:217], v155 offset:19456
	s_mov_b32 m0, s79
	s_nop 0
	global_load_lds_dwordx4 v132, s[76:77]
	ds_read_b128 v[226:229], v155 offset:20480
	ds_read_b128 v[234:237], v155 offset:21504
	s_add_i32 m0, s79, 0x2000
	s_nop 0
	global_load_lds_dwordx4 v136, s[76:77]
	ds_read_b128 v[238:241], v155 offset:22528
	ds_read_b128 v[242:245], v155 offset:23552
	s_mov_b32 m0, s53
	s_nop 0
	global_load_lds_dwordx4 v130, s[44:45]
	s_mov_b32 m0, s56
	s_nop 0
	global_load_lds_dwordx4 v134, s[44:45]
	s_waitcnt lgkmcnt(0)
	s_setprio 1
	v_mfma_f32_16x16x32_bf16 v[62:65], v[158:161], v[190:193], v[62:65]
	v_mfma_f32_16x16x32_bf16 v[54:57], v[166:169], v[190:193], v[54:57]
	v_mfma_f32_16x16x32_bf16 v[46:49], v[158:161], v[210:213], v[46:49]
	v_mfma_f32_16x16x32_bf16 v[38:41], v[166:169], v[210:213], v[38:41]
	s_waitcnt vmcnt(8)
	s_barrier
	v_mfma_f32_16x16x32_bf16 v[30:33], v[158:161], v[226:229], v[30:33]
	v_mfma_f32_16x16x32_bf16 v[22:25], v[166:169], v[226:229], v[22:25]
	v_mfma_f32_16x16x32_bf16 v[14:17], v[158:161], v[238:241], v[14:17]
	v_mfma_f32_16x16x32_bf16 v[6:9], v[166:169], v[238:241], v[6:9]
	v_mfma_f32_16x16x32_bf16 v[62:65], v[162:165], v[206:209], v[62:65]
	v_mfma_f32_16x16x32_bf16 v[54:57], v[170:173], v[206:209], v[54:57]
	v_mfma_f32_16x16x32_bf16 v[46:49], v[162:165], v[214:217], v[46:49]
	v_mfma_f32_16x16x32_bf16 v[38:41], v[170:173], v[214:217], v[38:41]
	v_mfma_f32_16x16x32_bf16 v[30:33], v[162:165], v[234:237], v[30:33]
	v_mfma_f32_16x16x32_bf16 v[22:25], v[170:173], v[234:237], v[22:25]
	v_mfma_f32_16x16x32_bf16 v[14:17], v[162:165], v[242:245], v[14:17]
	v_mfma_f32_16x16x32_bf16 v[6:9], v[170:173], v[242:245], v[6:9]
	s_setprio 0
	s_setprio 1
	v_mfma_f32_16x16x32_bf16 v[58:61], v[174:177], v[190:193], v[58:61]
	v_mfma_f32_16x16x32_bf16 v[50:53], v[182:185], v[190:193], v[50:53]
	v_mfma_f32_16x16x32_bf16 v[42:45], v[174:177], v[210:213], v[42:45]
	v_mfma_f32_16x16x32_bf16 v[34:37], v[182:185], v[210:213], v[34:37]
	v_mfma_f32_16x16x32_bf16 v[26:29], v[174:177], v[226:229], v[26:29]
	v_mfma_f32_16x16x32_bf16 v[18:21], v[182:185], v[226:229], v[18:21]
	v_mfma_f32_16x16x32_bf16 v[10:13], v[174:177], v[238:241], v[10:13]
	v_mfma_f32_16x16x32_bf16 v[2:5], v[182:185], v[238:241], v[2:5]
	v_mfma_f32_16x16x32_bf16 v[58:61], v[178:181], v[206:209], v[58:61]
	v_mfma_f32_16x16x32_bf16 v[50:53], v[186:189], v[206:209], v[50:53]
	v_mfma_f32_16x16x32_bf16 v[42:45], v[178:181], v[214:217], v[42:45]
	v_mfma_f32_16x16x32_bf16 v[34:37], v[186:189], v[214:217], v[34:37]
	v_mfma_f32_16x16x32_bf16 v[26:29], v[178:181], v[234:237], v[26:29]
	v_mfma_f32_16x16x32_bf16 v[18:21], v[186:189], v[234:237], v[18:21]
	v_mfma_f32_16x16x32_bf16 v[10:13], v[178:181], v[242:245], v[10:13]
	v_mfma_f32_16x16x32_bf16 v[2:5], v[186:189], v[242:245], v[2:5]
	s_setprio 0
	s_barrier
; #define PG8_STAGE(bufoff, gbase, voff) do { _Pragma("unroll") for (int _i = 0; _i < 2; ++_i) \
;         __builtin_amdgcn_global_load_lds((const unsigned*)((const char*)(gbase) + (voff)[_i]), (PG8_LAS unsigned*)(lds + (bufoff) + ldsw + _i * 8192), 16, 0, 0); } while (0)
; #define PG8_LDA(dst, b, h) do { _Pragma("unroll") for (int m = 0; m < 4; ++m) _Pragma("unroll") for (int k = 0; k < 2; ++k) dst[m][k] = *(const PG8_LAS bf16x8*)(lds + PG8_SA(b, h) + aoff + m * 2048 + k * 1024); } while (0)
; #define PG8_WAIT_V(n) asm volatile("s_waitcnt vmcnt(" #n ")" ::: "memory")
; #define PG8_WAIT_L(n) asm volatile("s_waitcnt lgkmcnt(" #n ")" ::: "memory")
; #define PG8_BAR __builtin_amdgcn_s_barrier()
; template <class Epi, class Sched, bool ALIGN_EPI = false, bool SP2 = false>
; __device__ __forceinline__ void gemm_phase(PG8_LAS unsigned char* lds, const Gemm g, const Sched& S, const Epi& E, const int wave_id) {
;     ...
;         for (int t = 0; t < nt; t += 2) {
;             const bool last = (t == nt - 2);
;             const char* a1 = cA + (size_t)(t + 1) * kstep;
;             const char* a2 = last ? nA : cA + (size_t)(t + 2) * kstep; const char* b2 = last ? nB : cB + (size_t)(t + 2) * kstep;
;             const char* a3 = a2 + kstep; const char* b3 = b2 + kstep;
;             if (last && has_next) S.a_ready(nxt);
;             if constexpr (SP2) {
;             PG8_LDB(B0, 0, 0); PG8_LDB(B1, 0, 1); PG8_SCHED; PG8_LDA(At, 0, 0); PG8_STAGE(PG8_SA(1, 1), a1 + hstep, voffA);
;             PG8_WAIT_V(8); PG8_WAIT_L(0); PG8_BAR; PG8_MMA(0, 0, At, B0); PG8_MMA(0, 1, At, B1); PG8_BAR; PG8_SCHED;
;             PG8_LDA(At, 0, 1); PG8_STAGE(PG8_SB(0, 0), b2, voffB); PG8_STAGE(PG8_SB(0, 1), b2 + hstep, voffB); PG8_STAGE(PG8_SA(0, 0), a2, voffA);
;             PG8_WAIT_V(8); PG8_WAIT_L(0); PG8_BAR; PG8_MMA(1, 0, At, B0); PG8_MMA(1, 1, At, B1); PG8_BAR; PG8_SCHED;
;             PG8_LDB(B0, 1, 0); PG8_LDB(B1, 1, 1); PG8_SCHED; PG8_LDA(At, 1, 0); PG8_STAGE(PG8_SA(0, 1), a2 + hstep, voffA);
;             PG8_WAIT_V(8); PG8_WAIT_L(0); PG8_BAR; PG8_MMA(0, 0, At, B0); PG8_MMA(0, 1, At, B1); PG8_BAR; PG8_SCHED;
;             PG8_LDA(At, 1, 1); PG8_STAGE(PG8_SB(1, 0), b3, voffB); PG8_STAGE(PG8_SB(1, 1), b3 + hstep, voffB); PG8_STAGE(PG8_SA(1, 0), a3, voffA);
;             PG8_WAIT_V(8); PG8_WAIT_L(0); PG8_BAR; PG8_MMA(1, 0, At, B0); PG8_MMA(1, 1, At, B1); PG8_BAR; PG8_SCHED;
	s_add_i32 s76, 0, 0x18000
	s_add_i32 s77, 0, 0x1c000
	s_add_u32 s44, s44, 0x80000
	s_addc_u32 s45, s45, 0
	s_mov_b32 m0, s57
	s_nop 0
	global_load_lds_dwordx4 v130, s[44:45]
	ds_read_b128 v[158:161], v144 offset:32768
	ds_read_b128 v[162:165], v144 offset:33792
	ds_read_b128 v[166:169], v144 offset:34816
	ds_read_b128 v[170:173], v144 offset:35840
	ds_read_b128 v[174:177], v144 offset:49152
	ds_read_b128 v[178:181], v144 offset:50176
	ds_read_b128 v[182:185], v144 offset:51200
	ds_read_b128 v[186:189], v144 offset:52224
	s_mov_b32 m0, s64
	s_nop 0
	global_load_lds_dwordx4 v134, s[44:45]
	ds_read_b128 v[190:193], v155 offset:32768
	ds_read_b128 v[206:209], v155 offset:33792
	ds_read_b128 v[210:213], v155 offset:34816
	ds_read_b128 v[214:217], v155 offset:35840
	ds_read_b128 v[226:229], v155 offset:36864
	ds_read_b128 v[234:237], v155 offset:37888
	ds_read_b128 v[238:241], v155 offset:38912
	ds_read_b128 v[242:245], v155 offset:39936
	s_waitcnt lgkmcnt(0)
	s_setprio 1
	v_mfma_f32_16x16x32_bf16 v[126:129], v[158:161], v[190:193], v[126:129]
	v_mfma_f32_16x16x32_bf16 v[118:121], v[166:169], v[190:193], v[118:121]
	v_mfma_f32_16x16x32_bf16 v[110:113], v[158:161], v[210:213], v[110:113]
	v_mfma_f32_16x16x32_bf16 v[102:105], v[166:169], v[210:213], v[102:105]
	s_waitcnt vmcnt(8)
	s_barrier
	v_mfma_f32_16x16x32_bf16 v[94:97], v[158:161], v[226:229], v[94:97]
	v_mfma_f32_16x16x32_bf16 v[86:89], v[166:169], v[226:229], v[86:89]
	v_mfma_f32_16x16x32_bf16 v[78:81], v[158:161], v[238:241], v[78:81]
	v_mfma_f32_16x16x32_bf16 v[70:73], v[166:169], v[238:241], v[70:73]
	v_mfma_f32_16x16x32_bf16 v[126:129], v[162:165], v[206:209], v[126:129]
	v_mfma_f32_16x16x32_bf16 v[118:121], v[170:173], v[206:209], v[118:121]
	v_mfma_f32_16x16x32_bf16 v[110:113], v[162:165], v[214:217], v[110:113]
	v_mfma_f32_16x16x32_bf16 v[102:105], v[170:173], v[214:217], v[102:105]
	v_mfma_f32_16x16x32_bf16 v[94:97], v[162:165], v[234:237], v[94:97]
	v_mfma_f32_16x16x32_bf16 v[86:89], v[170:173], v[234:237], v[86:89]
	v_mfma_f32_16x16x32_bf16 v[78:81], v[162:165], v[242:245], v[78:81]
	v_mfma_f32_16x16x32_bf16 v[70:73], v[170:173], v[242:245], v[70:73]
	s_setprio 0
	s_setprio 1
	v_mfma_f32_16x16x32_bf16 v[122:125], v[174:177], v[190:193], v[122:125]
	v_mfma_f32_16x16x32_bf16 v[114:117], v[182:185], v[190:193], v[114:117]
	v_mfma_f32_16x16x32_bf16 v[106:109], v[174:177], v[210:213], v[106:109]
	v_mfma_f32_16x16x32_bf16 v[98:101], v[182:185], v[210:213], v[98:101]
	v_mfma_f32_16x16x32_bf16 v[90:93], v[174:177], v[226:229], v[90:93]
	v_mfma_f32_16x16x32_bf16 v[82:85], v[182:185], v[226:229], v[82:85]
	v_mfma_f32_16x16x32_bf16 v[74:77], v[174:177], v[238:241], v[74:77]
	v_mfma_f32_16x16x32_bf16 v[66:69], v[182:185], v[238:241], v[66:69]
	v_mfma_f32_16x16x32_bf16 v[122:125], v[178:181], v[206:209], v[122:125]
	v_mfma_f32_16x16x32_bf16 v[114:117], v[186:189], v[206:209], v[114:117]
	v_mfma_f32_16x16x32_bf16 v[106:109], v[178:181], v[214:217], v[106:109]
	v_mfma_f32_16x16x32_bf16 v[98:101], v[186:189], v[214:217], v[98:101]
	v_mfma_f32_16x16x32_bf16 v[90:93], v[178:181], v[234:237], v[90:93]
	v_mfma_f32_16x16x32_bf16 v[82:85], v[186:189], v[234:237], v[82:85]
	v_mfma_f32_16x16x32_bf16 v[74:77], v[178:181], v[242:245], v[74:77]
	v_mfma_f32_16x16x32_bf16 v[66:69], v[186:189], v[242:245], v[66:69]
	s_setprio 0
	s_barrier
	s_add_u32 vcc_lo, s44, 0xfff80080
	s_addc_u32 vcc_hi, s45, -1
	s_mov_b32 m0, s65
	s_nop 0
	global_load_lds_dwordx4 v130, vcc
	ds_read_b128 v[190:193], v155 offset:49152
	ds_read_b128 v[206:209], v155 offset:50176
	s_mov_b32 m0, s68
	s_add_i32 s44, s76, s41
	global_load_lds_dwordx4 v134, vcc
	ds_read_b128 v[210:213], v155 offset:51200
	ds_read_b128 v[214:217], v155 offset:52224
	s_add_u32 vcc_lo, s42, 0x80
	s_addc_u32 vcc_hi, s43, 0
	s_mov_b32 m0, s44
	s_nop 0
	global_load_lds_dwordx4 v132, vcc
	ds_read_b128 v[226:229], v155 offset:53248
	ds_read_b128 v[234:237], v155 offset:54272
	s_add_i32 m0, s44, 0x2000
	s_add_u32 s42, s42, 0x80080
	s_addc_u32 s43, s43, 0
	global_load_lds_dwordx4 v136, vcc
	ds_read_b128 v[238:241], v155 offset:55296
	ds_read_b128 v[242:245], v155 offset:56320
	s_add_i32 s44, s77, s41
	s_mov_b32 m0, s44
	s_nop 0
	global_load_lds_dwordx4 v132, s[42:43]
	s_add_i32 m0, s44, 0x2000
	s_nop 0
	global_load_lds_dwordx4 v136, s[42:43]
	s_waitcnt lgkmcnt(0)
	s_setprio 1
	v_mfma_f32_16x16x32_bf16 v[62:65], v[158:161], v[190:193], v[62:65]
	v_mfma_f32_16x16x32_bf16 v[54:57], v[166:169], v[190:193], v[54:57]
	v_mfma_f32_16x16x32_bf16 v[46:49], v[158:161], v[210:213], v[46:49]
	v_mfma_f32_16x16x32_bf16 v[38:41], v[166:169], v[210:213], v[38:41]
	s_waitcnt vmcnt(8)
	s_barrier
	v_mfma_f32_16x16x32_bf16 v[30:33], v[158:161], v[226:229], v[30:33]
	v_mfma_f32_16x16x32_bf16 v[22:25], v[166:169], v[226:229], v[22:25]
	v_mfma_f32_16x16x32_bf16 v[14:17], v[158:161], v[238:241], v[14:17]
	v_mfma_f32_16x16x32_bf16 v[6:9], v[166:169], v[238:241], v[6:9]
	v_mfma_f32_16x16x32_bf16 v[62:65], v[162:165], v[206:209], v[62:65]
	v_mfma_f32_16x16x32_bf16 v[54:57], v[170:173], v[206:209], v[54:57]
	v_mfma_f32_16x16x32_bf16 v[46:49], v[162:165], v[214:217], v[46:49]
	v_mfma_f32_16x16x32_bf16 v[38:41], v[170:173], v[214:217], v[38:41]
	v_mfma_f32_16x16x32_bf16 v[30:33], v[162:165], v[234:237], v[30:33]
	v_mfma_f32_16x16x32_bf16 v[22:25], v[170:173], v[234:237], v[22:25]
	v_mfma_f32_16x16x32_bf16 v[14:17], v[162:165], v[242:245], v[14:17]
	v_mfma_f32_16x16x32_bf16 v[6:9], v[170:173], v[242:245], v[6:9]
	s_setprio 0
	s_setprio 1
	v_mfma_f32_16x16x32_bf16 v[58:61], v[174:177], v[190:193], v[58:61]
	v_mfma_f32_16x16x32_bf16 v[50:53], v[182:185], v[190:193], v[50:53]
	v_mfma_f32_16x16x32_bf16 v[42:45], v[174:177], v[210:213], v[42:45]
	v_mfma_f32_16x16x32_bf16 v[34:37], v[182:185], v[210:213], v[34:37]
	v_mfma_f32_16x16x32_bf16 v[26:29], v[174:177], v[226:229], v[26:29]
	v_mfma_f32_16x16x32_bf16 v[18:21], v[182:185], v[226:229], v[18:21]
	v_mfma_f32_16x16x32_bf16 v[10:13], v[174:177], v[238:241], v[10:13]
	v_mfma_f32_16x16x32_bf16 v[2:5], v[182:185], v[238:241], v[2:5]
	v_mfma_f32_16x16x32_bf16 v[58:61], v[178:181], v[206:209], v[58:61]
	v_mfma_f32_16x16x32_bf16 v[50:53], v[186:189], v[206:209], v[50:53]
	v_mfma_f32_16x16x32_bf16 v[42:45], v[178:181], v[214:217], v[42:45]
	v_mfma_f32_16x16x32_bf16 v[34:37], v[186:189], v[214:217], v[34:37]
	v_mfma_f32_16x16x32_bf16 v[26:29], v[178:181], v[234:237], v[26:29]
	v_mfma_f32_16x16x32_bf16 v[18:21], v[186:189], v[234:237], v[18:21]
	v_mfma_f32_16x16x32_bf16 v[10:13], v[178:181], v[242:245], v[10:13]
	v_mfma_f32_16x16x32_bf16 v[2:5], v[186:189], v[242:245], v[2:5]
	s_setprio 0
	s_barrier
	s_add_i32 s75, s75, 2
	s_add_u32 s20, s20, 0x100
	s_addc_u32 s21, s21, 0
	s_add_u32 s73, s73, 0x100
	s_addc_u32 s74, s74, 0
	s_cmp_gt_u32 s75, 29
	s_cbranch_scc0 .LBB0_641

;     __host__ __device__ bool next(int i, Unit& u) const { const bool ok = StaticOrder::next(i, u); u.lm = 0; u.ln = 0; return ok; }
; #define PG8_STAGE(bufoff, gbase, voff) do { _Pragma("unroll") for (int _i = 0; _i < 2; ++_i) \
;         __builtin_amdgcn_global_load_lds((const unsigned*)((const char*)(gbase) + (voff)[_i]), (PG8_LAS unsigned*)(lds + (bufoff) + ldsw + _i * 8192), 16, 0, 0); } while (0)
; #define PG8_LDA(dst, b, h) do { _Pragma("unroll") for (int m = 0; m < 4; ++m) _Pragma("unroll") for (int k = 0; k < 2; ++k) dst[m][k] = *(const PG8_LAS bf16x8*)(lds + PG8_SA(b, h) + aoff + m * 2048 + k * 1024); } while (0)
; #define PG8_LDB(dst, b, h) do { _Pragma("unroll") for (int n = 0; n < 2; ++n) _Pragma("unroll") for (int k = 0; k < 2; ++k) dst[n][k] = *(const PG8_LAS bf16x8*)(lds + PG8_SB(b, h) + boff + n * 2048 + k * 1024); } while (0)
; #define PG8_WAIT_V(n) asm volatile("s_waitcnt vmcnt(" #n ")" ::: "memory")
; #define PG8_BAR __builtin_amdgcn_s_barrier()
; template <class Epi, class Sched, bool ALIGN_EPI = false, bool SP2 = false>
; __device__ __forceinline__ void gemm_phase(PG8_LAS unsigned char* lds, const Gemm g, const Sched& S, const Epi& E, const int wave_id) {
;     ...
;         const bool has_next = S.next(ui + 1, nxt);
;         const char* nA = has_next ? (const char*)g.A + (size_t)nxt.lm * tstep : cA; const char* nB = has_next ? (const char*)g.Bt + (size_t)nxt.ln * tstep : cB;
; #pragma unroll 1
;         for (int t = 0; t < nt; t += 2) {
;             const bool last = (t == nt - 2);
;             const char* a1 = cA + (size_t)(t + 1) * kstep;
;             const char* a2 = last ? nA : cA + (size_t)(t + 2) * kstep; const char* b2 = last ? nB : cB + (size_t)(t + 2) * kstep;
;             const char* a3 = a2 + kstep; const char* b3 = b2 + kstep;
;             if (last && has_next) S.a_ready(nxt);
;             if constexpr (SP2) {
;             PG8_LDB(B0, 0, 0); PG8_LDB(B1, 0, 1); PG8_SCHED; PG8_LDA(At, 0, 0); PG8_STAGE(PG8_SA(1, 1), a1 + hstep, voffA);
;             PG8_WAIT_V(8); PG8_WAIT_L(0); PG8_BAR; PG8_MMA(0, 0, At, B0); PG8_MMA(0, 1, At, B1); PG8_BAR; PG8_SCHED;
;             PG8_LDA(At, 0, 1); PG8_STAGE(PG8_SB(0, 0), b2, voffB); PG8_STAGE(PG8_SB(0, 1), b2 + hstep, voffB); PG8_STAGE(PG8_SA(0, 0), a2, voffA);
;             PG8_WAIT_V(8); PG8_WAIT_L(0); PG8_BAR; PG8_MMA(1, 0, At, B0); PG8_MMA(1, 1, At, B1); PG8_BAR; PG8_SCHED;
.LBB0_758:
	s_add_u32 s74, s20, 0x100
	s_addc_u32 s75, s21, 0
	s_mov_b32 s76, -2
	v_add_u32_e32 v226, 0x10000, v218
	s_add_u32 s20, s18, 0x100
	s_addc_u32 s21, s19, 0
	s_add_i32 s77, 0, 0x10000
	s_cmpk_eq_i32 s76, 0x54
	s_cselect_b32 s43, s15, s21
	s_cselect_b32 s42, s14, s20
	s_cselect_b32 s41, s17, s75
	s_cselect_b32 s40, s16, s74
	s_add_i32 s79, 0, 0x14000
	s_add_i32 m0, s52, 0xc000
	s_nop 0
	global_load_lds_dwordx4 v210, s[18:19]
	ds_read_b128 v[118:121], v226
	ds_read_b128 v[122:125], v226 offset:1024
	ds_read_b128 v[130:133], v226 offset:2048
	ds_read_b128 v[134:137], v226 offset:3072
	ds_read_b128 v[146:149], v226 offset:16384
	ds_read_b128 v[150:153], v226 offset:17408
	ds_read_b128 v[154:157], v226 offset:18432
	ds_read_b128 v[158:161], v226 offset:19456
	s_add_i32 m0, s52, 0xe000
	s_nop 0
	global_load_lds_dwordx4 v212, s[18:19]
	ds_read_b128 v[162:165], v222
	ds_read_b128 v[166:169], v222 offset:1024
	ds_read_b128 v[170:173], v222 offset:2048
	ds_read_b128 v[174:177], v222 offset:3072
	ds_read_b128 v[178:181], v222 offset:4096
	ds_read_b128 v[182:185], v222 offset:5120
	ds_read_b128 v[186:189], v222 offset:6144
	ds_read_b128 v[214:217], v222 offset:7168
	s_waitcnt lgkmcnt(0)
	s_setprio 1
	v_mfma_f32_16x16x32_bf16 v[142:145], v[118:121], v[162:165], 0
	v_mfma_f32_16x16x32_bf16 v[138:141], v[130:133], v[162:165], 0
	v_mfma_f32_16x16x32_bf16 v[110:113], v[118:121], v[170:173], 0
	v_mfma_f32_16x16x32_bf16 v[106:109], v[130:133], v[170:173], 0
	s_waitcnt vmcnt(8)
	s_barrier
	v_mfma_f32_16x16x32_bf16 v[94:97], v[118:121], v[178:181], 0
	v_mfma_f32_16x16x32_bf16 v[90:93], v[130:133], v[178:181], 0
	v_mfma_f32_16x16x32_bf16 v[78:81], v[118:121], v[186:189], 0
	v_mfma_f32_16x16x32_bf16 v[74:77], v[130:133], v[186:189], 0
	v_mfma_f32_16x16x32_bf16 v[142:145], v[122:125], v[166:169], v[142:145]
	v_mfma_f32_16x16x32_bf16 v[138:141], v[134:137], v[166:169], v[138:141]
	v_mfma_f32_16x16x32_bf16 v[110:113], v[122:125], v[174:177], v[110:113]
	v_mfma_f32_16x16x32_bf16 v[106:109], v[134:137], v[174:177], v[106:109]
	v_mfma_f32_16x16x32_bf16 v[94:97], v[122:125], v[182:185], v[94:97]
	v_mfma_f32_16x16x32_bf16 v[90:93], v[134:137], v[182:185], v[90:93]
	v_mfma_f32_16x16x32_bf16 v[78:81], v[122:125], v[214:217], v[78:81]
	v_mfma_f32_16x16x32_bf16 v[74:77], v[134:137], v[214:217], v[74:77]
	s_setprio 0
	s_setprio 1
	v_mfma_f32_16x16x32_bf16 v[126:129], v[146:149], v[162:165], 0
	v_mfma_f32_16x16x32_bf16 v[114:117], v[154:157], v[162:165], 0
	v_mfma_f32_16x16x32_bf16 v[102:105], v[146:149], v[170:173], 0
	v_mfma_f32_16x16x32_bf16 v[98:101], v[154:157], v[170:173], 0
	v_mfma_f32_16x16x32_bf16 v[86:89], v[146:149], v[178:181], 0
	v_mfma_f32_16x16x32_bf16 v[82:85], v[154:157], v[178:181], 0
	v_mfma_f32_16x16x32_bf16 v[70:73], v[146:149], v[186:189], 0
	v_mfma_f32_16x16x32_bf16 v[66:69], v[154:157], v[186:189], 0
	v_mfma_f32_16x16x32_bf16 v[126:129], v[150:153], v[166:169], v[126:129]
	v_mfma_f32_16x16x32_bf16 v[114:117], v[158:161], v[166:169], v[114:117]
	v_mfma_f32_16x16x32_bf16 v[102:105], v[150:153], v[174:177], v[102:105]
	v_mfma_f32_16x16x32_bf16 v[98:101], v[158:161], v[174:177], v[98:101]
	v_mfma_f32_16x16x32_bf16 v[86:89], v[150:153], v[182:185], v[86:89]
	v_mfma_f32_16x16x32_bf16 v[82:85], v[158:161], v[182:185], v[82:85]
	v_mfma_f32_16x16x32_bf16 v[70:73], v[150:153], v[214:217], v[70:73]
	v_mfma_f32_16x16x32_bf16 v[66:69], v[158:161], v[214:217], v[66:69]
	s_setprio 0
	s_barrier
	s_add_i32 s18, s77, s49
	s_mov_b32 m0, s18
	s_nop 0
	global_load_lds_dwordx4 v192, s[40:41]
	ds_read_b128 v[162:165], v222 offset:16384
	ds_read_b128 v[166:169], v222 offset:17408
	s_add_i32 m0, s18, 0x2000
	s_add_u32 s18, s40, 0x160000
	s_addc_u32 s19, s41, 0
	s_add_i32 s77, s79, s49
	global_load_lds_dwordx4 v208, s[40:41]
	ds_read_b128 v[170:173], v222 offset:18432
	ds_read_b128 v[174:177], v222 offset:19456
	s_mov_b32 m0, s77
	s_nop 0
	global_load_lds_dwordx4 v192, s[18:19]
	ds_read_b128 v[178:181], v222 offset:20480
	ds_read_b128 v[182:185], v222 offset:21504
	s_add_i32 m0, s77, 0x2000
	s_nop 0
	global_load_lds_dwordx4 v208, s[18:19]
	ds_read_b128 v[186:189], v222 offset:22528
	ds_read_b128 v[214:217], v222 offset:23552
	s_mov_b32 m0, s52
	s_nop 0
	global_load_lds_dwordx4 v190, s[42:43]
	s_mov_b32 m0, s53
	s_nop 0
	global_load_lds_dwordx4 v206, s[42:43]
	s_waitcnt lgkmcnt(0)
	s_setprio 1
	v_mfma_f32_16x16x32_bf16 v[62:65], v[118:121], v[162:165], 0
	v_mfma_f32_16x16x32_bf16 v[58:61], v[130:133], v[162:165], 0
	v_mfma_f32_16x16x32_bf16 v[46:49], v[118:121], v[170:173], 0
	v_mfma_f32_16x16x32_bf16 v[42:45], v[130:133], v[170:173], 0
	s_waitcnt vmcnt(8)
	s_barrier
	v_mfma_f32_16x16x32_bf16 v[30:33], v[118:121], v[178:181], 0
	v_mfma_f32_16x16x32_bf16 v[26:29], v[130:133], v[178:181], 0
	v_mfma_f32_16x16x32_bf16 v[14:17], v[118:121], v[186:189], 0
	v_mfma_f32_16x16x32_bf16 v[10:13], v[130:133], v[186:189], 0
	v_mfma_f32_16x16x32_bf16 v[62:65], v[122:125], v[166:169], v[62:65]
	v_mfma_f32_16x16x32_bf16 v[58:61], v[134:137], v[166:169], v[58:61]
	v_mfma_f32_16x16x32_bf16 v[46:49], v[122:125], v[174:177], v[46:49]
	v_mfma_f32_16x16x32_bf16 v[42:45], v[134:137], v[174:177], v[42:45]
	v_mfma_f32_16x16x32_bf16 v[30:33], v[122:125], v[182:185], v[30:33]
	v_mfma_f32_16x16x32_bf16 v[26:29], v[134:137], v[182:185], v[26:29]
	v_mfma_f32_16x16x32_bf16 v[14:17], v[122:125], v[214:217], v[14:17]
	v_mfma_f32_16x16x32_bf16 v[10:13], v[134:137], v[214:217], v[10:13]
	s_setprio 0
	s_setprio 1
	v_mfma_f32_16x16x32_bf16 v[54:57], v[146:149], v[162:165], 0
	v_mfma_f32_16x16x32_bf16 v[50:53], v[154:157], v[162:165], 0
	v_mfma_f32_16x16x32_bf16 v[38:41], v[146:149], v[170:173], 0
	v_mfma_f32_16x16x32_bf16 v[34:37], v[154:157], v[170:173], 0
	v_mfma_f32_16x16x32_bf16 v[22:25], v[146:149], v[178:181], 0
	v_mfma_f32_16x16x32_bf16 v[18:21], v[154:157], v[178:181], 0
	v_mfma_f32_16x16x32_bf16 v[6:9], v[146:149], v[186:189], 0
	v_mfma_f32_16x16x32_bf16 v[2:5], v[154:157], v[186:189], 0
	v_mfma_f32_16x16x32_bf16 v[54:57], v[150:153], v[166:169], v[54:57]
	v_mfma_f32_16x16x32_bf16 v[50:53], v[158:161], v[166:169], v[50:53]
	v_mfma_f32_16x16x32_bf16 v[38:41], v[150:153], v[174:177], v[38:41]
	v_mfma_f32_16x16x32_bf16 v[34:37], v[158:161], v[174:177], v[34:37]
	v_mfma_f32_16x16x32_bf16 v[22:25], v[150:153], v[182:185], v[22:25]
	v_mfma_f32_16x16x32_bf16 v[18:21], v[158:161], v[182:185], v[18:21]
	v_mfma_f32_16x16x32_bf16 v[6:9], v[150:153], v[214:217], v[6:9]
	v_mfma_f32_16x16x32_bf16 v[2:5], v[158:161], v[214:217], v[2:5]
	s_setprio 0
	s_barrier
; #define PG8_STAGE(bufoff, gbase, voff) do { _Pragma("unroll") for (int _i = 0; _i < 2; ++_i) \
;         __builtin_amdgcn_global_load_lds((const unsigned*)((const char*)(gbase) + (voff)[_i]), (PG8_LAS unsigned*)(lds + (bufoff) + ldsw + _i * 8192), 16, 0, 0); } while (0)
; #define PG8_LDA(dst, b, h) do { _Pragma("unroll") for (int m = 0; m < 4; ++m) _Pragma("unroll") for (int k = 0; k < 2; ++k) dst[m][k] = *(const PG8_LAS bf16x8*)(lds + PG8_SA(b, h) + aoff + m * 2048 + k * 1024); } while (0)
; #define PG8_LDB(dst, b, h) do { _Pragma("unroll") for (int n = 0; n < 2; ++n) _Pragma("unroll") for (int k = 0; k < 2; ++k) dst[n][k] = *(const PG8_LAS bf16x8*)(lds + PG8_SB(b, h) + boff + n * 2048 + k * 1024); } while (0)
; #define PG8_MMA(ai, bj, At, Bt) do { __builtin_amdgcn_s_setprio(1); _Pragma("unroll") for (int m = 0; m < 4; ++m) _Pragma("unroll") for (int n = 0; n < 2; ++n) _Pragma("unroll") for (int k = 0; k < 2; ++k) \
;         acc[ai][bj][m][n] = __builtin_amdgcn_mfma_f32_16x16x32_bf16(Bt[n][k], At[m][k], acc[ai][bj][m][n], 0, 0, 0); __builtin_amdgcn_s_setprio(0); } while (0)
; #define PG8_WAIT_V(n) asm volatile("s_waitcnt vmcnt(" #n ")" ::: "memory")
; #define PG8_WAIT_L(n) asm volatile("s_waitcnt lgkmcnt(" #n ")" ::: "memory")
; #define PG8_BAR __builtin_amdgcn_s_barrier()
; #define PG8_SCHED __builtin_amdgcn_sched_barrier(0)
; template <class Epi, class Sched, bool ALIGN_EPI = false, bool SP2 = false>
; __device__ __forceinline__ void gemm_phase(PG8_LAS unsigned char* lds, const Gemm g, const Sched& S, const Epi& E, const int wave_id) {
;     ...
;             PG8_LDA(At, 0, 1); PG8_STAGE(PG8_SB(0, 0), b2, voffB); PG8_STAGE(PG8_SB(0, 1), b2 + hstep, voffB); PG8_STAGE(PG8_SA(0, 0), a2, voffA);
;             PG8_WAIT_V(8); PG8_WAIT_L(0); PG8_BAR; PG8_MMA(1, 0, At, B0); PG8_MMA(1, 1, At, B1); PG8_BAR; PG8_SCHED;
;             PG8_LDB(B0, 1, 0); PG8_LDB(B1, 1, 1); PG8_SCHED; PG8_LDA(At, 1, 0); PG8_STAGE(PG8_SA(0, 1), a2 + hstep, voffA);
;             PG8_WAIT_V(8); PG8_WAIT_L(0); PG8_BAR; PG8_MMA(0, 0, At, B0); PG8_MMA(0, 1, At, B1); PG8_BAR; PG8_SCHED;
;             PG8_LDA(At, 1, 1); PG8_STAGE(PG8_SB(1, 0), b3, voffB); PG8_STAGE(PG8_SB(1, 1), b3 + hstep, voffB); PG8_STAGE(PG8_SA(1, 0), a3, voffA);
;             PG8_WAIT_V(8); PG8_WAIT_L(0); PG8_BAR; PG8_MMA(1, 0, At, B0); PG8_MMA(1, 1, At, B1); PG8_BAR; PG8_SCHED;
	s_add_i32 s77, 0, 0x18000
	s_add_i32 s79, 0, 0x1c000
	s_add_u32 s18, s42, 0x160000
	s_addc_u32 s19, s43, 0
	s_mov_b32 m0, s56
	s_nop 0
	global_load_lds_dwordx4 v190, s[18:19]
	ds_read_b128 v[118:121], v226 offset:32768
	ds_read_b128 v[122:125], v226 offset:33792
	ds_read_b128 v[130:133], v226 offset:34816
	ds_read_b128 v[134:137], v226 offset:35840
	ds_read_b128 v[146:149], v226 offset:49152
	ds_read_b128 v[150:153], v226 offset:50176
	ds_read_b128 v[154:157], v226 offset:51200
	ds_read_b128 v[158:161], v226 offset:52224
	s_mov_b32 m0, s57
	s_nop 0
	global_load_lds_dwordx4 v206, s[18:19]
	ds_read_b128 v[162:165], v222 offset:32768
	ds_read_b128 v[166:169], v222 offset:33792
	ds_read_b128 v[170:173], v222 offset:34816
	ds_read_b128 v[174:177], v222 offset:35840
	ds_read_b128 v[178:181], v222 offset:36864
	ds_read_b128 v[182:185], v222 offset:37888
	ds_read_b128 v[186:189], v222 offset:38912
	ds_read_b128 v[214:217], v222 offset:39936
	s_waitcnt lgkmcnt(0)
	s_setprio 1
	v_mfma_f32_16x16x32_bf16 v[142:145], v[118:121], v[162:165], v[142:145]
	v_mfma_f32_16x16x32_bf16 v[138:141], v[130:133], v[162:165], v[138:141]
	v_mfma_f32_16x16x32_bf16 v[110:113], v[118:121], v[170:173], v[110:113]
	v_mfma_f32_16x16x32_bf16 v[106:109], v[130:133], v[170:173], v[106:109]
	s_waitcnt vmcnt(8)
	s_barrier
	v_mfma_f32_16x16x32_bf16 v[94:97], v[118:121], v[178:181], v[94:97]
	v_mfma_f32_16x16x32_bf16 v[90:93], v[130:133], v[178:181], v[90:93]
	v_mfma_f32_16x16x32_bf16 v[78:81], v[118:121], v[186:189], v[78:81]
	v_mfma_f32_16x16x32_bf16 v[74:77], v[130:133], v[186:189], v[74:77]
	v_mfma_f32_16x16x32_bf16 v[142:145], v[122:125], v[166:169], v[142:145]
	v_mfma_f32_16x16x32_bf16 v[138:141], v[134:137], v[166:169], v[138:141]
	v_mfma_f32_16x16x32_bf16 v[110:113], v[122:125], v[174:177], v[110:113]
	v_mfma_f32_16x16x32_bf16 v[106:109], v[134:137], v[174:177], v[106:109]
	v_mfma_f32_16x16x32_bf16 v[94:97], v[122:125], v[182:185], v[94:97]
	v_mfma_f32_16x16x32_bf16 v[90:93], v[134:137], v[182:185], v[90:93]
	v_mfma_f32_16x16x32_bf16 v[78:81], v[122:125], v[214:217], v[78:81]
	v_mfma_f32_16x16x32_bf16 v[74:77], v[134:137], v[214:217], v[74:77]
	s_setprio 0
	s_setprio 1
	v_mfma_f32_16x16x32_bf16 v[126:129], v[146:149], v[162:165], v[126:129]
	v_mfma_f32_16x16x32_bf16 v[114:117], v[154:157], v[162:165], v[114:117]
	v_mfma_f32_16x16x32_bf16 v[102:105], v[146:149], v[170:173], v[102:105]
	v_mfma_f32_16x16x32_bf16 v[98:101], v[154:157], v[170:173], v[98:101]
	v_mfma_f32_16x16x32_bf16 v[86:89], v[146:149], v[178:181], v[86:89]
	v_mfma_f32_16x16x32_bf16 v[82:85], v[154:157], v[178:181], v[82:85]
	v_mfma_f32_16x16x32_bf16 v[70:73], v[146:149], v[186:189], v[70:73]
	v_mfma_f32_16x16x32_bf16 v[66:69], v[154:157], v[186:189], v[66:69]
	v_mfma_f32_16x16x32_bf16 v[126:129], v[150:153], v[166:169], v[126:129]
	v_mfma_f32_16x16x32_bf16 v[114:117], v[158:161], v[166:169], v[114:117]
	v_mfma_f32_16x16x32_bf16 v[102:105], v[150:153], v[174:177], v[102:105]
	v_mfma_f32_16x16x32_bf16 v[98:101], v[158:161], v[174:177], v[98:101]
	v_mfma_f32_16x16x32_bf16 v[86:89], v[150:153], v[182:185], v[86:89]
	v_mfma_f32_16x16x32_bf16 v[82:85], v[158:161], v[182:185], v[82:85]
	v_mfma_f32_16x16x32_bf16 v[70:73], v[150:153], v[214:217], v[70:73]
	v_mfma_f32_16x16x32_bf16 v[66:69], v[158:161], v[214:217], v[66:69]
	s_setprio 0
	s_barrier
	s_add_u32 vcc_lo, s42, 0x80
	s_addc_u32 vcc_hi, s43, 0
	s_mov_b32 m0, s68
	s_nop 0
	global_load_lds_dwordx4 v190, vcc
	ds_read_b128 v[162:165], v222 offset:49152
	ds_read_b128 v[166:169], v222 offset:50176
	s_mov_b32 m0, s69
	s_add_i32 s18, s77, s49
	global_load_lds_dwordx4 v206, vcc
	ds_read_b128 v[170:173], v222 offset:51200
	ds_read_b128 v[174:177], v222 offset:52224
	s_add_u32 vcc_lo, s40, 0x80
	s_addc_u32 vcc_hi, s41, 0
	s_mov_b32 m0, s18
	s_nop 0
	global_load_lds_dwordx4 v192, vcc
	ds_read_b128 v[178:181], v222 offset:53248
	ds_read_b128 v[182:185], v222 offset:54272
	s_add_i32 m0, s18, 0x2000
	s_add_u32 s18, s40, 0x160080
	s_addc_u32 s19, s41, 0
	global_load_lds_dwordx4 v208, vcc
	ds_read_b128 v[186:189], v222 offset:55296
	ds_read_b128 v[214:217], v222 offset:56320
	s_add_i32 s40, s79, s49
	s_mov_b32 m0, s40
	s_nop 0
	global_load_lds_dwordx4 v192, s[18:19]
	s_add_i32 m0, s40, 0x2000
	s_nop 0
	global_load_lds_dwordx4 v208, s[18:19]
	s_waitcnt lgkmcnt(0)
	s_setprio 1
	v_mfma_f32_16x16x32_bf16 v[62:65], v[118:121], v[162:165], v[62:65]
	v_mfma_f32_16x16x32_bf16 v[58:61], v[130:133], v[162:165], v[58:61]
	v_mfma_f32_16x16x32_bf16 v[46:49], v[118:121], v[170:173], v[46:49]
	v_mfma_f32_16x16x32_bf16 v[42:45], v[130:133], v[170:173], v[42:45]
	s_waitcnt vmcnt(8)
	s_barrier
	v_mfma_f32_16x16x32_bf16 v[30:33], v[118:121], v[178:181], v[30:33]
	v_mfma_f32_16x16x32_bf16 v[26:29], v[130:133], v[178:181], v[26:29]
	v_mfma_f32_16x16x32_bf16 v[14:17], v[118:121], v[186:189], v[14:17]
	v_mfma_f32_16x16x32_bf16 v[10:13], v[130:133], v[186:189], v[10:13]
	v_mfma_f32_16x16x32_bf16 v[62:65], v[122:125], v[166:169], v[62:65]
	v_mfma_f32_16x16x32_bf16 v[58:61], v[134:137], v[166:169], v[58:61]
	v_mfma_f32_16x16x32_bf16 v[46:49], v[122:125], v[174:177], v[46:49]
	v_mfma_f32_16x16x32_bf16 v[42:45], v[134:137], v[174:177], v[42:45]
	v_mfma_f32_16x16x32_bf16 v[30:33], v[122:125], v[182:185], v[30:33]
	v_mfma_f32_16x16x32_bf16 v[26:29], v[134:137], v[182:185], v[26:29]
	v_mfma_f32_16x16x32_bf16 v[14:17], v[122:125], v[214:217], v[14:17]
	v_mfma_f32_16x16x32_bf16 v[10:13], v[134:137], v[214:217], v[10:13]
	s_setprio 0
	s_setprio 1
	v_mfma_f32_16x16x32_bf16 v[54:57], v[146:149], v[162:165], v[54:57]
	v_mfma_f32_16x16x32_bf16 v[50:53], v[154:157], v[162:165], v[50:53]
	v_mfma_f32_16x16x32_bf16 v[38:41], v[146:149], v[170:173], v[38:41]
	v_mfma_f32_16x16x32_bf16 v[34:37], v[154:157], v[170:173], v[34:37]
	v_mfma_f32_16x16x32_bf16 v[22:25], v[146:149], v[178:181], v[22:25]
	v_mfma_f32_16x16x32_bf16 v[18:21], v[154:157], v[178:181], v[18:21]
	v_mfma_f32_16x16x32_bf16 v[6:9], v[146:149], v[186:189], v[6:9]
	v_mfma_f32_16x16x32_bf16 v[2:5], v[154:157], v[186:189], v[2:5]
	v_mfma_f32_16x16x32_bf16 v[54:57], v[150:153], v[166:169], v[54:57]
	v_mfma_f32_16x16x32_bf16 v[50:53], v[158:161], v[166:169], v[50:53]
	v_mfma_f32_16x16x32_bf16 v[38:41], v[150:153], v[174:177], v[38:41]
	v_mfma_f32_16x16x32_bf16 v[34:37], v[158:161], v[174:177], v[34:37]
	v_mfma_f32_16x16x32_bf16 v[22:25], v[150:153], v[182:185], v[22:25]
	v_mfma_f32_16x16x32_bf16 v[18:21], v[158:161], v[182:185], v[18:21]
	v_mfma_f32_16x16x32_bf16 v[6:9], v[150:153], v[214:217], v[6:9]
	v_mfma_f32_16x16x32_bf16 v[2:5], v[158:161], v[214:217], v[2:5]
	s_setprio 0
	s_barrier
	s_add_i32 s76, s76, 2
	s_add_u32 s74, s74, 0x100
	s_addc_u32 s75, s75, 0
	s_cmpk_gt_u32 s76, 0x55
	s_mov_b64 s[18:19], s[20:21]
	s_cbranch_scc1 .Lpeel_exit_g4
; #define PG8_STAGE(bufoff, gbase, voff) do { _Pragma("unroll") for (int _i = 0; _i < 2; ++_i) \
;         __builtin_amdgcn_global_load_lds((const unsigned*)((const char*)(gbase) + (voff)[_i]), (PG8_LAS unsigned*)(lds + (bufoff) + ldsw + _i * 8192), 16, 0, 0); } while (0)
; #define PG8_LDA(dst, b, h) do { _Pragma("unroll") for (int m = 0; m < 4; ++m) _Pragma("unroll") for (int k = 0; k < 2; ++k) dst[m][k] = *(const PG8_LAS bf16x8*)(lds + PG8_SA(b, h) + aoff + m * 2048 + k * 1024); } while (0)
; #define PG8_LDB(dst, b, h) do { _Pragma("unroll") for (int n = 0; n < 2; ++n) _Pragma("unroll") for (int k = 0; k < 2; ++k) dst[n][k] = *(const PG8_LAS bf16x8*)(lds + PG8_SB(b, h) + boff + n * 2048 + k * 1024); } while (0)
; #define PG8_MMA(ai, bj, At, Bt) do { __builtin_amdgcn_s_setprio(1); _Pragma("unroll") for (int m = 0; m < 4; ++m) _Pragma("unroll") for (int n = 0; n < 2; ++n) _Pragma("unroll") for (int k = 0; k < 2; ++k) \
;         acc[ai][bj][m][n] = __builtin_amdgcn_mfma_f32_16x16x32_bf16(Bt[n][k], At[m][k], acc[ai][bj][m][n], 0, 0, 0); __builtin_amdgcn_s_setprio(0); } while (0)
; #define PG8_WAIT_V(n) asm volatile("s_waitcnt vmcnt(" #n ")" ::: "memory")
; #define PG8_BAR __builtin_amdgcn_s_barrier()
; template <class Epi, class Sched, bool ALIGN_EPI = false, bool SP2 = false>
; __device__ __forceinline__ void gemm_phase(PG8_LAS unsigned char* lds, const Gemm g, const Sched& S, const Epi& E, const int wave_id) {
;     ...
;         for (int t = 0; t < nt; t += 2) {
;             const bool last = (t == nt - 2);
;             const char* a1 = cA + (size_t)(t + 1) * kstep;
;             const char* a2 = last ? nA : cA + (size_t)(t + 2) * kstep; const char* b2 = last ? nB : cB + (size_t)(t + 2) * kstep;
;             const char* a3 = a2 + kstep; const char* b3 = b2 + kstep;
;             if (last && has_next) S.a_ready(nxt);
;             if constexpr (SP2) {
;             PG8_LDB(B0, 0, 0); PG8_LDB(B1, 0, 1); PG8_SCHED; PG8_LDA(At, 0, 0); PG8_STAGE(PG8_SA(1, 1), a1 + hstep, voffA);
;             PG8_WAIT_V(8); PG8_WAIT_L(0); PG8_BAR; PG8_MMA(0, 0, At, B0); PG8_MMA(0, 1, At, B1); PG8_BAR; PG8_SCHED;
;             PG8_LDA(At, 0, 1); PG8_STAGE(PG8_SB(0, 0), b2, voffB); PG8_STAGE(PG8_SB(0, 1), b2 + hstep, voffB); PG8_STAGE(PG8_SA(0, 0), a2, voffA);
;             PG8_WAIT_V(8); PG8_WAIT_L(0); PG8_BAR; PG8_MMA(1, 0, At, B0); PG8_MMA(1, 1, At, B1); PG8_BAR; PG8_SCHED;
.LBB0_759:
	s_add_u32 s20, s18, 0x100
	s_addc_u32 s21, s19, 0
	s_add_i32 s77, 0, 0x10000
	s_cmpk_eq_i32 s76, 0x54
	s_cselect_b32 s43, s15, s21
	s_cselect_b32 s42, s14, s20
	s_cselect_b32 s41, s17, s75
	s_cselect_b32 s40, s16, s74
	s_add_i32 s79, 0, 0x14000
	s_add_i32 m0, s52, 0xc000
	s_nop 0
	global_load_lds_dwordx4 v210, s[18:19]
	ds_read_b128 v[118:121], v226
	ds_read_b128 v[122:125], v226 offset:1024
	ds_read_b128 v[130:133], v226 offset:2048
	ds_read_b128 v[134:137], v226 offset:3072
	ds_read_b128 v[146:149], v226 offset:16384
	ds_read_b128 v[150:153], v226 offset:17408
	ds_read_b128 v[154:157], v226 offset:18432
	ds_read_b128 v[158:161], v226 offset:19456
	s_add_i32 m0, s52, 0xe000
	s_nop 0
	global_load_lds_dwordx4 v212, s[18:19]
	ds_read_b128 v[162:165], v222
	ds_read_b128 v[166:169], v222 offset:1024
	ds_read_b128 v[170:173], v222 offset:2048
	ds_read_b128 v[174:177], v222 offset:3072
	ds_read_b128 v[178:181], v222 offset:4096
	ds_read_b128 v[182:185], v222 offset:5120
	ds_read_b128 v[186:189], v222 offset:6144
	ds_read_b128 v[214:217], v222 offset:7168
	s_waitcnt lgkmcnt(0)
	s_setprio 1
	v_mfma_f32_16x16x32_bf16 v[142:145], v[118:121], v[162:165], v[142:145]
	v_mfma_f32_16x16x32_bf16 v[138:141], v[130:133], v[162:165], v[138:141]
	v_mfma_f32_16x16x32_bf16 v[110:113], v[118:121], v[170:173], v[110:113]
	v_mfma_f32_16x16x32_bf16 v[106:109], v[130:133], v[170:173], v[106:109]
	s_waitcnt vmcnt(8)
	s_barrier
	v_mfma_f32_16x16x32_bf16 v[94:97], v[118:121], v[178:181], v[94:97]
	v_mfma_f32_16x16x32_bf16 v[90:93], v[130:133], v[178:181], v[90:93]
	v_mfma_f32_16x16x32_bf16 v[78:81], v[118:121], v[186:189], v[78:81]
	v_mfma_f32_16x16x32_bf16 v[74:77], v[130:133], v[186:189], v[74:77]
	v_mfma_f32_16x16x32_bf16 v[142:145], v[122:125], v[166:169], v[142:145]
	v_mfma_f32_16x16x32_bf16 v[138:141], v[134:137], v[166:169], v[138:141]
	v_mfma_f32_16x16x32_bf16 v[110:113], v[122:125], v[174:177], v[110:113]
	v_mfma_f32_16x16x32_bf16 v[106:109], v[134:137], v[174:177], v[106:109]
	v_mfma_f32_16x16x32_bf16 v[94:97], v[122:125], v[182:185], v[94:97]
	v_mfma_f32_16x16x32_bf16 v[90:93], v[134:137], v[182:185], v[90:93]
	v_mfma_f32_16x16x32_bf16 v[78:81], v[122:125], v[214:217], v[78:81]
	v_mfma_f32_16x16x32_bf16 v[74:77], v[134:137], v[214:217], v[74:77]
	s_setprio 0
	s_setprio 1
	v_mfma_f32_16x16x32_bf16 v[126:129], v[146:149], v[162:165], v[126:129]
	v_mfma_f32_16x16x32_bf16 v[114:117], v[154:157], v[162:165], v[114:117]
	v_mfma_f32_16x16x32_bf16 v[102:105], v[146:149], v[170:173], v[102:105]
	v_mfma_f32_16x16x32_bf16 v[98:101], v[154:157], v[170:173], v[98:101]
	v_mfma_f32_16x16x32_bf16 v[86:89], v[146:149], v[178:181], v[86:89]
	v_mfma_f32_16x16x32_bf16 v[82:85], v[154:157], v[178:181], v[82:85]
	v_mfma_f32_16x16x32_bf16 v[70:73], v[146:149], v[186:189], v[70:73]
	v_mfma_f32_16x16x32_bf16 v[66:69], v[154:157], v[186:189], v[66:69]
	v_mfma_f32_16x16x32_bf16 v[126:129], v[150:153], v[166:169], v[126:129]
	v_mfma_f32_16x16x32_bf16 v[114:117], v[158:161], v[166:169], v[114:117]
	v_mfma_f32_16x16x32_bf16 v[102:105], v[150:153], v[174:177], v[102:105]
	v_mfma_f32_16x16x32_bf16 v[98:101], v[158:161], v[174:177], v[98:101]
	v_mfma_f32_16x16x32_bf16 v[86:89], v[150:153], v[182:185], v[86:89]
	v_mfma_f32_16x16x32_bf16 v[82:85], v[158:161], v[182:185], v[82:85]
	v_mfma_f32_16x16x32_bf16 v[70:73], v[150:153], v[214:217], v[70:73]
	v_mfma_f32_16x16x32_bf16 v[66:69], v[158:161], v[214:217], v[66:69]
	s_setprio 0
	s_barrier
	s_add_i32 s18, s77, s49
	s_mov_b32 m0, s18
	s_nop 0
	global_load_lds_dwordx4 v192, s[40:41]
	ds_read_b128 v[162:165], v222 offset:16384
	ds_read_b128 v[166:169], v222 offset:17408
	s_add_i32 m0, s18, 0x2000
	s_add_u32 s18, s40, 0x160000
	s_addc_u32 s19, s41, 0
	s_add_i32 s77, s79, s49
	global_load_lds_dwordx4 v208, s[40:41]
	ds_read_b128 v[170:173], v222 offset:18432
	ds_read_b128 v[174:177], v222 offset:19456
	s_mov_b32 m0, s77
	s_nop 0
	global_load_lds_dwordx4 v192, s[18:19]
	ds_read_b128 v[178:181], v222 offset:20480
	ds_read_b128 v[182:185], v222 offset:21504
	s_add_i32 m0, s77, 0x2000
	s_nop 0
	global_load_lds_dwordx4 v208, s[18:19]
	ds_read_b128 v[186:189], v222 offset:22528
	ds_read_b128 v[214:217], v222 offset:23552
	s_mov_b32 m0, s52
	s_nop 0
	global_load_lds_dwordx4 v190, s[42:43]
	s_mov_b32 m0, s53
	s_nop 0
	global_load_lds_dwordx4 v206, s[42:43]
	s_waitcnt lgkmcnt(0)
	s_setprio 1
	v_mfma_f32_16x16x32_bf16 v[62:65], v[118:121], v[162:165], v[62:65]
	v_mfma_f32_16x16x32_bf16 v[58:61], v[130:133], v[162:165], v[58:61]
	v_mfma_f32_16x16x32_bf16 v[46:49], v[118:121], v[170:173], v[46:49]
	v_mfma_f32_16x16x32_bf16 v[42:45], v[130:133], v[170:173], v[42:45]
	s_waitcnt vmcnt(8)
	s_barrier
; #define PG8_STAGE(bufoff, gbase, voff) do { _Pragma("unroll") for (int _i = 0; _i < 2; ++_i) \
;         __builtin_amdgcn_global_load_lds((const unsigned*)((const char*)(gbase) + (voff)[_i]), (PG8_LAS unsigned*)(lds + (bufoff) + ldsw + _i * 8192), 16, 0, 0); } while (0)
; #define PG8_LDA(dst, b, h) do { _Pragma("unroll") for (int m = 0; m < 4; ++m) _Pragma("unroll") for (int k = 0; k < 2; ++k) dst[m][k] = *(const PG8_LAS bf16x8*)(lds + PG8_SA(b, h) + aoff + m * 2048 + k * 1024); } while (0)
; #define PG8_LDB(dst, b, h) do { _Pragma("unroll") for (int n = 0; n < 2; ++n) _Pragma("unroll") for (int k = 0; k < 2; ++k) dst[n][k] = *(const PG8_LAS bf16x8*)(lds + PG8_SB(b, h) + boff + n * 2048 + k * 1024); } while (0)
; #define PG8_MMA(ai, bj, At, Bt) do { __builtin_amdgcn_s_setprio(1); _Pragma("unroll") for (int m = 0; m < 4; ++m) _Pragma("unroll") for (int n = 0; n < 2; ++n) _Pragma("unroll") for (int k = 0; k < 2; ++k) \
;         acc[ai][bj][m][n] = __builtin_amdgcn_mfma_f32_16x16x32_bf16(Bt[n][k], At[m][k], acc[ai][bj][m][n], 0, 0, 0); __builtin_amdgcn_s_setprio(0); } while (0)
; #define PG8_WAIT_V(n) asm volatile("s_waitcnt vmcnt(" #n ")" ::: "memory")
; #define PG8_WAIT_L(n) asm volatile("s_waitcnt lgkmcnt(" #n ")" ::: "memory")
; #define PG8_BAR __builtin_amdgcn_s_barrier()
; #define PG8_SCHED __builtin_amdgcn_sched_barrier(0)
; template <class Epi, class Sched, bool ALIGN_EPI = false, bool SP2 = false>
; __device__ __forceinline__ void gemm_phase(PG8_LAS unsigned char* lds, const Gemm g, const Sched& S, const Epi& E, const int wave_id) {
;     ...
;             PG8_WAIT_V(8); PG8_WAIT_L(0); PG8_BAR; PG8_MMA(1, 0, At, B0); PG8_MMA(1, 1, At, B1); PG8_BAR; PG8_SCHED;
;             PG8_LDB(B0, 1, 0); PG8_LDB(B1, 1, 1); PG8_SCHED; PG8_LDA(At, 1, 0); PG8_STAGE(PG8_SA(0, 1), a2 + hstep, voffA);
;             PG8_WAIT_V(8); PG8_WAIT_L(0); PG8_BAR; PG8_MMA(0, 0, At, B0); PG8_MMA(0, 1, At, B1); PG8_BAR; PG8_SCHED;
;             PG8_LDA(At, 1, 1); PG8_STAGE(PG8_SB(1, 0), b3, voffB); PG8_STAGE(PG8_SB(1, 1), b3 + hstep, voffB); PG8_STAGE(PG8_SA(1, 0), a3, voffA);
	v_mfma_f32_16x16x32_bf16 v[30:33], v[118:121], v[178:181], v[30:33]
	v_mfma_f32_16x16x32_bf16 v[26:29], v[130:133], v[178:181], v[26:29]
	v_mfma_f32_16x16x32_bf16 v[14:17], v[118:121], v[186:189], v[14:17]
	v_mfma_f32_16x16x32_bf16 v[10:13], v[130:133], v[186:189], v[10:13]
	v_mfma_f32_16x16x32_bf16 v[62:65], v[122:125], v[166:169], v[62:65]
	v_mfma_f32_16x16x32_bf16 v[58:61], v[134:137], v[166:169], v[58:61]
	v_mfma_f32_16x16x32_bf16 v[46:49], v[122:125], v[174:177], v[46:49]
	v_mfma_f32_16x16x32_bf16 v[42:45], v[134:137], v[174:177], v[42:45]
	v_mfma_f32_16x16x32_bf16 v[30:33], v[122:125], v[182:185], v[30:33]
	v_mfma_f32_16x16x32_bf16 v[26:29], v[134:137], v[182:185], v[26:29]
	v_mfma_f32_16x16x32_bf16 v[14:17], v[122:125], v[214:217], v[14:17]
	v_mfma_f32_16x16x32_bf16 v[10:13], v[134:137], v[214:217], v[10:13]
	s_setprio 0
	s_setprio 1
	v_mfma_f32_16x16x32_bf16 v[54:57], v[146:149], v[162:165], v[54:57]
	v_mfma_f32_16x16x32_bf16 v[50:53], v[154:157], v[162:165], v[50:53]
	v_mfma_f32_16x16x32_bf16 v[38:41], v[146:149], v[170:173], v[38:41]
	v_mfma_f32_16x16x32_bf16 v[34:37], v[154:157], v[170:173], v[34:37]
	v_mfma_f32_16x16x32_bf16 v[22:25], v[146:149], v[178:181], v[22:25]
	v_mfma_f32_16x16x32_bf16 v[18:21], v[154:157], v[178:181], v[18:21]
	v_mfma_f32_16x16x32_bf16 v[6:9], v[146:149], v[186:189], v[6:9]
	v_mfma_f32_16x16x32_bf16 v[2:5], v[154:157], v[186:189], v[2:5]
	v_mfma_f32_16x16x32_bf16 v[54:57], v[150:153], v[166:169], v[54:57]
	v_mfma_f32_16x16x32_bf16 v[50:53], v[158:161], v[166:169], v[50:53]
	v_mfma_f32_16x16x32_bf16 v[38:41], v[150:153], v[174:177], v[38:41]
	v_mfma_f32_16x16x32_bf16 v[34:37], v[158:161], v[174:177], v[34:37]
	v_mfma_f32_16x16x32_bf16 v[22:25], v[150:153], v[182:185], v[22:25]
	v_mfma_f32_16x16x32_bf16 v[18:21], v[158:161], v[182:185], v[18:21]
	v_mfma_f32_16x16x32_bf16 v[6:9], v[150:153], v[214:217], v[6:9]
	v_mfma_f32_16x16x32_bf16 v[2:5], v[158:161], v[214:217], v[2:5]
	s_setprio 0
	s_barrier
	s_add_i32 s77, 0, 0x18000
	s_add_i32 s79, 0, 0x1c000
	s_add_u32 s18, s42, 0x160000
	s_addc_u32 s19, s43, 0
	s_mov_b32 m0, s56
	s_nop 0
	global_load_lds_dwordx4 v190, s[18:19]
	ds_read_b128 v[118:121], v226 offset:32768
	ds_read_b128 v[122:125], v226 offset:33792
	ds_read_b128 v[130:133], v226 offset:34816
	ds_read_b128 v[134:137], v226 offset:35840
	ds_read_b128 v[146:149], v226 offset:49152
	ds_read_b128 v[150:153], v226 offset:50176
	ds_read_b128 v[154:157], v226 offset:51200
	ds_read_b128 v[158:161], v226 offset:52224
	s_mov_b32 m0, s57
	s_nop 0
	global_load_lds_dwordx4 v206, s[18:19]
	ds_read_b128 v[162:165], v222 offset:32768
	ds_read_b128 v[166:169], v222 offset:33792
	ds_read_b128 v[170:173], v222 offset:34816
	ds_read_b128 v[174:177], v222 offset:35840
	ds_read_b128 v[178:181], v222 offset:36864
	ds_read_b128 v[182:185], v222 offset:37888
	ds_read_b128 v[186:189], v222 offset:38912
	ds_read_b128 v[214:217], v222 offset:39936
	s_waitcnt lgkmcnt(0)
	s_setprio 1
	v_mfma_f32_16x16x32_bf16 v[142:145], v[118:121], v[162:165], v[142:145]
	v_mfma_f32_16x16x32_bf16 v[138:141], v[130:133], v[162:165], v[138:141]
	v_mfma_f32_16x16x32_bf16 v[110:113], v[118:121], v[170:173], v[110:113]
	v_mfma_f32_16x16x32_bf16 v[106:109], v[130:133], v[170:173], v[106:109]
	s_waitcnt vmcnt(8)
	s_barrier
	v_mfma_f32_16x16x32_bf16 v[94:97], v[118:121], v[178:181], v[94:97]
	v_mfma_f32_16x16x32_bf16 v[90:93], v[130:133], v[178:181], v[90:93]
	v_mfma_f32_16x16x32_bf16 v[78:81], v[118:121], v[186:189], v[78:81]
	v_mfma_f32_16x16x32_bf16 v[74:77], v[130:133], v[186:189], v[74:77]
	v_mfma_f32_16x16x32_bf16 v[142:145], v[122:125], v[166:169], v[142:145]
	v_mfma_f32_16x16x32_bf16 v[138:141], v[134:137], v[166:169], v[138:141]
	v_mfma_f32_16x16x32_bf16 v[110:113], v[122:125], v[174:177], v[110:113]
	v_mfma_f32_16x16x32_bf16 v[106:109], v[134:137], v[174:177], v[106:109]
	v_mfma_f32_16x16x32_bf16 v[94:97], v[122:125], v[182:185], v[94:97]
	v_mfma_f32_16x16x32_bf16 v[90:93], v[134:137], v[182:185], v[90:93]
	v_mfma_f32_16x16x32_bf16 v[78:81], v[122:125], v[214:217], v[78:81]
	v_mfma_f32_16x16x32_bf16 v[74:77], v[134:137], v[214:217], v[74:77]
	s_setprio 0
	s_setprio 1
	v_mfma_f32_16x16x32_bf16 v[126:129], v[146:149], v[162:165], v[126:129]
	v_mfma_f32_16x16x32_bf16 v[114:117], v[154:157], v[162:165], v[114:117]
	v_mfma_f32_16x16x32_bf16 v[102:105], v[146:149], v[170:173], v[102:105]
	v_mfma_f32_16x16x32_bf16 v[98:101], v[154:157], v[170:173], v[98:101]
	v_mfma_f32_16x16x32_bf16 v[86:89], v[146:149], v[178:181], v[86:89]
	v_mfma_f32_16x16x32_bf16 v[82:85], v[154:157], v[178:181], v[82:85]
	v_mfma_f32_16x16x32_bf16 v[70:73], v[146:149], v[186:189], v[70:73]
	v_mfma_f32_16x16x32_bf16 v[66:69], v[154:157], v[186:189], v[66:69]
	v_mfma_f32_16x16x32_bf16 v[126:129], v[150:153], v[166:169], v[126:129]
	v_mfma_f32_16x16x32_bf16 v[114:117], v[158:161], v[166:169], v[114:117]
	v_mfma_f32_16x16x32_bf16 v[102:105], v[150:153], v[174:177], v[102:105]
	v_mfma_f32_16x16x32_bf16 v[98:101], v[158:161], v[174:177], v[98:101]
	v_mfma_f32_16x16x32_bf16 v[86:89], v[150:153], v[182:185], v[86:89]
	v_mfma_f32_16x16x32_bf16 v[82:85], v[158:161], v[182:185], v[82:85]
	v_mfma_f32_16x16x32_bf16 v[70:73], v[150:153], v[214:217], v[70:73]
	v_mfma_f32_16x16x32_bf16 v[66:69], v[158:161], v[214:217], v[66:69]
	s_setprio 0
	s_barrier
; #define PG8_STAGE(bufoff, gbase, voff) do { _Pragma("unroll") for (int _i = 0; _i < 2; ++_i) \
;         __builtin_amdgcn_global_load_lds((const unsigned*)((const char*)(gbase) + (voff)[_i]), (PG8_LAS unsigned*)(lds + (bufoff) + ldsw + _i * 8192), 16, 0, 0); } while (0)
; #define PG8_LDA(dst, b, h) do { _Pragma("unroll") for (int m = 0; m < 4; ++m) _Pragma("unroll") for (int k = 0; k < 2; ++k) dst[m][k] = *(const PG8_LAS bf16x8*)(lds + PG8_SA(b, h) + aoff + m * 2048 + k * 1024); } while (0)
; #define PG8_WAIT_V(n) asm volatile("s_waitcnt vmcnt(" #n ")" ::: "memory")
; #define PG8_WAIT_L(n) asm volatile("s_waitcnt lgkmcnt(" #n ")" ::: "memory")
; #define PG8_BAR __builtin_amdgcn_s_barrier()
; template <class Epi, class Sched, bool ALIGN_EPI = false, bool SP2 = false>
; __device__ __forceinline__ void gemm_phase(PG8_LAS unsigned char* lds, const Gemm g, const Sched& S, const Epi& E, const int wave_id) {
;     ...
;         for (int t = 0; t < nt; t += 2) {
;             const bool last = (t == nt - 2);
;             const char* a1 = cA + (size_t)(t + 1) * kstep;
;             const char* a2 = last ? nA : cA + (size_t)(t + 2) * kstep; const char* b2 = last ? nB : cB + (size_t)(t + 2) * kstep;
;             const char* a3 = a2 + kstep; const char* b3 = b2 + kstep;
;             if (last && has_next) S.a_ready(nxt);
;             if constexpr (SP2) {
;             PG8_LDB(B0, 0, 0); PG8_LDB(B1, 0, 1); PG8_SCHED; PG8_LDA(At, 0, 0); PG8_STAGE(PG8_SA(1, 1), a1 + hstep, voffA);
;             PG8_WAIT_V(8); PG8_WAIT_L(0); PG8_BAR; PG8_MMA(0, 0, At, B0); PG8_MMA(0, 1, At, B1); PG8_BAR; PG8_SCHED;
;             PG8_LDA(At, 0, 1); PG8_STAGE(PG8_SB(0, 0), b2, voffB); PG8_STAGE(PG8_SB(0, 1), b2 + hstep, voffB); PG8_STAGE(PG8_SA(0, 0), a2, voffA);
;             PG8_WAIT_V(8); PG8_WAIT_L(0); PG8_BAR; PG8_MMA(1, 0, At, B0); PG8_MMA(1, 1, At, B1); PG8_BAR; PG8_SCHED;
;             PG8_LDB(B0, 1, 0); PG8_LDB(B1, 1, 1); PG8_SCHED; PG8_LDA(At, 1, 0); PG8_STAGE(PG8_SA(0, 1), a2 + hstep, voffA);
;             PG8_WAIT_V(8); PG8_WAIT_L(0); PG8_BAR; PG8_MMA(0, 0, At, B0); PG8_MMA(0, 1, At, B1); PG8_BAR; PG8_SCHED;
;             PG8_LDA(At, 1, 1); PG8_STAGE(PG8_SB(1, 0), b3, voffB); PG8_STAGE(PG8_SB(1, 1), b3 + hstep, voffB); PG8_STAGE(PG8_SA(1, 0), a3, voffA);
;             PG8_WAIT_V(8); PG8_WAIT_L(0); PG8_BAR; PG8_MMA(1, 0, At, B0); PG8_MMA(1, 1, At, B1); PG8_BAR; PG8_SCHED;
	s_add_u32 vcc_lo, s42, 0x80
	s_addc_u32 vcc_hi, s43, 0
	s_mov_b32 m0, s68
	s_nop 0
	global_load_lds_dwordx4 v190, vcc
	ds_read_b128 v[162:165], v222 offset:49152
	ds_read_b128 v[166:169], v222 offset:50176
	s_mov_b32 m0, s69
	s_add_i32 s18, s77, s49
	global_load_lds_dwordx4 v206, vcc
	ds_read_b128 v[170:173], v222 offset:51200
	ds_read_b128 v[174:177], v222 offset:52224
	s_add_u32 vcc_lo, s40, 0x80
	s_addc_u32 vcc_hi, s41, 0
	s_mov_b32 m0, s18
	s_nop 0
	global_load_lds_dwordx4 v192, vcc
	ds_read_b128 v[178:181], v222 offset:53248
	ds_read_b128 v[182:185], v222 offset:54272
	s_add_i32 m0, s18, 0x2000
	s_add_u32 s18, s40, 0x160080
	s_addc_u32 s19, s41, 0
	global_load_lds_dwordx4 v208, vcc
	ds_read_b128 v[186:189], v222 offset:55296
	ds_read_b128 v[214:217], v222 offset:56320
	s_add_i32 s40, s79, s49
	s_mov_b32 m0, s40
	s_nop 0
	global_load_lds_dwordx4 v192, s[18:19]
	s_add_i32 m0, s40, 0x2000
	s_nop 0
	global_load_lds_dwordx4 v208, s[18:19]
	s_waitcnt lgkmcnt(0)
	s_setprio 1
	v_mfma_f32_16x16x32_bf16 v[62:65], v[118:121], v[162:165], v[62:65]
	v_mfma_f32_16x16x32_bf16 v[58:61], v[130:133], v[162:165], v[58:61]
	v_mfma_f32_16x16x32_bf16 v[46:49], v[118:121], v[170:173], v[46:49]
	v_mfma_f32_16x16x32_bf16 v[42:45], v[130:133], v[170:173], v[42:45]
	s_waitcnt vmcnt(8)
	s_barrier
	v_mfma_f32_16x16x32_bf16 v[30:33], v[118:121], v[178:181], v[30:33]
	v_mfma_f32_16x16x32_bf16 v[26:29], v[130:133], v[178:181], v[26:29]
	v_mfma_f32_16x16x32_bf16 v[14:17], v[118:121], v[186:189], v[14:17]
	v_mfma_f32_16x16x32_bf16 v[10:13], v[130:133], v[186:189], v[10:13]
	v_mfma_f32_16x16x32_bf16 v[62:65], v[122:125], v[166:169], v[62:65]
	v_mfma_f32_16x16x32_bf16 v[58:61], v[134:137], v[166:169], v[58:61]
	v_mfma_f32_16x16x32_bf16 v[46:49], v[122:125], v[174:177], v[46:49]
	v_mfma_f32_16x16x32_bf16 v[42:45], v[134:137], v[174:177], v[42:45]
	v_mfma_f32_16x16x32_bf16 v[30:33], v[122:125], v[182:185], v[30:33]
	v_mfma_f32_16x16x32_bf16 v[26:29], v[134:137], v[182:185], v[26:29]
	v_mfma_f32_16x16x32_bf16 v[14:17], v[122:125], v[214:217], v[14:17]
	v_mfma_f32_16x16x32_bf16 v[10:13], v[134:137], v[214:217], v[10:13]
	s_setprio 0
	s_setprio 1
	v_mfma_f32_16x16x32_bf16 v[54:57], v[146:149], v[162:165], v[54:57]
	v_mfma_f32_16x16x32_bf16 v[50:53], v[154:157], v[162:165], v[50:53]
	v_mfma_f32_16x16x32_bf16 v[38:41], v[146:149], v[170:173], v[38:41]
	v_mfma_f32_16x16x32_bf16 v[34:37], v[154:157], v[170:173], v[34:37]
	v_mfma_f32_16x16x32_bf16 v[22:25], v[146:149], v[178:181], v[22:25]
	v_mfma_f32_16x16x32_bf16 v[18:21], v[154:157], v[178:181], v[18:21]
	v_mfma_f32_16x16x32_bf16 v[6:9], v[146:149], v[186:189], v[6:9]
	v_mfma_f32_16x16x32_bf16 v[2:5], v[154:157], v[186:189], v[2:5]
	v_mfma_f32_16x16x32_bf16 v[54:57], v[150:153], v[166:169], v[54:57]
	v_mfma_f32_16x16x32_bf16 v[50:53], v[158:161], v[166:169], v[50:53]
	v_mfma_f32_16x16x32_bf16 v[38:41], v[150:153], v[174:177], v[38:41]
	v_mfma_f32_16x16x32_bf16 v[34:37], v[158:161], v[174:177], v[34:37]
	v_mfma_f32_16x16x32_bf16 v[22:25], v[150:153], v[182:185], v[22:25]
	v_mfma_f32_16x16x32_bf16 v[18:21], v[158:161], v[182:185], v[18:21]
	v_mfma_f32_16x16x32_bf16 v[6:9], v[150:153], v[214:217], v[6:9]
	v_mfma_f32_16x16x32_bf16 v[2:5], v[158:161], v[214:217], v[2:5]
	s_setprio 0
	s_barrier
	s_add_i32 s76, s76, 2
	s_add_u32 s74, s74, 0x100
	s_addc_u32 s75, s75, 0
	s_cmpk_gt_u32 s76, 0x55
	s_mov_b64 s[18:19], s[20:21]
	s_cbranch_scc0 .LBB0_759

;     __host__ __device__ bool next(int i, Unit& u) const { const bool ok = StaticOrder::next(i, u); u.lm = 0; u.ln = 0; return ok; }
; #define PG8_STAGE(bufoff, gbase, voff) do { _Pragma("unroll") for (int _i = 0; _i < 2; ++_i) \
;         __builtin_amdgcn_global_load_lds((const unsigned*)((const char*)(gbase) + (voff)[_i]), (PG8_LAS unsigned*)(lds + (bufoff) + ldsw + _i * 8192), 16, 0, 0); } while (0)
; #define PG8_LDA(dst, b, h) do { _Pragma("unroll") for (int m = 0; m < 4; ++m) _Pragma("unroll") for (int k = 0; k < 2; ++k) dst[m][k] = *(const PG8_LAS bf16x8*)(lds + PG8_SA(b, h) + aoff + m * 2048 + k * 1024); } while (0)
; #define PG8_LDB(dst, b, h) do { _Pragma("unroll") for (int n = 0; n < 2; ++n) _Pragma("unroll") for (int k = 0; k < 2; ++k) dst[n][k] = *(const PG8_LAS bf16x8*)(lds + PG8_SB(b, h) + boff + n * 2048 + k * 1024); } while (0)
; #define PG8_WAIT_V(n) asm volatile("s_waitcnt vmcnt(" #n ")" ::: "memory")
; #define PG8_BAR __builtin_amdgcn_s_barrier()
; template <class Epi, class Sched, bool ALIGN_EPI = false, bool SP2 = false>
; __device__ __forceinline__ void gemm_phase(PG8_LAS unsigned char* lds, const Gemm g, const Sched& S, const Epi& E, const int wave_id) {
;     ...
;         const bool has_next = S.next(ui + 1, nxt);
;         const char* nA = has_next ? (const char*)g.A + (size_t)nxt.lm * tstep : cA; const char* nB = has_next ? (const char*)g.Bt + (size_t)nxt.ln * tstep : cB;
; #pragma unroll 1
;         for (int t = 0; t < nt; t += 2) {
;             const bool last = (t == nt - 2);
;             const char* a1 = cA + (size_t)(t + 1) * kstep;
;             const char* a2 = last ? nA : cA + (size_t)(t + 2) * kstep; const char* b2 = last ? nB : cB + (size_t)(t + 2) * kstep;
;             const char* a3 = a2 + kstep; const char* b3 = b2 + kstep;
;             if (last && has_next) S.a_ready(nxt);
;             if constexpr (SP2) {
;             PG8_LDB(B0, 0, 0); PG8_LDB(B1, 0, 1); PG8_SCHED; PG8_LDA(At, 0, 0); PG8_STAGE(PG8_SA(1, 1), a1 + hstep, voffA);
;             PG8_WAIT_V(8); PG8_WAIT_L(0); PG8_BAR; PG8_MMA(0, 0, At, B0); PG8_MMA(0, 1, At, B1); PG8_BAR; PG8_SCHED;
;             PG8_LDA(At, 0, 1); PG8_STAGE(PG8_SB(0, 0), b2, voffB); PG8_STAGE(PG8_SB(0, 1), b2 + hstep, voffB); PG8_STAGE(PG8_SA(0, 0), a2, voffA);
;             PG8_WAIT_V(8); PG8_WAIT_L(0); PG8_BAR; PG8_MMA(1, 0, At, B0); PG8_MMA(1, 1, At, B1); PG8_BAR; PG8_SCHED;
.LBB0_798:
	s_ashr_i32 s19, s18, 31
	s_lshl_b64 s[20:21], s[18:19], 17
	s_add_u32 s20, s56, s20
	s_addc_u32 s21, s57, s21
	s_and_b64 s[38:39], s[36:37], exec
	s_cselect_b32 s19, s21, s15
	s_cselect_b32 s77, s20, s14
	s_ashr_i32 s17, s16, 31
	s_lshl_b64 s[38:39], s[16:17], 17
	s_add_u32 s38, s64, s38
	s_addc_u32 s39, s65, s39
	s_and_b64 s[40:41], s[36:37], exec
	s_cselect_b32 s17, s39, s13
	s_cselect_b32 s79, s38, s12
	s_mov_b64 s[44:45], 0
	s_mov_b64 s[40:41], -1
	s_mov_b64 s[42:43], 0
	s_add_u32 s52, s14, s44
	s_addc_u32 s53, s15, s45
	s_add_u32 s48, s52, 0x100
	s_addc_u32 s49, s53, 0
	s_and_b64 s[46:47], s[42:43], exec
	s_cselect_b32 s47, s19, s49
	s_cselect_b32 s46, s77, s48
	s_add_u32 s44, s12, s44
	s_addc_u32 s45, s13, s45
	s_add_u32 s44, s44, 0x100
	s_addc_u32 s45, s45, 0
	s_add_i32 s96, 0, 0x10000
	s_and_b64 s[42:43], s[42:43], exec
	s_cselect_b32 s49, s17, s45
	s_cselect_b32 s48, s79, s44
	s_add_i32 s43, 0, 0x14000
	s_add_u32 s82, s52, 0x10080
	s_addc_u32 s83, s53, 0
	s_add_i32 s93, s96, s68
	s_add_i32 m0, s69, 0xc000
	s_add_i32 vcc_lo, s69, 0xe000
	s_add_i32 s88, s93, 0x2000
	v_add_u32_e32 v141, s96, v138
	s_add_u32 s52, s48, 0x10000
	ds_read_b128 v[142:145], v141
	ds_read_b128 v[146:149], v141 offset:1024
	ds_read_b128 v[150:153], v141 offset:2048
	ds_read_b128 v[154:157], v141 offset:3072
	v_add_u32_e32 v141, s43, v138
	s_addc_u32 s53, s49, 0
	s_add_i32 s92, s43, s68
	ds_read_b128 v[158:161], v141
	ds_read_b128 v[162:165], v141 offset:1024
	ds_read_b128 v[166:169], v141 offset:2048
	ds_read_b128 v[170:173], v141 offset:3072
	s_add_i32 s89, s92, 0x2000
	s_add_i32 s85, 0, 0x18000
	s_add_i32 s84, 0, 0x1c000
	s_add_u32 s44, s46, 0x10000
	s_addc_u32 s45, s47, 0
	s_add_i32 s81, s85, s68
	s_add_i32 s80, s81, 0x2000
	s_add_u32 s42, s48, 0x10080
	s_addc_u32 s43, s49, 0
	s_add_i32 s97, s84, s68
	s_add_i32 s96, s97, 0x2000
	v_lshl_add_u64 v[226:227], s[82:83], 0, v[130:131]
	ds_read_b128 v[174:177], v140
	ds_read_b128 v[178:181], v140 offset:1024
	ds_read_b128 v[182:185], v140 offset:2048
	ds_read_b128 v[186:189], v140 offset:3072
	ds_read_b128 v[190:193], v140 offset:4096
	ds_read_b128 v[206:209], v140 offset:5120
	ds_read_b128 v[210:213], v140 offset:6144
	ds_read_b128 v[214:217], v140 offset:7168
	global_load_lds_dwordx4 v[226:227], off
	v_lshl_add_u64 v[226:227], s[82:83], 0, v[134:135]
	s_mov_b32 m0, vcc_lo
	s_nop 0
	global_load_lds_dwordx4 v[226:227], off
	s_waitcnt lgkmcnt(0)
	s_setprio 1
	v_mfma_f32_16x16x32_bf16 v[126:129], v[142:145], v[174:177], 0
	v_mfma_f32_16x16x32_bf16 v[122:125], v[150:153], v[174:177], 0
	v_mfma_f32_16x16x32_bf16 v[118:121], v[142:145], v[182:185], 0
	v_mfma_f32_16x16x32_bf16 v[114:117], v[150:153], v[182:185], 0
	s_waitcnt vmcnt(8)
	s_barrier
	v_mfma_f32_16x16x32_bf16 v[102:105], v[142:145], v[190:193], 0
	v_mfma_f32_16x16x32_bf16 v[98:101], v[150:153], v[190:193], 0
	v_mfma_f32_16x16x32_bf16 v[86:89], v[142:145], v[210:213], 0
	v_mfma_f32_16x16x32_bf16 v[82:85], v[150:153], v[210:213], 0
	v_mfma_f32_16x16x32_bf16 v[126:129], v[146:149], v[178:181], v[126:129]
	v_mfma_f32_16x16x32_bf16 v[122:125], v[154:157], v[178:181], v[122:125]
	v_mfma_f32_16x16x32_bf16 v[118:121], v[146:149], v[186:189], v[118:121]
	v_mfma_f32_16x16x32_bf16 v[114:117], v[154:157], v[186:189], v[114:117]
	v_mfma_f32_16x16x32_bf16 v[102:105], v[146:149], v[206:209], v[102:105]
	v_mfma_f32_16x16x32_bf16 v[98:101], v[154:157], v[206:209], v[98:101]
	v_mfma_f32_16x16x32_bf16 v[86:89], v[146:149], v[214:217], v[86:89]
	v_mfma_f32_16x16x32_bf16 v[82:85], v[154:157], v[214:217], v[82:85]
	s_setprio 0
	s_setprio 1
	v_mfma_f32_16x16x32_bf16 v[110:113], v[158:161], v[174:177], 0
	v_mfma_f32_16x16x32_bf16 v[106:109], v[166:169], v[174:177], 0
	v_mfma_f32_16x16x32_bf16 v[94:97], v[158:161], v[182:185], 0
	v_mfma_f32_16x16x32_bf16 v[90:93], v[166:169], v[182:185], 0
	v_mfma_f32_16x16x32_bf16 v[78:81], v[158:161], v[190:193], 0
	v_mfma_f32_16x16x32_bf16 v[74:77], v[166:169], v[190:193], 0
	v_mfma_f32_16x16x32_bf16 v[70:73], v[158:161], v[210:213], 0
	v_mfma_f32_16x16x32_bf16 v[66:69], v[166:169], v[210:213], 0
	v_mfma_f32_16x16x32_bf16 v[110:113], v[162:165], v[178:181], v[110:113]
	v_mfma_f32_16x16x32_bf16 v[106:109], v[170:173], v[178:181], v[106:109]
	v_mfma_f32_16x16x32_bf16 v[94:97], v[162:165], v[186:189], v[94:97]
	v_mfma_f32_16x16x32_bf16 v[90:93], v[170:173], v[186:189], v[90:93]
	v_mfma_f32_16x16x32_bf16 v[78:81], v[162:165], v[206:209], v[78:81]
	v_mfma_f32_16x16x32_bf16 v[74:77], v[170:173], v[206:209], v[74:77]
	v_mfma_f32_16x16x32_bf16 v[70:73], v[162:165], v[214:217], v[70:73]
	v_mfma_f32_16x16x32_bf16 v[66:69], v[170:173], v[214:217], v[66:69]
	s_setprio 0
	s_barrier
	s_mov_b32 m0, s93
	v_lshl_add_u64 v[226:227], s[48:49], 0, v[132:133]
	ds_read_b128 v[174:177], v140 offset:16384
	ds_read_b128 v[178:181], v140 offset:17408
	ds_read_b128 v[182:185], v140 offset:18432
	ds_read_b128 v[186:189], v140 offset:19456
	ds_read_b128 v[190:193], v140 offset:20480
	ds_read_b128 v[206:209], v140 offset:21504
	ds_read_b128 v[210:213], v140 offset:22528
	ds_read_b128 v[214:217], v140 offset:23552
	global_load_lds_dwordx4 v[226:227], off
	v_lshl_add_u64 v[228:229], s[48:49], 0, v[136:137]
	s_mov_b32 m0, s88
	v_lshl_add_u64 v[230:231], s[52:53], 0, v[132:133]
	global_load_lds_dwordx4 v[228:229], off
	s_mov_b32 m0, s92
	v_lshl_add_u64 v[234:235], s[46:47], 0, v[134:135]
	global_load_lds_dwordx4 v[230:231], off
	v_lshl_add_u64 v[230:231], s[52:53], 0, v[136:137]
	s_mov_b32 m0, s89
	s_nop 0
	global_load_lds_dwordx4 v[230:231], off
	v_lshl_add_u64 v[230:231], s[46:47], 0, v[130:131]
	s_mov_b32 m0, s69
	s_nop 0
	global_load_lds_dwordx4 v[230:231], off
	s_mov_b32 m0, s70
	s_nop 0
	global_load_lds_dwordx4 v[234:235], off
	s_waitcnt lgkmcnt(0)
	s_setprio 1
	v_mfma_f32_16x16x32_bf16 v[62:65], v[142:145], v[174:177], 0
	v_mfma_f32_16x16x32_bf16 v[58:61], v[150:153], v[174:177], 0
	v_mfma_f32_16x16x32_bf16 v[54:57], v[142:145], v[182:185], 0
	v_mfma_f32_16x16x32_bf16 v[50:53], v[150:153], v[182:185], 0
	s_waitcnt vmcnt(8)
	s_barrier
; #define PG8_STAGE(bufoff, gbase, voff) do { _Pragma("unroll") for (int _i = 0; _i < 2; ++_i) \
;         __builtin_amdgcn_global_load_lds((const unsigned*)((const char*)(gbase) + (voff)[_i]), (PG8_LAS unsigned*)(lds + (bufoff) + ldsw + _i * 8192), 16, 0, 0); } while (0)
; #define PG8_LDA(dst, b, h) do { _Pragma("unroll") for (int m = 0; m < 4; ++m) _Pragma("unroll") for (int k = 0; k < 2; ++k) dst[m][k] = *(const PG8_LAS bf16x8*)(lds + PG8_SA(b, h) + aoff + m * 2048 + k * 1024); } while (0)
; #define PG8_LDB(dst, b, h) do { _Pragma("unroll") for (int n = 0; n < 2; ++n) _Pragma("unroll") for (int k = 0; k < 2; ++k) dst[n][k] = *(const PG8_LAS bf16x8*)(lds + PG8_SB(b, h) + boff + n * 2048 + k * 1024); } while (0)
; #define PG8_MMA(ai, bj, At, Bt) do { __builtin_amdgcn_s_setprio(1); _Pragma("unroll") for (int m = 0; m < 4; ++m) _Pragma("unroll") for (int n = 0; n < 2; ++n) _Pragma("unroll") for (int k = 0; k < 2; ++k) \
;         acc[ai][bj][m][n] = __builtin_amdgcn_mfma_f32_16x16x32_bf16(Bt[n][k], At[m][k], acc[ai][bj][m][n], 0, 0, 0); __builtin_amdgcn_s_setprio(0); } while (0)
; #define PG8_WAIT_V(n) asm volatile("s_waitcnt vmcnt(" #n ")" ::: "memory")
; #define PG8_WAIT_L(n) asm volatile("s_waitcnt lgkmcnt(" #n ")" ::: "memory")
; #define PG8_BAR __builtin_amdgcn_s_barrier()
; #define PG8_SCHED __builtin_amdgcn_sched_barrier(0)
; template <class Epi, class Sched, bool ALIGN_EPI = false, bool SP2 = false>
; __device__ __forceinline__ void gemm_phase(PG8_LAS unsigned char* lds, const Gemm g, const Sched& S, const Epi& E, const int wave_id) {
;     ...
;             PG8_WAIT_V(8); PG8_WAIT_L(0); PG8_BAR; PG8_MMA(1, 0, At, B0); PG8_MMA(1, 1, At, B1); PG8_BAR; PG8_SCHED;
;             PG8_LDB(B0, 1, 0); PG8_LDB(B1, 1, 1); PG8_SCHED; PG8_LDA(At, 1, 0); PG8_STAGE(PG8_SA(0, 1), a2 + hstep, voffA);
;             PG8_WAIT_V(8); PG8_WAIT_L(0); PG8_BAR; PG8_MMA(0, 0, At, B0); PG8_MMA(0, 1, At, B1); PG8_BAR; PG8_SCHED;
	v_mfma_f32_16x16x32_bf16 v[38:41], v[142:145], v[190:193], 0
	v_mfma_f32_16x16x32_bf16 v[34:37], v[150:153], v[190:193], 0
	v_mfma_f32_16x16x32_bf16 v[22:25], v[142:145], v[210:213], 0
	v_mfma_f32_16x16x32_bf16 v[18:21], v[150:153], v[210:213], 0
	v_mfma_f32_16x16x32_bf16 v[62:65], v[146:149], v[178:181], v[62:65]
	v_mfma_f32_16x16x32_bf16 v[58:61], v[154:157], v[178:181], v[58:61]
	v_mfma_f32_16x16x32_bf16 v[54:57], v[146:149], v[186:189], v[54:57]
	v_mfma_f32_16x16x32_bf16 v[50:53], v[154:157], v[186:189], v[50:53]
	v_mfma_f32_16x16x32_bf16 v[38:41], v[146:149], v[206:209], v[38:41]
	v_mfma_f32_16x16x32_bf16 v[34:37], v[154:157], v[206:209], v[34:37]
	v_mfma_f32_16x16x32_bf16 v[22:25], v[146:149], v[214:217], v[22:25]
	v_mfma_f32_16x16x32_bf16 v[18:21], v[154:157], v[214:217], v[18:21]
	s_setprio 0
	s_setprio 1
	v_mfma_f32_16x16x32_bf16 v[46:49], v[158:161], v[174:177], 0
	v_mfma_f32_16x16x32_bf16 v[42:45], v[166:169], v[174:177], 0
	v_mfma_f32_16x16x32_bf16 v[30:33], v[158:161], v[182:185], 0
	v_mfma_f32_16x16x32_bf16 v[26:29], v[166:169], v[182:185], 0
	v_mfma_f32_16x16x32_bf16 v[14:17], v[158:161], v[190:193], 0
	v_mfma_f32_16x16x32_bf16 v[10:13], v[166:169], v[190:193], 0
	v_mfma_f32_16x16x32_bf16 v[6:9], v[158:161], v[210:213], 0
	v_mfma_f32_16x16x32_bf16 v[2:5], v[166:169], v[210:213], 0
	v_mfma_f32_16x16x32_bf16 v[46:49], v[162:165], v[178:181], v[46:49]
	v_mfma_f32_16x16x32_bf16 v[42:45], v[170:173], v[178:181], v[42:45]
	v_mfma_f32_16x16x32_bf16 v[30:33], v[162:165], v[186:189], v[30:33]
	v_mfma_f32_16x16x32_bf16 v[26:29], v[170:173], v[186:189], v[26:29]
	v_mfma_f32_16x16x32_bf16 v[14:17], v[162:165], v[206:209], v[14:17]
	v_mfma_f32_16x16x32_bf16 v[10:13], v[170:173], v[206:209], v[10:13]
	v_mfma_f32_16x16x32_bf16 v[6:9], v[162:165], v[214:217], v[6:9]
	v_mfma_f32_16x16x32_bf16 v[2:5], v[170:173], v[214:217], v[2:5]
	s_setprio 0
	s_barrier
	v_add_u32_e32 v141, s85, v138
	ds_read_b128 v[142:145], v141
	ds_read_b128 v[146:149], v141 offset:1024
	ds_read_b128 v[150:153], v141 offset:2048
	ds_read_b128 v[154:157], v141 offset:3072
	v_add_u32_e32 v141, s84, v138
	ds_read_b128 v[158:161], v141
	ds_read_b128 v[162:165], v141 offset:1024
	ds_read_b128 v[166:169], v141 offset:2048
	ds_read_b128 v[170:173], v141 offset:3072
	s_mov_b32 m0, s71
	v_lshl_add_u64 v[236:237], s[44:45], 0, v[130:131]
	ds_read_b128 v[174:177], v140 offset:32768
	ds_read_b128 v[178:181], v140 offset:33792
	ds_read_b128 v[182:185], v140 offset:34816
	ds_read_b128 v[186:189], v140 offset:35840
	ds_read_b128 v[190:193], v140 offset:36864
	ds_read_b128 v[206:209], v140 offset:37888
	ds_read_b128 v[210:213], v140 offset:38912
	ds_read_b128 v[214:217], v140 offset:39936
	global_load_lds_dwordx4 v[236:237], off
	v_lshl_add_u64 v[236:237], s[44:45], 0, v[134:135]
	s_mov_b32 m0, s72
	s_nop 0
	global_load_lds_dwordx4 v[236:237], off
	s_waitcnt lgkmcnt(0)
	s_setprio 1
	v_mfma_f32_16x16x32_bf16 v[126:129], v[142:145], v[174:177], v[126:129]
	v_mfma_f32_16x16x32_bf16 v[122:125], v[150:153], v[174:177], v[122:125]
	v_mfma_f32_16x16x32_bf16 v[118:121], v[142:145], v[182:185], v[118:121]
	v_mfma_f32_16x16x32_bf16 v[114:117], v[150:153], v[182:185], v[114:117]
	s_waitcnt vmcnt(8)
	s_barrier
	v_mfma_f32_16x16x32_bf16 v[102:105], v[142:145], v[190:193], v[102:105]
	v_mfma_f32_16x16x32_bf16 v[98:101], v[150:153], v[190:193], v[98:101]
	v_mfma_f32_16x16x32_bf16 v[86:89], v[142:145], v[210:213], v[86:89]
	v_mfma_f32_16x16x32_bf16 v[82:85], v[150:153], v[210:213], v[82:85]
	v_mfma_f32_16x16x32_bf16 v[126:129], v[146:149], v[178:181], v[126:129]
	v_mfma_f32_16x16x32_bf16 v[122:125], v[154:157], v[178:181], v[122:125]
	v_mfma_f32_16x16x32_bf16 v[118:121], v[146:149], v[186:189], v[118:121]
	v_mfma_f32_16x16x32_bf16 v[114:117], v[154:157], v[186:189], v[114:117]
	v_mfma_f32_16x16x32_bf16 v[102:105], v[146:149], v[206:209], v[102:105]
	v_mfma_f32_16x16x32_bf16 v[98:101], v[154:157], v[206:209], v[98:101]
	v_mfma_f32_16x16x32_bf16 v[86:89], v[146:149], v[214:217], v[86:89]
	v_mfma_f32_16x16x32_bf16 v[82:85], v[154:157], v[214:217], v[82:85]
	s_setprio 0
	s_setprio 1
	v_mfma_f32_16x16x32_bf16 v[110:113], v[158:161], v[174:177], v[110:113]
	v_mfma_f32_16x16x32_bf16 v[106:109], v[166:169], v[174:177], v[106:109]
	v_mfma_f32_16x16x32_bf16 v[94:97], v[158:161], v[182:185], v[94:97]
	v_mfma_f32_16x16x32_bf16 v[90:93], v[166:169], v[182:185], v[90:93]
	v_mfma_f32_16x16x32_bf16 v[78:81], v[158:161], v[190:193], v[78:81]
	v_mfma_f32_16x16x32_bf16 v[74:77], v[166:169], v[190:193], v[74:77]
	v_mfma_f32_16x16x32_bf16 v[70:73], v[158:161], v[210:213], v[70:73]
	v_mfma_f32_16x16x32_bf16 v[66:69], v[166:169], v[210:213], v[66:69]
	v_mfma_f32_16x16x32_bf16 v[110:113], v[162:165], v[178:181], v[110:113]
	v_mfma_f32_16x16x32_bf16 v[106:109], v[170:173], v[178:181], v[106:109]
	v_mfma_f32_16x16x32_bf16 v[94:97], v[162:165], v[186:189], v[94:97]
	v_mfma_f32_16x16x32_bf16 v[90:93], v[170:173], v[186:189], v[90:93]
	v_mfma_f32_16x16x32_bf16 v[78:81], v[162:165], v[206:209], v[78:81]
	v_mfma_f32_16x16x32_bf16 v[74:77], v[170:173], v[206:209], v[74:77]
	v_mfma_f32_16x16x32_bf16 v[70:73], v[162:165], v[214:217], v[70:73]
	v_mfma_f32_16x16x32_bf16 v[66:69], v[170:173], v[214:217], v[66:69]
	s_setprio 0
	s_barrier
; #define PG8_STAGE(bufoff, gbase, voff) do { _Pragma("unroll") for (int _i = 0; _i < 2; ++_i) \
;         __builtin_amdgcn_global_load_lds((const unsigned*)((const char*)(gbase) + (voff)[_i]), (PG8_LAS unsigned*)(lds + (bufoff) + ldsw + _i * 8192), 16, 0, 0); } while (0)
; #define PG8_LDA(dst, b, h) do { _Pragma("unroll") for (int m = 0; m < 4; ++m) _Pragma("unroll") for (int k = 0; k < 2; ++k) dst[m][k] = *(const PG8_LAS bf16x8*)(lds + PG8_SA(b, h) + aoff + m * 2048 + k * 1024); } while (0)
; #define PG8_WAIT_V(n) asm volatile("s_waitcnt vmcnt(" #n ")" ::: "memory")
; #define PG8_WAIT_L(n) asm volatile("s_waitcnt lgkmcnt(" #n ")" ::: "memory")
; #define PG8_BAR __builtin_amdgcn_s_barrier()
; template <class Epi, class Sched, bool ALIGN_EPI = false, bool SP2 = false>
; __device__ __forceinline__ void gemm_phase(PG8_LAS unsigned char* lds, const Gemm g, const Sched& S, const Epi& E, const int wave_id) {
;     ...
;         for (int t = 0; t < nt; t += 2) {
;             const bool last = (t == nt - 2);
;             const char* a1 = cA + (size_t)(t + 1) * kstep;
;             const char* a2 = last ? nA : cA + (size_t)(t + 2) * kstep; const char* b2 = last ? nB : cB + (size_t)(t + 2) * kstep;
;             const char* a3 = a2 + kstep; const char* b3 = b2 + kstep;
;             if (last && has_next) S.a_ready(nxt);
;             if constexpr (SP2) {
;             PG8_LDB(B0, 0, 0); PG8_LDB(B1, 0, 1); PG8_SCHED; PG8_LDA(At, 0, 0); PG8_STAGE(PG8_SA(1, 1), a1 + hstep, voffA);
;             PG8_WAIT_V(8); PG8_WAIT_L(0); PG8_BAR; PG8_MMA(0, 0, At, B0); PG8_MMA(0, 1, At, B1); PG8_BAR; PG8_SCHED;
;             PG8_LDA(At, 0, 1); PG8_STAGE(PG8_SB(0, 0), b2, voffB); PG8_STAGE(PG8_SB(0, 1), b2 + hstep, voffB); PG8_STAGE(PG8_SA(0, 0), a2, voffA);
;             PG8_WAIT_V(8); PG8_WAIT_L(0); PG8_BAR; PG8_MMA(1, 0, At, B0); PG8_MMA(1, 1, At, B1); PG8_BAR; PG8_SCHED;
;             PG8_LDB(B0, 1, 0); PG8_LDB(B1, 1, 1); PG8_SCHED; PG8_LDA(At, 1, 0); PG8_STAGE(PG8_SA(0, 1), a2 + hstep, voffA);
;             PG8_WAIT_V(8); PG8_WAIT_L(0); PG8_BAR; PG8_MMA(0, 0, At, B0); PG8_MMA(0, 1, At, B1); PG8_BAR; PG8_SCHED;
;             PG8_LDA(At, 1, 1); PG8_STAGE(PG8_SB(1, 0), b3, voffB); PG8_STAGE(PG8_SB(1, 1), b3 + hstep, voffB); PG8_STAGE(PG8_SA(1, 0), a3, voffA);
;             PG8_WAIT_V(8); PG8_WAIT_L(0); PG8_BAR; PG8_MMA(1, 0, At, B0); PG8_MMA(1, 1, At, B1); PG8_BAR; PG8_SCHED;
	s_mov_b32 m0, s81
	v_lshl_add_u64 v[226:227], v[226:227], 0, s[30:31]
	ds_read_b128 v[174:177], v140 offset:49152
	ds_read_b128 v[178:181], v140 offset:50176
	ds_read_b128 v[182:185], v140 offset:51200
	ds_read_b128 v[186:189], v140 offset:52224
	ds_read_b128 v[190:193], v140 offset:53248
	ds_read_b128 v[206:209], v140 offset:54272
	ds_read_b128 v[210:213], v140 offset:55296
	ds_read_b128 v[214:217], v140 offset:56320
	global_load_lds_dwordx4 v[226:227], off
	v_lshl_add_u64 v[226:227], v[228:229], 0, s[30:31]
	s_mov_b32 m0, s80
	s_nop 0
	global_load_lds_dwordx4 v[226:227], off
	v_lshl_add_u64 v[226:227], s[42:43], 0, v[132:133]
	s_mov_b32 m0, s97
	s_nop 0
	global_load_lds_dwordx4 v[226:227], off
	v_lshl_add_u64 v[226:227], s[42:43], 0, v[136:137]
	s_mov_b32 m0, s96
	s_nop 0
	global_load_lds_dwordx4 v[226:227], off
	v_lshl_add_u64 v[226:227], v[230:231], 0, s[30:31]
	s_mov_b32 m0, s73
	s_nop 0
	global_load_lds_dwordx4 v[226:227], off
	v_lshl_add_u64 v[226:227], v[234:235], 0, s[30:31]
	s_mov_b32 m0, s74
	s_nop 0
	global_load_lds_dwordx4 v[226:227], off
	s_waitcnt lgkmcnt(0)
	s_setprio 1
	v_mfma_f32_16x16x32_bf16 v[62:65], v[142:145], v[174:177], v[62:65]
	v_mfma_f32_16x16x32_bf16 v[58:61], v[150:153], v[174:177], v[58:61]
	v_mfma_f32_16x16x32_bf16 v[54:57], v[142:145], v[182:185], v[54:57]
	v_mfma_f32_16x16x32_bf16 v[50:53], v[150:153], v[182:185], v[50:53]
	s_waitcnt vmcnt(8)
	s_barrier
	v_mfma_f32_16x16x32_bf16 v[38:41], v[142:145], v[190:193], v[38:41]
	v_mfma_f32_16x16x32_bf16 v[34:37], v[150:153], v[190:193], v[34:37]
	v_mfma_f32_16x16x32_bf16 v[22:25], v[142:145], v[210:213], v[22:25]
	v_mfma_f32_16x16x32_bf16 v[18:21], v[150:153], v[210:213], v[18:21]
	v_mfma_f32_16x16x32_bf16 v[62:65], v[146:149], v[178:181], v[62:65]
	v_mfma_f32_16x16x32_bf16 v[58:61], v[154:157], v[178:181], v[58:61]
	v_mfma_f32_16x16x32_bf16 v[54:57], v[146:149], v[186:189], v[54:57]
	v_mfma_f32_16x16x32_bf16 v[50:53], v[154:157], v[186:189], v[50:53]
	v_mfma_f32_16x16x32_bf16 v[38:41], v[146:149], v[206:209], v[38:41]
	v_mfma_f32_16x16x32_bf16 v[34:37], v[154:157], v[206:209], v[34:37]
	v_mfma_f32_16x16x32_bf16 v[22:25], v[146:149], v[214:217], v[22:25]
	v_mfma_f32_16x16x32_bf16 v[18:21], v[154:157], v[214:217], v[18:21]
	s_setprio 0
	s_setprio 1
	v_mfma_f32_16x16x32_bf16 v[46:49], v[158:161], v[174:177], v[46:49]
	v_mfma_f32_16x16x32_bf16 v[42:45], v[166:169], v[174:177], v[42:45]
	v_mfma_f32_16x16x32_bf16 v[30:33], v[158:161], v[182:185], v[30:33]
	v_mfma_f32_16x16x32_bf16 v[26:29], v[166:169], v[182:185], v[26:29]
	v_mfma_f32_16x16x32_bf16 v[14:17], v[158:161], v[190:193], v[14:17]
	v_mfma_f32_16x16x32_bf16 v[10:13], v[166:169], v[190:193], v[10:13]
	v_mfma_f32_16x16x32_bf16 v[6:9], v[158:161], v[210:213], v[6:9]
	v_mfma_f32_16x16x32_bf16 v[2:5], v[166:169], v[210:213], v[2:5]
	v_mfma_f32_16x16x32_bf16 v[46:49], v[162:165], v[178:181], v[46:49]
	v_mfma_f32_16x16x32_bf16 v[42:45], v[170:173], v[178:181], v[42:45]
	v_mfma_f32_16x16x32_bf16 v[30:33], v[162:165], v[186:189], v[30:33]
	v_mfma_f32_16x16x32_bf16 v[26:29], v[170:173], v[186:189], v[26:29]
	v_mfma_f32_16x16x32_bf16 v[14:17], v[162:165], v[206:209], v[14:17]
	v_mfma_f32_16x16x32_bf16 v[10:13], v[170:173], v[206:209], v[10:13]
	v_mfma_f32_16x16x32_bf16 v[6:9], v[162:165], v[214:217], v[6:9]
	v_mfma_f32_16x16x32_bf16 v[2:5], v[170:173], v[214:217], v[2:5]
	s_setprio 0
	s_barrier
	s_andn2_b64 vcc, exec, s[40:41]
	s_mov_b64 s[42:43], -1
	s_mov_b64 s[40:41], 0
	s_mov_b64 s[44:45], 0x100
	s_cbranch_vccnz .Lpeel_exit_pp
.LBB0_799:
	s_add_u32 s52, s14, s44
	s_addc_u32 s53, s15, s45
	s_add_u32 s48, s52, 0x100
	s_addc_u32 s49, s53, 0
	s_and_b64 s[46:47], s[42:43], exec
	s_cselect_b32 s47, s19, s49
	s_cselect_b32 s46, s77, s48
	s_add_u32 s44, s12, s44
	s_addc_u32 s45, s13, s45
	s_add_u32 s44, s44, 0x100
	s_addc_u32 s45, s45, 0
	s_add_i32 s96, 0, 0x10000
	s_and_b64 s[42:43], s[42:43], exec
	s_cselect_b32 s49, s17, s45
	s_cselect_b32 s48, s79, s44
	s_add_i32 s43, 0, 0x14000
	s_add_u32 s82, s52, 0x10080
	s_addc_u32 s83, s53, 0
	s_add_i32 s93, s96, s68
	s_add_i32 m0, s69, 0xc000
	s_add_i32 vcc_lo, s69, 0xe000
	s_add_i32 s88, s93, 0x2000
	v_add_u32_e32 v141, s96, v138
	s_add_u32 s52, s48, 0x10000
	ds_read_b128 v[142:145], v141
	ds_read_b128 v[146:149], v141 offset:1024
	ds_read_b128 v[150:153], v141 offset:2048
	ds_read_b128 v[154:157], v141 offset:3072
	v_add_u32_e32 v141, s43, v138
	s_addc_u32 s53, s49, 0
	s_add_i32 s92, s43, s68
	ds_read_b128 v[158:161], v141
	ds_read_b128 v[162:165], v141 offset:1024
	ds_read_b128 v[166:169], v141 offset:2048
	ds_read_b128 v[170:173], v141 offset:3072
	s_add_i32 s89, s92, 0x2000
	s_add_i32 s85, 0, 0x18000
	s_add_i32 s84, 0, 0x1c000
	s_add_u32 s44, s46, 0x10000
	s_addc_u32 s45, s47, 0
	s_add_i32 s81, s85, s68
	s_add_i32 s80, s81, 0x2000
	s_add_u32 s42, s48, 0x10080
	s_addc_u32 s43, s49, 0
	s_add_i32 s97, s84, s68
	s_add_i32 s96, s97, 0x2000
	v_lshl_add_u64 v[226:227], s[82:83], 0, v[130:131]
	ds_read_b128 v[174:177], v140
	ds_read_b128 v[178:181], v140 offset:1024
	ds_read_b128 v[182:185], v140 offset:2048
	ds_read_b128 v[186:189], v140 offset:3072
	ds_read_b128 v[190:193], v140 offset:4096
	ds_read_b128 v[206:209], v140 offset:5120
	ds_read_b128 v[210:213], v140 offset:6144
	ds_read_b128 v[214:217], v140 offset:7168
	global_load_lds_dwordx4 v[226:227], off
	v_lshl_add_u64 v[226:227], s[82:83], 0, v[134:135]
	s_mov_b32 m0, vcc_lo
	s_nop 0
	global_load_lds_dwordx4 v[226:227], off
	s_waitcnt lgkmcnt(0)
	s_setprio 1
	v_mfma_f32_16x16x32_bf16 v[126:129], v[142:145], v[174:177], v[126:129]
	v_mfma_f32_16x16x32_bf16 v[122:125], v[150:153], v[174:177], v[122:125]
	v_mfma_f32_16x16x32_bf16 v[118:121], v[142:145], v[182:185], v[118:121]
	v_mfma_f32_16x16x32_bf16 v[114:117], v[150:153], v[182:185], v[114:117]
	s_waitcnt vmcnt(8)
	s_barrier
; #define PG8_STAGE(bufoff, gbase, voff) do { _Pragma("unroll") for (int _i = 0; _i < 2; ++_i) \
;         __builtin_amdgcn_global_load_lds((const unsigned*)((const char*)(gbase) + (voff)[_i]), (PG8_LAS unsigned*)(lds + (bufoff) + ldsw + _i * 8192), 16, 0, 0); } while (0)
; #define PG8_LDA(dst, b, h) do { _Pragma("unroll") for (int m = 0; m < 4; ++m) _Pragma("unroll") for (int k = 0; k < 2; ++k) dst[m][k] = *(const PG8_LAS bf16x8*)(lds + PG8_SA(b, h) + aoff + m * 2048 + k * 1024); } while (0)
; #define PG8_LDB(dst, b, h) do { _Pragma("unroll") for (int n = 0; n < 2; ++n) _Pragma("unroll") for (int k = 0; k < 2; ++k) dst[n][k] = *(const PG8_LAS bf16x8*)(lds + PG8_SB(b, h) + boff + n * 2048 + k * 1024); } while (0)
; #define PG8_MMA(ai, bj, At, Bt) do { __builtin_amdgcn_s_setprio(1); _Pragma("unroll") for (int m = 0; m < 4; ++m) _Pragma("unroll") for (int n = 0; n < 2; ++n) _Pragma("unroll") for (int k = 0; k < 2; ++k) \
;         acc[ai][bj][m][n] = __builtin_amdgcn_mfma_f32_16x16x32_bf16(Bt[n][k], At[m][k], acc[ai][bj][m][n], 0, 0, 0); __builtin_amdgcn_s_setprio(0); } while (0)
; #define PG8_WAIT_V(n) asm volatile("s_waitcnt vmcnt(" #n ")" ::: "memory")
; #define PG8_WAIT_L(n) asm volatile("s_waitcnt lgkmcnt(" #n ")" ::: "memory")
; #define PG8_BAR __builtin_amdgcn_s_barrier()
; #define PG8_SCHED __builtin_amdgcn_sched_barrier(0)
; template <class Epi, class Sched, bool ALIGN_EPI = false, bool SP2 = false>
; __device__ __forceinline__ void gemm_phase(PG8_LAS unsigned char* lds, const Gemm g, const Sched& S, const Epi& E, const int wave_id) {
;     ...
;             PG8_WAIT_V(8); PG8_WAIT_L(0); PG8_BAR; PG8_MMA(0, 0, At, B0); PG8_MMA(0, 1, At, B1); PG8_BAR; PG8_SCHED;
;             PG8_LDA(At, 0, 1); PG8_STAGE(PG8_SB(0, 0), b2, voffB); PG8_STAGE(PG8_SB(0, 1), b2 + hstep, voffB); PG8_STAGE(PG8_SA(0, 0), a2, voffA);
;             PG8_WAIT_V(8); PG8_WAIT_L(0); PG8_BAR; PG8_MMA(1, 0, At, B0); PG8_MMA(1, 1, At, B1); PG8_BAR; PG8_SCHED;
;             PG8_LDB(B0, 1, 0); PG8_LDB(B1, 1, 1); PG8_SCHED; PG8_LDA(At, 1, 0); PG8_STAGE(PG8_SA(0, 1), a2 + hstep, voffA);
;             PG8_WAIT_V(8); PG8_WAIT_L(0); PG8_BAR; PG8_MMA(0, 0, At, B0); PG8_MMA(0, 1, At, B1); PG8_BAR; PG8_SCHED;
	v_mfma_f32_16x16x32_bf16 v[102:105], v[142:145], v[190:193], v[102:105]
	v_mfma_f32_16x16x32_bf16 v[98:101], v[150:153], v[190:193], v[98:101]
	v_mfma_f32_16x16x32_bf16 v[86:89], v[142:145], v[210:213], v[86:89]
	v_mfma_f32_16x16x32_bf16 v[82:85], v[150:153], v[210:213], v[82:85]
	v_mfma_f32_16x16x32_bf16 v[126:129], v[146:149], v[178:181], v[126:129]
	v_mfma_f32_16x16x32_bf16 v[122:125], v[154:157], v[178:181], v[122:125]
	v_mfma_f32_16x16x32_bf16 v[118:121], v[146:149], v[186:189], v[118:121]
	v_mfma_f32_16x16x32_bf16 v[114:117], v[154:157], v[186:189], v[114:117]
	v_mfma_f32_16x16x32_bf16 v[102:105], v[146:149], v[206:209], v[102:105]
	v_mfma_f32_16x16x32_bf16 v[98:101], v[154:157], v[206:209], v[98:101]
	v_mfma_f32_16x16x32_bf16 v[86:89], v[146:149], v[214:217], v[86:89]
	v_mfma_f32_16x16x32_bf16 v[82:85], v[154:157], v[214:217], v[82:85]
	s_setprio 0
	s_setprio 1
	v_mfma_f32_16x16x32_bf16 v[110:113], v[158:161], v[174:177], v[110:113]
	v_mfma_f32_16x16x32_bf16 v[106:109], v[166:169], v[174:177], v[106:109]
	v_mfma_f32_16x16x32_bf16 v[94:97], v[158:161], v[182:185], v[94:97]
	v_mfma_f32_16x16x32_bf16 v[90:93], v[166:169], v[182:185], v[90:93]
	v_mfma_f32_16x16x32_bf16 v[78:81], v[158:161], v[190:193], v[78:81]
	v_mfma_f32_16x16x32_bf16 v[74:77], v[166:169], v[190:193], v[74:77]
	v_mfma_f32_16x16x32_bf16 v[70:73], v[158:161], v[210:213], v[70:73]
	v_mfma_f32_16x16x32_bf16 v[66:69], v[166:169], v[210:213], v[66:69]
	v_mfma_f32_16x16x32_bf16 v[110:113], v[162:165], v[178:181], v[110:113]
	v_mfma_f32_16x16x32_bf16 v[106:109], v[170:173], v[178:181], v[106:109]
	v_mfma_f32_16x16x32_bf16 v[94:97], v[162:165], v[186:189], v[94:97]
	v_mfma_f32_16x16x32_bf16 v[90:93], v[170:173], v[186:189], v[90:93]
	v_mfma_f32_16x16x32_bf16 v[78:81], v[162:165], v[206:209], v[78:81]
	v_mfma_f32_16x16x32_bf16 v[74:77], v[170:173], v[206:209], v[74:77]
	v_mfma_f32_16x16x32_bf16 v[70:73], v[162:165], v[214:217], v[70:73]
	v_mfma_f32_16x16x32_bf16 v[66:69], v[170:173], v[214:217], v[66:69]
	s_setprio 0
	s_barrier
	s_mov_b32 m0, s93
	v_lshl_add_u64 v[226:227], s[48:49], 0, v[132:133]
	ds_read_b128 v[174:177], v140 offset:16384
	ds_read_b128 v[178:181], v140 offset:17408
	ds_read_b128 v[182:185], v140 offset:18432
	ds_read_b128 v[186:189], v140 offset:19456
	ds_read_b128 v[190:193], v140 offset:20480
	ds_read_b128 v[206:209], v140 offset:21504
	ds_read_b128 v[210:213], v140 offset:22528
	ds_read_b128 v[214:217], v140 offset:23552
	global_load_lds_dwordx4 v[226:227], off
	v_lshl_add_u64 v[228:229], s[48:49], 0, v[136:137]
	s_mov_b32 m0, s88
	v_lshl_add_u64 v[230:231], s[52:53], 0, v[132:133]
	global_load_lds_dwordx4 v[228:229], off
	s_mov_b32 m0, s92
	v_lshl_add_u64 v[234:235], s[46:47], 0, v[134:135]
	global_load_lds_dwordx4 v[230:231], off
	v_lshl_add_u64 v[230:231], s[52:53], 0, v[136:137]
	s_mov_b32 m0, s89
	s_nop 0
	global_load_lds_dwordx4 v[230:231], off
	v_lshl_add_u64 v[230:231], s[46:47], 0, v[130:131]
	s_mov_b32 m0, s69
	s_nop 0
	global_load_lds_dwordx4 v[230:231], off
	s_mov_b32 m0, s70
	s_nop 0
	global_load_lds_dwordx4 v[234:235], off
	s_waitcnt lgkmcnt(0)
	s_setprio 1
	v_mfma_f32_16x16x32_bf16 v[62:65], v[142:145], v[174:177], v[62:65]
	v_mfma_f32_16x16x32_bf16 v[58:61], v[150:153], v[174:177], v[58:61]
	v_mfma_f32_16x16x32_bf16 v[54:57], v[142:145], v[182:185], v[54:57]
	v_mfma_f32_16x16x32_bf16 v[50:53], v[150:153], v[182:185], v[50:53]
	s_waitcnt vmcnt(8)
	s_barrier
	v_mfma_f32_16x16x32_bf16 v[38:41], v[142:145], v[190:193], v[38:41]
	v_mfma_f32_16x16x32_bf16 v[34:37], v[150:153], v[190:193], v[34:37]
	v_mfma_f32_16x16x32_bf16 v[22:25], v[142:145], v[210:213], v[22:25]
	v_mfma_f32_16x16x32_bf16 v[18:21], v[150:153], v[210:213], v[18:21]
	v_mfma_f32_16x16x32_bf16 v[62:65], v[146:149], v[178:181], v[62:65]
	v_mfma_f32_16x16x32_bf16 v[58:61], v[154:157], v[178:181], v[58:61]
	v_mfma_f32_16x16x32_bf16 v[54:57], v[146:149], v[186:189], v[54:57]
	v_mfma_f32_16x16x32_bf16 v[50:53], v[154:157], v[186:189], v[50:53]
	v_mfma_f32_16x16x32_bf16 v[38:41], v[146:149], v[206:209], v[38:41]
	v_mfma_f32_16x16x32_bf16 v[34:37], v[154:157], v[206:209], v[34:37]
	v_mfma_f32_16x16x32_bf16 v[22:25], v[146:149], v[214:217], v[22:25]
	v_mfma_f32_16x16x32_bf16 v[18:21], v[154:157], v[214:217], v[18:21]
	s_setprio 0
	s_setprio 1
	v_mfma_f32_16x16x32_bf16 v[46:49], v[158:161], v[174:177], v[46:49]
	v_mfma_f32_16x16x32_bf16 v[42:45], v[166:169], v[174:177], v[42:45]
	v_mfma_f32_16x16x32_bf16 v[30:33], v[158:161], v[182:185], v[30:33]
	v_mfma_f32_16x16x32_bf16 v[26:29], v[166:169], v[182:185], v[26:29]
	v_mfma_f32_16x16x32_bf16 v[14:17], v[158:161], v[190:193], v[14:17]
	v_mfma_f32_16x16x32_bf16 v[10:13], v[166:169], v[190:193], v[10:13]
	v_mfma_f32_16x16x32_bf16 v[6:9], v[158:161], v[210:213], v[6:9]
	v_mfma_f32_16x16x32_bf16 v[2:5], v[166:169], v[210:213], v[2:5]
	v_mfma_f32_16x16x32_bf16 v[46:49], v[162:165], v[178:181], v[46:49]
	v_mfma_f32_16x16x32_bf16 v[42:45], v[170:173], v[178:181], v[42:45]
	v_mfma_f32_16x16x32_bf16 v[30:33], v[162:165], v[186:189], v[30:33]
	v_mfma_f32_16x16x32_bf16 v[26:29], v[170:173], v[186:189], v[26:29]
	v_mfma_f32_16x16x32_bf16 v[14:17], v[162:165], v[206:209], v[14:17]
	v_mfma_f32_16x16x32_bf16 v[10:13], v[170:173], v[206:209], v[10:13]
	v_mfma_f32_16x16x32_bf16 v[6:9], v[162:165], v[214:217], v[6:9]
	v_mfma_f32_16x16x32_bf16 v[2:5], v[170:173], v[214:217], v[2:5]
	s_setprio 0
	s_barrier
; #define PG8_STAGE(bufoff, gbase, voff) do { _Pragma("unroll") for (int _i = 0; _i < 2; ++_i) \
;         __builtin_amdgcn_global_load_lds((const unsigned*)((const char*)(gbase) + (voff)[_i]), (PG8_LAS unsigned*)(lds + (bufoff) + ldsw + _i * 8192), 16, 0, 0); } while (0)
; #define PG8_LDA(dst, b, h) do { _Pragma("unroll") for (int m = 0; m < 4; ++m) _Pragma("unroll") for (int k = 0; k < 2; ++k) dst[m][k] = *(const PG8_LAS bf16x8*)(lds + PG8_SA(b, h) + aoff + m * 2048 + k * 1024); } while (0)
; #define PG8_LDB(dst, b, h) do { _Pragma("unroll") for (int n = 0; n < 2; ++n) _Pragma("unroll") for (int k = 0; k < 2; ++k) dst[n][k] = *(const PG8_LAS bf16x8*)(lds + PG8_SB(b, h) + boff + n * 2048 + k * 1024); } while (0)
; #define PG8_MMA(ai, bj, At, Bt) do { __builtin_amdgcn_s_setprio(1); _Pragma("unroll") for (int m = 0; m < 4; ++m) _Pragma("unroll") for (int n = 0; n < 2; ++n) _Pragma("unroll") for (int k = 0; k < 2; ++k) \
;         acc[ai][bj][m][n] = __builtin_amdgcn_mfma_f32_16x16x32_bf16(Bt[n][k], At[m][k], acc[ai][bj][m][n], 0, 0, 0); __builtin_amdgcn_s_setprio(0); } while (0)
; #define PG8_WAIT_V(n) asm volatile("s_waitcnt vmcnt(" #n ")" ::: "memory")
; #define PG8_WAIT_L(n) asm volatile("s_waitcnt lgkmcnt(" #n ")" ::: "memory")
; #define PG8_BAR __builtin_amdgcn_s_barrier()
; #define PG8_SCHED __builtin_amdgcn_sched_barrier(0)
; template <class Epi, class Sched, bool ALIGN_EPI = false, bool SP2 = false>
; __device__ __forceinline__ void gemm_phase(PG8_LAS unsigned char* lds, const Gemm g, const Sched& S, const Epi& E, const int wave_id) {
;     ...
;             PG8_LDB(B0, 1, 0); PG8_LDB(B1, 1, 1); PG8_SCHED; PG8_LDA(At, 1, 0); PG8_STAGE(PG8_SA(0, 1), a2 + hstep, voffA);
;             PG8_WAIT_V(8); PG8_WAIT_L(0); PG8_BAR; PG8_MMA(0, 0, At, B0); PG8_MMA(0, 1, At, B1); PG8_BAR; PG8_SCHED;
;             PG8_LDA(At, 1, 1); PG8_STAGE(PG8_SB(1, 0), b3, voffB); PG8_STAGE(PG8_SB(1, 1), b3 + hstep, voffB); PG8_STAGE(PG8_SA(1, 0), a3, voffA);
;             PG8_WAIT_V(8); PG8_WAIT_L(0); PG8_BAR; PG8_MMA(1, 0, At, B0); PG8_MMA(1, 1, At, B1); PG8_BAR; PG8_SCHED;
	v_add_u32_e32 v141, s85, v138
	ds_read_b128 v[142:145], v141
	ds_read_b128 v[146:149], v141 offset:1024
	ds_read_b128 v[150:153], v141 offset:2048
	ds_read_b128 v[154:157], v141 offset:3072
	v_add_u32_e32 v141, s84, v138
	ds_read_b128 v[158:161], v141
	ds_read_b128 v[162:165], v141 offset:1024
	ds_read_b128 v[166:169], v141 offset:2048
	ds_read_b128 v[170:173], v141 offset:3072
	s_mov_b32 m0, s71
	v_lshl_add_u64 v[236:237], s[44:45], 0, v[130:131]
	ds_read_b128 v[174:177], v140 offset:32768
	ds_read_b128 v[178:181], v140 offset:33792
	ds_read_b128 v[182:185], v140 offset:34816
	ds_read_b128 v[186:189], v140 offset:35840
	ds_read_b128 v[190:193], v140 offset:36864
	ds_read_b128 v[206:209], v140 offset:37888
	ds_read_b128 v[210:213], v140 offset:38912
	ds_read_b128 v[214:217], v140 offset:39936
	global_load_lds_dwordx4 v[236:237], off
	v_lshl_add_u64 v[236:237], s[44:45], 0, v[134:135]
	s_mov_b32 m0, s72
	s_nop 0
	global_load_lds_dwordx4 v[236:237], off
	s_waitcnt lgkmcnt(0)
	s_setprio 1
	v_mfma_f32_16x16x32_bf16 v[126:129], v[142:145], v[174:177], v[126:129]
	v_mfma_f32_16x16x32_bf16 v[122:125], v[150:153], v[174:177], v[122:125]
	v_mfma_f32_16x16x32_bf16 v[118:121], v[142:145], v[182:185], v[118:121]
	v_mfma_f32_16x16x32_bf16 v[114:117], v[150:153], v[182:185], v[114:117]
	s_waitcnt vmcnt(8)
	s_barrier
	v_mfma_f32_16x16x32_bf16 v[102:105], v[142:145], v[190:193], v[102:105]
	v_mfma_f32_16x16x32_bf16 v[98:101], v[150:153], v[190:193], v[98:101]
	v_mfma_f32_16x16x32_bf16 v[86:89], v[142:145], v[210:213], v[86:89]
	v_mfma_f32_16x16x32_bf16 v[82:85], v[150:153], v[210:213], v[82:85]
	v_mfma_f32_16x16x32_bf16 v[126:129], v[146:149], v[178:181], v[126:129]
	v_mfma_f32_16x16x32_bf16 v[122:125], v[154:157], v[178:181], v[122:125]
	v_mfma_f32_16x16x32_bf16 v[118:121], v[146:149], v[186:189], v[118:121]
	v_mfma_f32_16x16x32_bf16 v[114:117], v[154:157], v[186:189], v[114:117]
	v_mfma_f32_16x16x32_bf16 v[102:105], v[146:149], v[206:209], v[102:105]
	v_mfma_f32_16x16x32_bf16 v[98:101], v[154:157], v[206:209], v[98:101]
	v_mfma_f32_16x16x32_bf16 v[86:89], v[146:149], v[214:217], v[86:89]
	v_mfma_f32_16x16x32_bf16 v[82:85], v[154:157], v[214:217], v[82:85]
	s_setprio 0
	s_setprio 1
	v_mfma_f32_16x16x32_bf16 v[110:113], v[158:161], v[174:177], v[110:113]
	v_mfma_f32_16x16x32_bf16 v[106:109], v[166:169], v[174:177], v[106:109]
	v_mfma_f32_16x16x32_bf16 v[94:97], v[158:161], v[182:185], v[94:97]
	v_mfma_f32_16x16x32_bf16 v[90:93], v[166:169], v[182:185], v[90:93]
	v_mfma_f32_16x16x32_bf16 v[78:81], v[158:161], v[190:193], v[78:81]
	v_mfma_f32_16x16x32_bf16 v[74:77], v[166:169], v[190:193], v[74:77]
	v_mfma_f32_16x16x32_bf16 v[70:73], v[158:161], v[210:213], v[70:73]
	v_mfma_f32_16x16x32_bf16 v[66:69], v[166:169], v[210:213], v[66:69]
	v_mfma_f32_16x16x32_bf16 v[110:113], v[162:165], v[178:181], v[110:113]
	v_mfma_f32_16x16x32_bf16 v[106:109], v[170:173], v[178:181], v[106:109]
	v_mfma_f32_16x16x32_bf16 v[94:97], v[162:165], v[186:189], v[94:97]
	v_mfma_f32_16x16x32_bf16 v[90:93], v[170:173], v[186:189], v[90:93]
	v_mfma_f32_16x16x32_bf16 v[78:81], v[162:165], v[206:209], v[78:81]
	v_mfma_f32_16x16x32_bf16 v[74:77], v[170:173], v[206:209], v[74:77]
	v_mfma_f32_16x16x32_bf16 v[70:73], v[162:165], v[214:217], v[70:73]
	v_mfma_f32_16x16x32_bf16 v[66:69], v[170:173], v[214:217], v[66:69]
	s_setprio 0
	s_barrier
	s_mov_b32 m0, s81
	v_lshl_add_u64 v[226:227], v[226:227], 0, s[30:31]
	ds_read_b128 v[174:177], v140 offset:49152
	ds_read_b128 v[178:181], v140 offset:50176
	ds_read_b128 v[182:185], v140 offset:51200
	ds_read_b128 v[186:189], v140 offset:52224
	ds_read_b128 v[190:193], v140 offset:53248
	ds_read_b128 v[206:209], v140 offset:54272
	ds_read_b128 v[210:213], v140 offset:55296
	ds_read_b128 v[214:217], v140 offset:56320
	global_load_lds_dwordx4 v[226:227], off
	v_lshl_add_u64 v[226:227], v[228:229], 0, s[30:31]
	s_mov_b32 m0, s80
	s_nop 0
	global_load_lds_dwordx4 v[226:227], off
	v_lshl_add_u64 v[226:227], s[42:43], 0, v[132:133]
	s_mov_b32 m0, s97
	s_nop 0
	global_load_lds_dwordx4 v[226:227], off
	v_lshl_add_u64 v[226:227], s[42:43], 0, v[136:137]
	s_mov_b32 m0, s96
	s_nop 0
	global_load_lds_dwordx4 v[226:227], off
	v_lshl_add_u64 v[226:227], v[230:231], 0, s[30:31]
	s_mov_b32 m0, s73
	s_nop 0
	global_load_lds_dwordx4 v[226:227], off
	v_lshl_add_u64 v[226:227], v[234:235], 0, s[30:31]
	s_mov_b32 m0, s74
	s_nop 0
	global_load_lds_dwordx4 v[226:227], off
	s_waitcnt lgkmcnt(0)
	s_setprio 1
	v_mfma_f32_16x16x32_bf16 v[62:65], v[142:145], v[174:177], v[62:65]
	v_mfma_f32_16x16x32_bf16 v[58:61], v[150:153], v[174:177], v[58:61]
	v_mfma_f32_16x16x32_bf16 v[54:57], v[142:145], v[182:185], v[54:57]
	v_mfma_f32_16x16x32_bf16 v[50:53], v[150:153], v[182:185], v[50:53]
	s_waitcnt vmcnt(8)
	s_barrier
	v_mfma_f32_16x16x32_bf16 v[38:41], v[142:145], v[190:193], v[38:41]
	v_mfma_f32_16x16x32_bf16 v[34:37], v[150:153], v[190:193], v[34:37]
	v_mfma_f32_16x16x32_bf16 v[22:25], v[142:145], v[210:213], v[22:25]
	v_mfma_f32_16x16x32_bf16 v[18:21], v[150:153], v[210:213], v[18:21]
	v_mfma_f32_16x16x32_bf16 v[62:65], v[146:149], v[178:181], v[62:65]
	v_mfma_f32_16x16x32_bf16 v[58:61], v[154:157], v[178:181], v[58:61]
	v_mfma_f32_16x16x32_bf16 v[54:57], v[146:149], v[186:189], v[54:57]
	v_mfma_f32_16x16x32_bf16 v[50:53], v[154:157], v[186:189], v[50:53]
	v_mfma_f32_16x16x32_bf16 v[38:41], v[146:149], v[206:209], v[38:41]
	v_mfma_f32_16x16x32_bf16 v[34:37], v[154:157], v[206:209], v[34:37]
	v_mfma_f32_16x16x32_bf16 v[22:25], v[146:149], v[214:217], v[22:25]
	v_mfma_f32_16x16x32_bf16 v[18:21], v[154:157], v[214:217], v[18:21]
	s_setprio 0
	s_setprio 1
	v_mfma_f32_16x16x32_bf16 v[46:49], v[158:161], v[174:177], v[46:49]
	v_mfma_f32_16x16x32_bf16 v[42:45], v[166:169], v[174:177], v[42:45]
	v_mfma_f32_16x16x32_bf16 v[30:33], v[158:161], v[182:185], v[30:33]
	v_mfma_f32_16x16x32_bf16 v[26:29], v[166:169], v[182:185], v[26:29]
	v_mfma_f32_16x16x32_bf16 v[14:17], v[158:161], v[190:193], v[14:17]
	v_mfma_f32_16x16x32_bf16 v[10:13], v[166:169], v[190:193], v[10:13]
	v_mfma_f32_16x16x32_bf16 v[6:9], v[158:161], v[210:213], v[6:9]
	v_mfma_f32_16x16x32_bf16 v[2:5], v[166:169], v[210:213], v[2:5]
	v_mfma_f32_16x16x32_bf16 v[46:49], v[162:165], v[178:181], v[46:49]
	v_mfma_f32_16x16x32_bf16 v[42:45], v[170:173], v[178:181], v[42:45]
	v_mfma_f32_16x16x32_bf16 v[30:33], v[162:165], v[186:189], v[30:33]
	v_mfma_f32_16x16x32_bf16 v[26:29], v[170:173], v[186:189], v[26:29]
	v_mfma_f32_16x16x32_bf16 v[14:17], v[162:165], v[206:209], v[14:17]
	v_mfma_f32_16x16x32_bf16 v[10:13], v[170:173], v[206:209], v[10:13]
	v_mfma_f32_16x16x32_bf16 v[6:9], v[162:165], v[214:217], v[6:9]
	v_mfma_f32_16x16x32_bf16 v[2:5], v[170:173], v[214:217], v[2:5]
	s_setprio 0
	s_barrier
	s_andn2_b64 vcc, exec, s[40:41]
	s_mov_b64 s[42:43], -1
	s_mov_b64 s[40:41], 0
	s_mov_b64 s[44:45], 0x100
	s_cbranch_vccz .LBB0_799

;     __host__ __device__ bool next(int i, Unit& u) const { const bool ok = StaticOrder::next(i, u); u.lm = 0; u.ln = 0; return ok; }
; #define PG8_STAGE(bufoff, gbase, voff) do { _Pragma("unroll") for (int _i = 0; _i < 2; ++_i) \
;         __builtin_amdgcn_global_load_lds((const unsigned*)((const char*)(gbase) + (voff)[_i]), (PG8_LAS unsigned*)(lds + (bufoff) + ldsw + _i * 8192), 16, 0, 0); } while (0)
; #define PG8_LDA(dst, b, h) do { _Pragma("unroll") for (int m = 0; m < 4; ++m) _Pragma("unroll") for (int k = 0; k < 2; ++k) dst[m][k] = *(const PG8_LAS bf16x8*)(lds + PG8_SA(b, h) + aoff + m * 2048 + k * 1024); } while (0)
; #define PG8_LDB(dst, b, h) do { _Pragma("unroll") for (int n = 0; n < 2; ++n) _Pragma("unroll") for (int k = 0; k < 2; ++k) dst[n][k] = *(const PG8_LAS bf16x8*)(lds + PG8_SB(b, h) + boff + n * 2048 + k * 1024); } while (0)
; #define PG8_WAIT_V(n) asm volatile("s_waitcnt vmcnt(" #n ")" ::: "memory")
; #define PG8_BAR __builtin_amdgcn_s_barrier()
; template <class Epi, class Sched, bool ALIGN_EPI = false, bool SP2 = false>
; __device__ __forceinline__ void gemm_phase(PG8_LAS unsigned char* lds, const Gemm g, const Sched& S, const Epi& E, const int wave_id) {
;     ...
;         const bool has_next = S.next(ui + 1, nxt);
;         const char* nA = has_next ? (const char*)g.A + (size_t)nxt.lm * tstep : cA; const char* nB = has_next ? (const char*)g.Bt + (size_t)nxt.ln * tstep : cB;
; #pragma unroll 1
;         for (int t = 0; t < nt; t += 2) {
;             const bool last = (t == nt - 2);
;             const char* a1 = cA + (size_t)(t + 1) * kstep;
;             const char* a2 = last ? nA : cA + (size_t)(t + 2) * kstep; const char* b2 = last ? nB : cB + (size_t)(t + 2) * kstep;
;             const char* a3 = a2 + kstep; const char* b3 = b2 + kstep;
;             if (last && has_next) S.a_ready(nxt);
;             if constexpr (SP2) {
;             PG8_LDB(B0, 0, 0); PG8_LDB(B1, 0, 1); PG8_SCHED; PG8_LDA(At, 0, 0); PG8_STAGE(PG8_SA(1, 1), a1 + hstep, voffA);
;             PG8_WAIT_V(8); PG8_WAIT_L(0); PG8_BAR; PG8_MMA(0, 0, At, B0); PG8_MMA(0, 1, At, B1); PG8_BAR; PG8_SCHED;
;             PG8_LDA(At, 0, 1); PG8_STAGE(PG8_SB(0, 0), b2, voffB); PG8_STAGE(PG8_SB(0, 1), b2 + hstep, voffB); PG8_STAGE(PG8_SA(0, 0), a2, voffA);
;             PG8_WAIT_V(8); PG8_WAIT_L(0); PG8_BAR; PG8_MMA(1, 0, At, B0); PG8_MMA(1, 1, At, B1); PG8_BAR; PG8_SCHED;
.LBB0_903:
	s_ashr_i32 s21, s20, 31
	s_lshl_b64 s[42:43], s[20:21], 20
	s_add_u32 s42, s8, s42
	s_addc_u32 s43, s9, s43
	s_and_b64 s[44:45], s[40:41], exec
	s_cselect_b32 s21, s43, s47
	s_cselect_b32 s49, s42, s46
	s_ashr_i32 s19, s18, 31
	s_lshl_b64 s[44:45], s[18:19], 20
	s_add_u32 s44, s65, s44
	s_addc_u32 s45, s68, s45
	s_and_b64 s[80:81], s[40:41], exec
	s_cselect_b32 s19, s45, s53
	s_cselect_b32 s79, s44, s52
	s_add_u32 s46, s46, 0x80080
	s_addc_u32 s47, s47, 0
	s_add_u32 s80, s52, 0x100
	s_addc_u32 s81, s53, 0
	s_mov_b32 s84, -2
	v_add_u32_e32 v226, 0x10000, v237
	s_add_u32 s52, s46, 0xfff80080
	s_addc_u32 s53, s47, -1
	s_add_i32 s85, 0, 0x10000
	s_cmp_eq_u32 s84, 28
	s_cselect_b32 s83, s21, s53
	s_cselect_b32 s82, s49, s52
	s_cselect_b32 s53, s19, s81
	s_cselect_b32 s52, s79, s80
	s_add_i32 s92, 0, 0x14000
	s_add_i32 m0, s70, 0xc000
	s_nop 0
	global_load_lds_dwordx4 v214, s[46:47]
	ds_read_b128 v[114:117], v226
	ds_read_b128 v[118:121], v226 offset:1024
	ds_read_b128 v[130:133], v226 offset:2048
	ds_read_b128 v[134:137], v226 offset:3072
	ds_read_b128 v[138:141], v226 offset:16384
	ds_read_b128 v[142:145], v226 offset:17408
	ds_read_b128 v[146:149], v226 offset:18432
	ds_read_b128 v[150:153], v226 offset:19456
	s_add_i32 m0, s70, 0xe000
	s_nop 0
	global_load_lds_dwordx4 v216, s[46:47]
	ds_read_b128 v[162:165], v244
	ds_read_b128 v[166:169], v244 offset:1024
	ds_read_b128 v[170:173], v244 offset:2048
	ds_read_b128 v[174:177], v244 offset:3072
	ds_read_b128 v[178:181], v244 offset:4096
	ds_read_b128 v[182:185], v244 offset:5120
	ds_read_b128 v[186:189], v244 offset:6144
	ds_read_b128 v[190:193], v244 offset:7168
	s_waitcnt lgkmcnt(0)
	s_setprio 1
	v_mfma_f32_16x16x32_bf16 v[158:161], v[114:117], v[162:165], 0
	v_mfma_f32_16x16x32_bf16 v[154:157], v[130:133], v[162:165], 0
	v_mfma_f32_16x16x32_bf16 v[110:113], v[114:117], v[170:173], 0
	v_mfma_f32_16x16x32_bf16 v[106:109], v[130:133], v[170:173], 0
	s_waitcnt vmcnt(8)
	s_barrier
	v_mfma_f32_16x16x32_bf16 v[94:97], v[114:117], v[178:181], 0
	v_mfma_f32_16x16x32_bf16 v[90:93], v[130:133], v[178:181], 0
	v_mfma_f32_16x16x32_bf16 v[78:81], v[114:117], v[186:189], 0
	v_mfma_f32_16x16x32_bf16 v[74:77], v[130:133], v[186:189], 0
	v_mfma_f32_16x16x32_bf16 v[158:161], v[118:121], v[166:169], v[158:161]
	v_mfma_f32_16x16x32_bf16 v[154:157], v[134:137], v[166:169], v[154:157]
	v_mfma_f32_16x16x32_bf16 v[110:113], v[118:121], v[174:177], v[110:113]
	v_mfma_f32_16x16x32_bf16 v[106:109], v[134:137], v[174:177], v[106:109]
	v_mfma_f32_16x16x32_bf16 v[94:97], v[118:121], v[182:185], v[94:97]
	v_mfma_f32_16x16x32_bf16 v[90:93], v[134:137], v[182:185], v[90:93]
	v_mfma_f32_16x16x32_bf16 v[78:81], v[118:121], v[190:193], v[78:81]
	v_mfma_f32_16x16x32_bf16 v[74:77], v[134:137], v[190:193], v[74:77]
	s_setprio 0
	s_setprio 1
	v_mfma_f32_16x16x32_bf16 v[126:129], v[138:141], v[162:165], 0
	v_mfma_f32_16x16x32_bf16 v[122:125], v[146:149], v[162:165], 0
	v_mfma_f32_16x16x32_bf16 v[102:105], v[138:141], v[170:173], 0
	v_mfma_f32_16x16x32_bf16 v[98:101], v[146:149], v[170:173], 0
	v_mfma_f32_16x16x32_bf16 v[86:89], v[138:141], v[178:181], 0
	v_mfma_f32_16x16x32_bf16 v[82:85], v[146:149], v[178:181], 0
	v_mfma_f32_16x16x32_bf16 v[70:73], v[138:141], v[186:189], 0
	v_mfma_f32_16x16x32_bf16 v[66:69], v[146:149], v[186:189], 0
	v_mfma_f32_16x16x32_bf16 v[126:129], v[142:145], v[166:169], v[126:129]
	v_mfma_f32_16x16x32_bf16 v[122:125], v[150:153], v[166:169], v[122:125]
	v_mfma_f32_16x16x32_bf16 v[102:105], v[142:145], v[174:177], v[102:105]
	v_mfma_f32_16x16x32_bf16 v[98:101], v[150:153], v[174:177], v[98:101]
	v_mfma_f32_16x16x32_bf16 v[86:89], v[142:145], v[182:185], v[86:89]
	v_mfma_f32_16x16x32_bf16 v[82:85], v[150:153], v[182:185], v[82:85]
	v_mfma_f32_16x16x32_bf16 v[70:73], v[142:145], v[190:193], v[70:73]
	v_mfma_f32_16x16x32_bf16 v[66:69], v[150:153], v[190:193], v[66:69]
	s_setprio 0
	s_barrier
	s_add_i32 s85, s85, s69
	s_mov_b32 m0, s85
	s_nop 0
	global_load_lds_dwordx4 v208, s[52:53]
	ds_read_b128 v[162:165], v244 offset:16384
	ds_read_b128 v[166:169], v244 offset:17408
	s_add_i32 m0, s85, 0x2000
	s_add_u32 s88, s52, 0x80000
	s_addc_u32 s89, s53, 0
	s_add_i32 s85, s92, s69
	global_load_lds_dwordx4 v212, s[52:53]
	ds_read_b128 v[170:173], v244 offset:18432
	ds_read_b128 v[174:177], v244 offset:19456
	s_mov_b32 m0, s85
	s_nop 0
	global_load_lds_dwordx4 v208, s[88:89]
	ds_read_b128 v[178:181], v244 offset:20480
	ds_read_b128 v[182:185], v244 offset:21504
	s_add_i32 m0, s85, 0x2000
	s_nop 0
	global_load_lds_dwordx4 v212, s[88:89]
	ds_read_b128 v[186:189], v244 offset:22528
	ds_read_b128 v[190:193], v244 offset:23552
	s_mov_b32 m0, s70
	s_nop 0
	global_load_lds_dwordx4 v206, s[82:83]
	s_mov_b32 m0, s71
	s_nop 0
	global_load_lds_dwordx4 v210, s[82:83]
	s_waitcnt lgkmcnt(0)
	s_setprio 1
	v_mfma_f32_16x16x32_bf16 v[62:65], v[114:117], v[162:165], 0
	v_mfma_f32_16x16x32_bf16 v[58:61], v[130:133], v[162:165], 0
	v_mfma_f32_16x16x32_bf16 v[46:49], v[114:117], v[170:173], 0
	v_mfma_f32_16x16x32_bf16 v[42:45], v[130:133], v[170:173], 0
	s_waitcnt vmcnt(8)
	s_barrier
; #define PG8_STAGE(bufoff, gbase, voff) do { _Pragma("unroll") for (int _i = 0; _i < 2; ++_i) \
;         __builtin_amdgcn_global_load_lds((const unsigned*)((const char*)(gbase) + (voff)[_i]), (PG8_LAS unsigned*)(lds + (bufoff) + ldsw + _i * 8192), 16, 0, 0); } while (0)
; #define PG8_LDA(dst, b, h) do { _Pragma("unroll") for (int m = 0; m < 4; ++m) _Pragma("unroll") for (int k = 0; k < 2; ++k) dst[m][k] = *(const PG8_LAS bf16x8*)(lds + PG8_SA(b, h) + aoff + m * 2048 + k * 1024); } while (0)
; #define PG8_LDB(dst, b, h) do { _Pragma("unroll") for (int n = 0; n < 2; ++n) _Pragma("unroll") for (int k = 0; k < 2; ++k) dst[n][k] = *(const PG8_LAS bf16x8*)(lds + PG8_SB(b, h) + boff + n * 2048 + k * 1024); } while (0)
; #define PG8_MMA(ai, bj, At, Bt) do { __builtin_amdgcn_s_setprio(1); _Pragma("unroll") for (int m = 0; m < 4; ++m) _Pragma("unroll") for (int n = 0; n < 2; ++n) _Pragma("unroll") for (int k = 0; k < 2; ++k) \
;         acc[ai][bj][m][n] = __builtin_amdgcn_mfma_f32_16x16x32_bf16(Bt[n][k], At[m][k], acc[ai][bj][m][n], 0, 0, 0); __builtin_amdgcn_s_setprio(0); } while (0)
; #define PG8_WAIT_V(n) asm volatile("s_waitcnt vmcnt(" #n ")" ::: "memory")
; #define PG8_WAIT_L(n) asm volatile("s_waitcnt lgkmcnt(" #n ")" ::: "memory")
; #define PG8_BAR __builtin_amdgcn_s_barrier()
; #define PG8_SCHED __builtin_amdgcn_sched_barrier(0)
; template <class Epi, class Sched, bool ALIGN_EPI = false, bool SP2 = false>
; __device__ __forceinline__ void gemm_phase(PG8_LAS unsigned char* lds, const Gemm g, const Sched& S, const Epi& E, const int wave_id) {
;     ...
;             PG8_WAIT_V(8); PG8_WAIT_L(0); PG8_BAR; PG8_MMA(0, 0, At, B0); PG8_MMA(0, 1, At, B1); PG8_BAR; PG8_SCHED;
;             PG8_LDA(At, 0, 1); PG8_STAGE(PG8_SB(0, 0), b2, voffB); PG8_STAGE(PG8_SB(0, 1), b2 + hstep, voffB); PG8_STAGE(PG8_SA(0, 0), a2, voffA);
;             PG8_WAIT_V(8); PG8_WAIT_L(0); PG8_BAR; PG8_MMA(1, 0, At, B0); PG8_MMA(1, 1, At, B1); PG8_BAR; PG8_SCHED;
;             PG8_LDB(B0, 1, 0); PG8_LDB(B1, 1, 1); PG8_SCHED; PG8_LDA(At, 1, 0); PG8_STAGE(PG8_SA(0, 1), a2 + hstep, voffA);
;             PG8_WAIT_V(8); PG8_WAIT_L(0); PG8_BAR; PG8_MMA(0, 0, At, B0); PG8_MMA(0, 1, At, B1); PG8_BAR; PG8_SCHED;
	v_mfma_f32_16x16x32_bf16 v[30:33], v[114:117], v[178:181], 0
	v_mfma_f32_16x16x32_bf16 v[26:29], v[130:133], v[178:181], 0
	v_mfma_f32_16x16x32_bf16 v[14:17], v[114:117], v[186:189], 0
	v_mfma_f32_16x16x32_bf16 v[10:13], v[130:133], v[186:189], 0
	v_mfma_f32_16x16x32_bf16 v[62:65], v[118:121], v[166:169], v[62:65]
	v_mfma_f32_16x16x32_bf16 v[58:61], v[134:137], v[166:169], v[58:61]
	v_mfma_f32_16x16x32_bf16 v[46:49], v[118:121], v[174:177], v[46:49]
	v_mfma_f32_16x16x32_bf16 v[42:45], v[134:137], v[174:177], v[42:45]
	v_mfma_f32_16x16x32_bf16 v[30:33], v[118:121], v[182:185], v[30:33]
	v_mfma_f32_16x16x32_bf16 v[26:29], v[134:137], v[182:185], v[26:29]
	v_mfma_f32_16x16x32_bf16 v[14:17], v[118:121], v[190:193], v[14:17]
	v_mfma_f32_16x16x32_bf16 v[10:13], v[134:137], v[190:193], v[10:13]
	s_setprio 0
	s_setprio 1
	v_mfma_f32_16x16x32_bf16 v[54:57], v[138:141], v[162:165], 0
	v_mfma_f32_16x16x32_bf16 v[50:53], v[146:149], v[162:165], 0
	v_mfma_f32_16x16x32_bf16 v[38:41], v[138:141], v[170:173], 0
	v_mfma_f32_16x16x32_bf16 v[34:37], v[146:149], v[170:173], 0
	v_mfma_f32_16x16x32_bf16 v[22:25], v[138:141], v[178:181], 0
	v_mfma_f32_16x16x32_bf16 v[18:21], v[146:149], v[178:181], 0
	v_mfma_f32_16x16x32_bf16 v[6:9], v[138:141], v[186:189], 0
	v_mfma_f32_16x16x32_bf16 v[2:5], v[146:149], v[186:189], 0
	v_mfma_f32_16x16x32_bf16 v[54:57], v[142:145], v[166:169], v[54:57]
	v_mfma_f32_16x16x32_bf16 v[50:53], v[150:153], v[166:169], v[50:53]
	v_mfma_f32_16x16x32_bf16 v[38:41], v[142:145], v[174:177], v[38:41]
	v_mfma_f32_16x16x32_bf16 v[34:37], v[150:153], v[174:177], v[34:37]
	v_mfma_f32_16x16x32_bf16 v[22:25], v[142:145], v[182:185], v[22:25]
	v_mfma_f32_16x16x32_bf16 v[18:21], v[150:153], v[182:185], v[18:21]
	v_mfma_f32_16x16x32_bf16 v[6:9], v[142:145], v[190:193], v[6:9]
	v_mfma_f32_16x16x32_bf16 v[2:5], v[150:153], v[190:193], v[2:5]
	s_setprio 0
	s_barrier
	s_add_i32 s85, 0, 0x18000
	s_add_i32 s88, 0, 0x1c000
	s_add_u32 s82, s82, 0x80000
	s_addc_u32 s83, s83, 0
	s_mov_b32 m0, s72
	s_nop 0
	global_load_lds_dwordx4 v206, s[82:83]
	ds_read_b128 v[114:117], v226 offset:32768
	ds_read_b128 v[118:121], v226 offset:33792
	ds_read_b128 v[130:133], v226 offset:34816
	ds_read_b128 v[134:137], v226 offset:35840
	ds_read_b128 v[138:141], v226 offset:49152
	ds_read_b128 v[142:145], v226 offset:50176
	ds_read_b128 v[146:149], v226 offset:51200
	ds_read_b128 v[150:153], v226 offset:52224
	s_mov_b32 m0, s73
	s_nop 0
	global_load_lds_dwordx4 v210, s[82:83]
	ds_read_b128 v[162:165], v244 offset:32768
	ds_read_b128 v[166:169], v244 offset:33792
	ds_read_b128 v[170:173], v244 offset:34816
	ds_read_b128 v[174:177], v244 offset:35840
	ds_read_b128 v[178:181], v244 offset:36864
	ds_read_b128 v[182:185], v244 offset:37888
	ds_read_b128 v[186:189], v244 offset:38912
	ds_read_b128 v[190:193], v244 offset:39936
	s_waitcnt lgkmcnt(0)
	s_setprio 1
	v_mfma_f32_16x16x32_bf16 v[158:161], v[114:117], v[162:165], v[158:161]
	v_mfma_f32_16x16x32_bf16 v[154:157], v[130:133], v[162:165], v[154:157]
	v_mfma_f32_16x16x32_bf16 v[110:113], v[114:117], v[170:173], v[110:113]
	v_mfma_f32_16x16x32_bf16 v[106:109], v[130:133], v[170:173], v[106:109]
	s_waitcnt vmcnt(8)
	s_barrier
	v_mfma_f32_16x16x32_bf16 v[94:97], v[114:117], v[178:181], v[94:97]
	v_mfma_f32_16x16x32_bf16 v[90:93], v[130:133], v[178:181], v[90:93]
	v_mfma_f32_16x16x32_bf16 v[78:81], v[114:117], v[186:189], v[78:81]
	v_mfma_f32_16x16x32_bf16 v[74:77], v[130:133], v[186:189], v[74:77]
	v_mfma_f32_16x16x32_bf16 v[158:161], v[118:121], v[166:169], v[158:161]
	v_mfma_f32_16x16x32_bf16 v[154:157], v[134:137], v[166:169], v[154:157]
	v_mfma_f32_16x16x32_bf16 v[110:113], v[118:121], v[174:177], v[110:113]
	v_mfma_f32_16x16x32_bf16 v[106:109], v[134:137], v[174:177], v[106:109]
	v_mfma_f32_16x16x32_bf16 v[94:97], v[118:121], v[182:185], v[94:97]
	v_mfma_f32_16x16x32_bf16 v[90:93], v[134:137], v[182:185], v[90:93]
	v_mfma_f32_16x16x32_bf16 v[78:81], v[118:121], v[190:193], v[78:81]
	v_mfma_f32_16x16x32_bf16 v[74:77], v[134:137], v[190:193], v[74:77]
	s_setprio 0
	s_setprio 1
	v_mfma_f32_16x16x32_bf16 v[126:129], v[138:141], v[162:165], v[126:129]
	v_mfma_f32_16x16x32_bf16 v[122:125], v[146:149], v[162:165], v[122:125]
	v_mfma_f32_16x16x32_bf16 v[102:105], v[138:141], v[170:173], v[102:105]
	v_mfma_f32_16x16x32_bf16 v[98:101], v[146:149], v[170:173], v[98:101]
	v_mfma_f32_16x16x32_bf16 v[86:89], v[138:141], v[178:181], v[86:89]
	v_mfma_f32_16x16x32_bf16 v[82:85], v[146:149], v[178:181], v[82:85]
	v_mfma_f32_16x16x32_bf16 v[70:73], v[138:141], v[186:189], v[70:73]
	v_mfma_f32_16x16x32_bf16 v[66:69], v[146:149], v[186:189], v[66:69]
	v_mfma_f32_16x16x32_bf16 v[126:129], v[142:145], v[166:169], v[126:129]
	v_mfma_f32_16x16x32_bf16 v[122:125], v[150:153], v[166:169], v[122:125]
	v_mfma_f32_16x16x32_bf16 v[102:105], v[142:145], v[174:177], v[102:105]
	v_mfma_f32_16x16x32_bf16 v[98:101], v[150:153], v[174:177], v[98:101]
	v_mfma_f32_16x16x32_bf16 v[86:89], v[142:145], v[182:185], v[86:89]
	v_mfma_f32_16x16x32_bf16 v[82:85], v[150:153], v[182:185], v[82:85]
	v_mfma_f32_16x16x32_bf16 v[70:73], v[142:145], v[190:193], v[70:73]
	v_mfma_f32_16x16x32_bf16 v[66:69], v[150:153], v[190:193], v[66:69]
	s_setprio 0
	s_barrier
; #define PG8_STAGE(bufoff, gbase, voff) do { _Pragma("unroll") for (int _i = 0; _i < 2; ++_i) \
;         __builtin_amdgcn_global_load_lds((const unsigned*)((const char*)(gbase) + (voff)[_i]), (PG8_LAS unsigned*)(lds + (bufoff) + ldsw + _i * 8192), 16, 0, 0); } while (0)
; #define PG8_LDA(dst, b, h) do { _Pragma("unroll") for (int m = 0; m < 4; ++m) _Pragma("unroll") for (int k = 0; k < 2; ++k) dst[m][k] = *(const PG8_LAS bf16x8*)(lds + PG8_SA(b, h) + aoff + m * 2048 + k * 1024); } while (0)
; #define PG8_WAIT_V(n) asm volatile("s_waitcnt vmcnt(" #n ")" ::: "memory")
; #define PG8_WAIT_L(n) asm volatile("s_waitcnt lgkmcnt(" #n ")" ::: "memory")
; #define PG8_BAR __builtin_amdgcn_s_barrier()
; template <class Epi, class Sched, bool ALIGN_EPI = false, bool SP2 = false>
; __device__ __forceinline__ void gemm_phase(PG8_LAS unsigned char* lds, const Gemm g, const Sched& S, const Epi& E, const int wave_id) {
;     ...
;         for (int t = 0; t < nt; t += 2) {
;             const bool last = (t == nt - 2);
;             const char* a1 = cA + (size_t)(t + 1) * kstep;
;             const char* a2 = last ? nA : cA + (size_t)(t + 2) * kstep; const char* b2 = last ? nB : cB + (size_t)(t + 2) * kstep;
;             const char* a3 = a2 + kstep; const char* b3 = b2 + kstep;
;             if (last && has_next) S.a_ready(nxt);
;             if constexpr (SP2) {
;             PG8_LDB(B0, 0, 0); PG8_LDB(B1, 0, 1); PG8_SCHED; PG8_LDA(At, 0, 0); PG8_STAGE(PG8_SA(1, 1), a1 + hstep, voffA);
;             PG8_WAIT_V(8); PG8_WAIT_L(0); PG8_BAR; PG8_MMA(0, 0, At, B0); PG8_MMA(0, 1, At, B1); PG8_BAR; PG8_SCHED;
;             PG8_LDA(At, 0, 1); PG8_STAGE(PG8_SB(0, 0), b2, voffB); PG8_STAGE(PG8_SB(0, 1), b2 + hstep, voffB); PG8_STAGE(PG8_SA(0, 0), a2, voffA);
;             PG8_WAIT_V(8); PG8_WAIT_L(0); PG8_BAR; PG8_MMA(1, 0, At, B0); PG8_MMA(1, 1, At, B1); PG8_BAR; PG8_SCHED;
;             PG8_LDB(B0, 1, 0); PG8_LDB(B1, 1, 1); PG8_SCHED; PG8_LDA(At, 1, 0); PG8_STAGE(PG8_SA(0, 1), a2 + hstep, voffA);
;             PG8_WAIT_V(8); PG8_WAIT_L(0); PG8_BAR; PG8_MMA(0, 0, At, B0); PG8_MMA(0, 1, At, B1); PG8_BAR; PG8_SCHED;
;             PG8_LDA(At, 1, 1); PG8_STAGE(PG8_SB(1, 0), b3, voffB); PG8_STAGE(PG8_SB(1, 1), b3 + hstep, voffB); PG8_STAGE(PG8_SA(1, 0), a3, voffA);
;             PG8_WAIT_V(8); PG8_WAIT_L(0); PG8_BAR; PG8_MMA(1, 0, At, B0); PG8_MMA(1, 1, At, B1); PG8_BAR; PG8_SCHED;
	s_add_u32 vcc_lo, s82, 0xfff80080
	s_addc_u32 vcc_hi, s83, -1
	s_mov_b32 m0, s76
	s_nop 0
	global_load_lds_dwordx4 v206, vcc
	ds_read_b128 v[162:165], v244 offset:49152
	ds_read_b128 v[166:169], v244 offset:50176
	s_mov_b32 m0, s77
	s_add_i32 s82, s85, s69
	global_load_lds_dwordx4 v210, vcc
	ds_read_b128 v[170:173], v244 offset:51200
	ds_read_b128 v[174:177], v244 offset:52224
	s_add_u32 vcc_lo, s52, 0x80
	s_addc_u32 vcc_hi, s53, 0
	s_mov_b32 m0, s82
	s_nop 0
	global_load_lds_dwordx4 v208, vcc
	ds_read_b128 v[178:181], v244 offset:53248
	ds_read_b128 v[182:185], v244 offset:54272
	s_add_i32 m0, s82, 0x2000
	s_add_u32 s52, s52, 0x80080
	s_addc_u32 s53, s53, 0
	global_load_lds_dwordx4 v212, vcc
	ds_read_b128 v[186:189], v244 offset:55296
	ds_read_b128 v[190:193], v244 offset:56320
	s_add_i32 s82, s88, s69
	s_mov_b32 m0, s82
	s_nop 0
	global_load_lds_dwordx4 v208, s[52:53]
	s_add_i32 m0, s82, 0x2000
	s_nop 0
	global_load_lds_dwordx4 v212, s[52:53]
	s_waitcnt lgkmcnt(0)
	s_setprio 1
	v_mfma_f32_16x16x32_bf16 v[62:65], v[114:117], v[162:165], v[62:65]
	v_mfma_f32_16x16x32_bf16 v[58:61], v[130:133], v[162:165], v[58:61]
	v_mfma_f32_16x16x32_bf16 v[46:49], v[114:117], v[170:173], v[46:49]
	v_mfma_f32_16x16x32_bf16 v[42:45], v[130:133], v[170:173], v[42:45]
	s_waitcnt vmcnt(8)
	s_barrier
	v_mfma_f32_16x16x32_bf16 v[30:33], v[114:117], v[178:181], v[30:33]
	v_mfma_f32_16x16x32_bf16 v[26:29], v[130:133], v[178:181], v[26:29]
	v_mfma_f32_16x16x32_bf16 v[14:17], v[114:117], v[186:189], v[14:17]
	v_mfma_f32_16x16x32_bf16 v[10:13], v[130:133], v[186:189], v[10:13]
	v_mfma_f32_16x16x32_bf16 v[62:65], v[118:121], v[166:169], v[62:65]
	v_mfma_f32_16x16x32_bf16 v[58:61], v[134:137], v[166:169], v[58:61]
	v_mfma_f32_16x16x32_bf16 v[46:49], v[118:121], v[174:177], v[46:49]
	v_mfma_f32_16x16x32_bf16 v[42:45], v[134:137], v[174:177], v[42:45]
	v_mfma_f32_16x16x32_bf16 v[30:33], v[118:121], v[182:185], v[30:33]
	v_mfma_f32_16x16x32_bf16 v[26:29], v[134:137], v[182:185], v[26:29]
	v_mfma_f32_16x16x32_bf16 v[14:17], v[118:121], v[190:193], v[14:17]
	v_mfma_f32_16x16x32_bf16 v[10:13], v[134:137], v[190:193], v[10:13]
	s_setprio 0
	s_setprio 1
	v_mfma_f32_16x16x32_bf16 v[54:57], v[138:141], v[162:165], v[54:57]
	v_mfma_f32_16x16x32_bf16 v[50:53], v[146:149], v[162:165], v[50:53]
	v_mfma_f32_16x16x32_bf16 v[38:41], v[138:141], v[170:173], v[38:41]
	v_mfma_f32_16x16x32_bf16 v[34:37], v[146:149], v[170:173], v[34:37]
	v_mfma_f32_16x16x32_bf16 v[22:25], v[138:141], v[178:181], v[22:25]
	v_mfma_f32_16x16x32_bf16 v[18:21], v[146:149], v[178:181], v[18:21]
	v_mfma_f32_16x16x32_bf16 v[6:9], v[138:141], v[186:189], v[6:9]
	v_mfma_f32_16x16x32_bf16 v[2:5], v[146:149], v[186:189], v[2:5]
	v_mfma_f32_16x16x32_bf16 v[54:57], v[142:145], v[166:169], v[54:57]
	v_mfma_f32_16x16x32_bf16 v[50:53], v[150:153], v[166:169], v[50:53]
	v_mfma_f32_16x16x32_bf16 v[38:41], v[142:145], v[174:177], v[38:41]
	v_mfma_f32_16x16x32_bf16 v[34:37], v[150:153], v[174:177], v[34:37]
	v_mfma_f32_16x16x32_bf16 v[22:25], v[142:145], v[182:185], v[22:25]
	v_mfma_f32_16x16x32_bf16 v[18:21], v[150:153], v[182:185], v[18:21]
	v_mfma_f32_16x16x32_bf16 v[6:9], v[142:145], v[190:193], v[6:9]
	v_mfma_f32_16x16x32_bf16 v[2:5], v[150:153], v[190:193], v[2:5]
	s_setprio 0
	s_barrier
	s_add_i32 s84, s84, 2
	s_add_u32 s46, s46, 0x100
	s_addc_u32 s47, s47, 0
	s_add_u32 s80, s80, 0x100
	s_addc_u32 s81, s81, 0
	s_cmp_gt_u32 s84, 29
	s_cbranch_scc1 .Lpeel_exit_g5
.LBB0_904:
	s_add_u32 s52, s46, 0xfff80080
	s_addc_u32 s53, s47, -1
	s_add_i32 s85, 0, 0x10000
	s_cmp_eq_u32 s84, 28
	s_cselect_b32 s83, s21, s53
	s_cselect_b32 s82, s49, s52
	s_cselect_b32 s53, s19, s81
	s_cselect_b32 s52, s79, s80
	s_add_i32 s92, 0, 0x14000
	s_add_i32 m0, s70, 0xc000
	s_nop 0
	global_load_lds_dwordx4 v214, s[46:47]
	ds_read_b128 v[114:117], v226
	ds_read_b128 v[118:121], v226 offset:1024
	ds_read_b128 v[130:133], v226 offset:2048
	ds_read_b128 v[134:137], v226 offset:3072
	ds_read_b128 v[138:141], v226 offset:16384
	ds_read_b128 v[142:145], v226 offset:17408
	ds_read_b128 v[146:149], v226 offset:18432
	ds_read_b128 v[150:153], v226 offset:19456
	s_add_i32 m0, s70, 0xe000
	s_nop 0
	global_load_lds_dwordx4 v216, s[46:47]
	ds_read_b128 v[162:165], v244
	ds_read_b128 v[166:169], v244 offset:1024
	ds_read_b128 v[170:173], v244 offset:2048
	ds_read_b128 v[174:177], v244 offset:3072
	ds_read_b128 v[178:181], v244 offset:4096
	ds_read_b128 v[182:185], v244 offset:5120
	ds_read_b128 v[186:189], v244 offset:6144
	ds_read_b128 v[190:193], v244 offset:7168
	s_waitcnt lgkmcnt(0)
	s_setprio 1
	v_mfma_f32_16x16x32_bf16 v[158:161], v[114:117], v[162:165], v[158:161]
	v_mfma_f32_16x16x32_bf16 v[154:157], v[130:133], v[162:165], v[154:157]
	v_mfma_f32_16x16x32_bf16 v[110:113], v[114:117], v[170:173], v[110:113]
	v_mfma_f32_16x16x32_bf16 v[106:109], v[130:133], v[170:173], v[106:109]
	s_waitcnt vmcnt(8)
	s_barrier
; #define PG8_STAGE(bufoff, gbase, voff) do { _Pragma("unroll") for (int _i = 0; _i < 2; ++_i) \
;         __builtin_amdgcn_global_load_lds((const unsigned*)((const char*)(gbase) + (voff)[_i]), (PG8_LAS unsigned*)(lds + (bufoff) + ldsw + _i * 8192), 16, 0, 0); } while (0)
; #define PG8_LDA(dst, b, h) do { _Pragma("unroll") for (int m = 0; m < 4; ++m) _Pragma("unroll") for (int k = 0; k < 2; ++k) dst[m][k] = *(const PG8_LAS bf16x8*)(lds + PG8_SA(b, h) + aoff + m * 2048 + k * 1024); } while (0)
; #define PG8_LDB(dst, b, h) do { _Pragma("unroll") for (int n = 0; n < 2; ++n) _Pragma("unroll") for (int k = 0; k < 2; ++k) dst[n][k] = *(const PG8_LAS bf16x8*)(lds + PG8_SB(b, h) + boff + n * 2048 + k * 1024); } while (0)
; #define PG8_MMA(ai, bj, At, Bt) do { __builtin_amdgcn_s_setprio(1); _Pragma("unroll") for (int m = 0; m < 4; ++m) _Pragma("unroll") for (int n = 0; n < 2; ++n) _Pragma("unroll") for (int k = 0; k < 2; ++k) \
;         acc[ai][bj][m][n] = __builtin_amdgcn_mfma_f32_16x16x32_bf16(Bt[n][k], At[m][k], acc[ai][bj][m][n], 0, 0, 0); __builtin_amdgcn_s_setprio(0); } while (0)
; #define PG8_WAIT_V(n) asm volatile("s_waitcnt vmcnt(" #n ")" ::: "memory")
; #define PG8_WAIT_L(n) asm volatile("s_waitcnt lgkmcnt(" #n ")" ::: "memory")
; #define PG8_BAR __builtin_amdgcn_s_barrier()
; #define PG8_SCHED __builtin_amdgcn_sched_barrier(0)
; template <class Epi, class Sched, bool ALIGN_EPI = false, bool SP2 = false>
; __device__ __forceinline__ void gemm_phase(PG8_LAS unsigned char* lds, const Gemm g, const Sched& S, const Epi& E, const int wave_id) {
;     ...
;             PG8_WAIT_V(8); PG8_WAIT_L(0); PG8_BAR; PG8_MMA(0, 0, At, B0); PG8_MMA(0, 1, At, B1); PG8_BAR; PG8_SCHED;
;             PG8_LDA(At, 0, 1); PG8_STAGE(PG8_SB(0, 0), b2, voffB); PG8_STAGE(PG8_SB(0, 1), b2 + hstep, voffB); PG8_STAGE(PG8_SA(0, 0), a2, voffA);
;             PG8_WAIT_V(8); PG8_WAIT_L(0); PG8_BAR; PG8_MMA(1, 0, At, B0); PG8_MMA(1, 1, At, B1); PG8_BAR; PG8_SCHED;
;             PG8_LDB(B0, 1, 0); PG8_LDB(B1, 1, 1); PG8_SCHED; PG8_LDA(At, 1, 0); PG8_STAGE(PG8_SA(0, 1), a2 + hstep, voffA);
;             PG8_WAIT_V(8); PG8_WAIT_L(0); PG8_BAR; PG8_MMA(0, 0, At, B0); PG8_MMA(0, 1, At, B1); PG8_BAR; PG8_SCHED;
	v_mfma_f32_16x16x32_bf16 v[94:97], v[114:117], v[178:181], v[94:97]
	v_mfma_f32_16x16x32_bf16 v[90:93], v[130:133], v[178:181], v[90:93]
	v_mfma_f32_16x16x32_bf16 v[78:81], v[114:117], v[186:189], v[78:81]
	v_mfma_f32_16x16x32_bf16 v[74:77], v[130:133], v[186:189], v[74:77]
	v_mfma_f32_16x16x32_bf16 v[158:161], v[118:121], v[166:169], v[158:161]
	v_mfma_f32_16x16x32_bf16 v[154:157], v[134:137], v[166:169], v[154:157]
	v_mfma_f32_16x16x32_bf16 v[110:113], v[118:121], v[174:177], v[110:113]
	v_mfma_f32_16x16x32_bf16 v[106:109], v[134:137], v[174:177], v[106:109]
	v_mfma_f32_16x16x32_bf16 v[94:97], v[118:121], v[182:185], v[94:97]
	v_mfma_f32_16x16x32_bf16 v[90:93], v[134:137], v[182:185], v[90:93]
	v_mfma_f32_16x16x32_bf16 v[78:81], v[118:121], v[190:193], v[78:81]
	v_mfma_f32_16x16x32_bf16 v[74:77], v[134:137], v[190:193], v[74:77]
	s_setprio 0
	s_setprio 1
	v_mfma_f32_16x16x32_bf16 v[126:129], v[138:141], v[162:165], v[126:129]
	v_mfma_f32_16x16x32_bf16 v[122:125], v[146:149], v[162:165], v[122:125]
	v_mfma_f32_16x16x32_bf16 v[102:105], v[138:141], v[170:173], v[102:105]
	v_mfma_f32_16x16x32_bf16 v[98:101], v[146:149], v[170:173], v[98:101]
	v_mfma_f32_16x16x32_bf16 v[86:89], v[138:141], v[178:181], v[86:89]
	v_mfma_f32_16x16x32_bf16 v[82:85], v[146:149], v[178:181], v[82:85]
	v_mfma_f32_16x16x32_bf16 v[70:73], v[138:141], v[186:189], v[70:73]
	v_mfma_f32_16x16x32_bf16 v[66:69], v[146:149], v[186:189], v[66:69]
	v_mfma_f32_16x16x32_bf16 v[126:129], v[142:145], v[166:169], v[126:129]
	v_mfma_f32_16x16x32_bf16 v[122:125], v[150:153], v[166:169], v[122:125]
	v_mfma_f32_16x16x32_bf16 v[102:105], v[142:145], v[174:177], v[102:105]
	v_mfma_f32_16x16x32_bf16 v[98:101], v[150:153], v[174:177], v[98:101]
	v_mfma_f32_16x16x32_bf16 v[86:89], v[142:145], v[182:185], v[86:89]
	v_mfma_f32_16x16x32_bf16 v[82:85], v[150:153], v[182:185], v[82:85]
	v_mfma_f32_16x16x32_bf16 v[70:73], v[142:145], v[190:193], v[70:73]
	v_mfma_f32_16x16x32_bf16 v[66:69], v[150:153], v[190:193], v[66:69]
	s_setprio 0
	s_barrier
	s_add_i32 s85, s85, s69
	s_mov_b32 m0, s85
	s_nop 0
	global_load_lds_dwordx4 v208, s[52:53]
	ds_read_b128 v[162:165], v244 offset:16384
	ds_read_b128 v[166:169], v244 offset:17408
	s_add_i32 m0, s85, 0x2000
	s_add_u32 s88, s52, 0x80000
	s_addc_u32 s89, s53, 0
	s_add_i32 s85, s92, s69
	global_load_lds_dwordx4 v212, s[52:53]
	ds_read_b128 v[170:173], v244 offset:18432
	ds_read_b128 v[174:177], v244 offset:19456
	s_mov_b32 m0, s85
	s_nop 0
	global_load_lds_dwordx4 v208, s[88:89]
	ds_read_b128 v[178:181], v244 offset:20480
	ds_read_b128 v[182:185], v244 offset:21504
	s_add_i32 m0, s85, 0x2000
	s_nop 0
	global_load_lds_dwordx4 v212, s[88:89]
	ds_read_b128 v[186:189], v244 offset:22528
	ds_read_b128 v[190:193], v244 offset:23552
	s_mov_b32 m0, s70
	s_nop 0
	global_load_lds_dwordx4 v206, s[82:83]
	s_mov_b32 m0, s71
	s_nop 0
	global_load_lds_dwordx4 v210, s[82:83]
	s_waitcnt lgkmcnt(0)
	s_setprio 1
	v_mfma_f32_16x16x32_bf16 v[62:65], v[114:117], v[162:165], v[62:65]
	v_mfma_f32_16x16x32_bf16 v[58:61], v[130:133], v[162:165], v[58:61]
	v_mfma_f32_16x16x32_bf16 v[46:49], v[114:117], v[170:173], v[46:49]
	v_mfma_f32_16x16x32_bf16 v[42:45], v[130:133], v[170:173], v[42:45]
	s_waitcnt vmcnt(8)
	s_barrier
	v_mfma_f32_16x16x32_bf16 v[30:33], v[114:117], v[178:181], v[30:33]
	v_mfma_f32_16x16x32_bf16 v[26:29], v[130:133], v[178:181], v[26:29]
	v_mfma_f32_16x16x32_bf16 v[14:17], v[114:117], v[186:189], v[14:17]
	v_mfma_f32_16x16x32_bf16 v[10:13], v[130:133], v[186:189], v[10:13]
	v_mfma_f32_16x16x32_bf16 v[62:65], v[118:121], v[166:169], v[62:65]
	v_mfma_f32_16x16x32_bf16 v[58:61], v[134:137], v[166:169], v[58:61]
	v_mfma_f32_16x16x32_bf16 v[46:49], v[118:121], v[174:177], v[46:49]
	v_mfma_f32_16x16x32_bf16 v[42:45], v[134:137], v[174:177], v[42:45]
	v_mfma_f32_16x16x32_bf16 v[30:33], v[118:121], v[182:185], v[30:33]
	v_mfma_f32_16x16x32_bf16 v[26:29], v[134:137], v[182:185], v[26:29]
	v_mfma_f32_16x16x32_bf16 v[14:17], v[118:121], v[190:193], v[14:17]
	v_mfma_f32_16x16x32_bf16 v[10:13], v[134:137], v[190:193], v[10:13]
	s_setprio 0
	s_setprio 1
	v_mfma_f32_16x16x32_bf16 v[54:57], v[138:141], v[162:165], v[54:57]
	v_mfma_f32_16x16x32_bf16 v[50:53], v[146:149], v[162:165], v[50:53]
	v_mfma_f32_16x16x32_bf16 v[38:41], v[138:141], v[170:173], v[38:41]
	v_mfma_f32_16x16x32_bf16 v[34:37], v[146:149], v[170:173], v[34:37]
	v_mfma_f32_16x16x32_bf16 v[22:25], v[138:141], v[178:181], v[22:25]
	v_mfma_f32_16x16x32_bf16 v[18:21], v[146:149], v[178:181], v[18:21]
	v_mfma_f32_16x16x32_bf16 v[6:9], v[138:141], v[186:189], v[6:9]
	v_mfma_f32_16x16x32_bf16 v[2:5], v[146:149], v[186:189], v[2:5]
	v_mfma_f32_16x16x32_bf16 v[54:57], v[142:145], v[166:169], v[54:57]
	v_mfma_f32_16x16x32_bf16 v[50:53], v[150:153], v[166:169], v[50:53]
	v_mfma_f32_16x16x32_bf16 v[38:41], v[142:145], v[174:177], v[38:41]
	v_mfma_f32_16x16x32_bf16 v[34:37], v[150:153], v[174:177], v[34:37]
	v_mfma_f32_16x16x32_bf16 v[22:25], v[142:145], v[182:185], v[22:25]
	v_mfma_f32_16x16x32_bf16 v[18:21], v[150:153], v[182:185], v[18:21]
	v_mfma_f32_16x16x32_bf16 v[6:9], v[142:145], v[190:193], v[6:9]
	v_mfma_f32_16x16x32_bf16 v[2:5], v[150:153], v[190:193], v[2:5]
	s_setprio 0
	s_barrier
; #define PG8_STAGE(bufoff, gbase, voff) do { _Pragma("unroll") for (int _i = 0; _i < 2; ++_i) \
;         __builtin_amdgcn_global_load_lds((const unsigned*)((const char*)(gbase) + (voff)[_i]), (PG8_LAS unsigned*)(lds + (bufoff) + ldsw + _i * 8192), 16, 0, 0); } while (0)
; #define PG8_LDA(dst, b, h) do { _Pragma("unroll") for (int m = 0; m < 4; ++m) _Pragma("unroll") for (int k = 0; k < 2; ++k) dst[m][k] = *(const PG8_LAS bf16x8*)(lds + PG8_SA(b, h) + aoff + m * 2048 + k * 1024); } while (0)
; #define PG8_LDB(dst, b, h) do { _Pragma("unroll") for (int n = 0; n < 2; ++n) _Pragma("unroll") for (int k = 0; k < 2; ++k) dst[n][k] = *(const PG8_LAS bf16x8*)(lds + PG8_SB(b, h) + boff + n * 2048 + k * 1024); } while (0)
; #define PG8_MMA(ai, bj, At, Bt) do { __builtin_amdgcn_s_setprio(1); _Pragma("unroll") for (int m = 0; m < 4; ++m) _Pragma("unroll") for (int n = 0; n < 2; ++n) _Pragma("unroll") for (int k = 0; k < 2; ++k) \
;         acc[ai][bj][m][n] = __builtin_amdgcn_mfma_f32_16x16x32_bf16(Bt[n][k], At[m][k], acc[ai][bj][m][n], 0, 0, 0); __builtin_amdgcn_s_setprio(0); } while (0)
; #define PG8_WAIT_V(n) asm volatile("s_waitcnt vmcnt(" #n ")" ::: "memory")
; #define PG8_WAIT_L(n) asm volatile("s_waitcnt lgkmcnt(" #n ")" ::: "memory")
; #define PG8_BAR __builtin_amdgcn_s_barrier()
; #define PG8_SCHED __builtin_amdgcn_sched_barrier(0)
; template <class Epi, class Sched, bool ALIGN_EPI = false, bool SP2 = false>
; __device__ __forceinline__ void gemm_phase(PG8_LAS unsigned char* lds, const Gemm g, const Sched& S, const Epi& E, const int wave_id) {
;     ...
;             PG8_LDB(B0, 1, 0); PG8_LDB(B1, 1, 1); PG8_SCHED; PG8_LDA(At, 1, 0); PG8_STAGE(PG8_SA(0, 1), a2 + hstep, voffA);
;             PG8_WAIT_V(8); PG8_WAIT_L(0); PG8_BAR; PG8_MMA(0, 0, At, B0); PG8_MMA(0, 1, At, B1); PG8_BAR; PG8_SCHED;
;             PG8_LDA(At, 1, 1); PG8_STAGE(PG8_SB(1, 0), b3, voffB); PG8_STAGE(PG8_SB(1, 1), b3 + hstep, voffB); PG8_STAGE(PG8_SA(1, 0), a3, voffA);
;             PG8_WAIT_V(8); PG8_WAIT_L(0); PG8_BAR; PG8_MMA(1, 0, At, B0); PG8_MMA(1, 1, At, B1); PG8_BAR; PG8_SCHED;
	s_add_i32 s85, 0, 0x18000
	s_add_i32 s88, 0, 0x1c000
	s_add_u32 s82, s82, 0x80000
	s_addc_u32 s83, s83, 0
	s_mov_b32 m0, s72
	s_nop 0
	global_load_lds_dwordx4 v206, s[82:83]
	ds_read_b128 v[114:117], v226 offset:32768
	ds_read_b128 v[118:121], v226 offset:33792
	ds_read_b128 v[130:133], v226 offset:34816
	ds_read_b128 v[134:137], v226 offset:35840
	ds_read_b128 v[138:141], v226 offset:49152
	ds_read_b128 v[142:145], v226 offset:50176
	ds_read_b128 v[146:149], v226 offset:51200
	ds_read_b128 v[150:153], v226 offset:52224
	s_mov_b32 m0, s73
	s_nop 0
	global_load_lds_dwordx4 v210, s[82:83]
	ds_read_b128 v[162:165], v244 offset:32768
	ds_read_b128 v[166:169], v244 offset:33792
	ds_read_b128 v[170:173], v244 offset:34816
	ds_read_b128 v[174:177], v244 offset:35840
	ds_read_b128 v[178:181], v244 offset:36864
	ds_read_b128 v[182:185], v244 offset:37888
	ds_read_b128 v[186:189], v244 offset:38912
	ds_read_b128 v[190:193], v244 offset:39936
	s_waitcnt lgkmcnt(0)
	s_setprio 1
	v_mfma_f32_16x16x32_bf16 v[158:161], v[114:117], v[162:165], v[158:161]
	v_mfma_f32_16x16x32_bf16 v[154:157], v[130:133], v[162:165], v[154:157]
	v_mfma_f32_16x16x32_bf16 v[110:113], v[114:117], v[170:173], v[110:113]
	v_mfma_f32_16x16x32_bf16 v[106:109], v[130:133], v[170:173], v[106:109]
	s_waitcnt vmcnt(8)
	s_barrier
	v_mfma_f32_16x16x32_bf16 v[94:97], v[114:117], v[178:181], v[94:97]
	v_mfma_f32_16x16x32_bf16 v[90:93], v[130:133], v[178:181], v[90:93]
	v_mfma_f32_16x16x32_bf16 v[78:81], v[114:117], v[186:189], v[78:81]
	v_mfma_f32_16x16x32_bf16 v[74:77], v[130:133], v[186:189], v[74:77]
	v_mfma_f32_16x16x32_bf16 v[158:161], v[118:121], v[166:169], v[158:161]
	v_mfma_f32_16x16x32_bf16 v[154:157], v[134:137], v[166:169], v[154:157]
	v_mfma_f32_16x16x32_bf16 v[110:113], v[118:121], v[174:177], v[110:113]
	v_mfma_f32_16x16x32_bf16 v[106:109], v[134:137], v[174:177], v[106:109]
	v_mfma_f32_16x16x32_bf16 v[94:97], v[118:121], v[182:185], v[94:97]
	v_mfma_f32_16x16x32_bf16 v[90:93], v[134:137], v[182:185], v[90:93]
	v_mfma_f32_16x16x32_bf16 v[78:81], v[118:121], v[190:193], v[78:81]
	v_mfma_f32_16x16x32_bf16 v[74:77], v[134:137], v[190:193], v[74:77]
	s_setprio 0
	s_setprio 1
	v_mfma_f32_16x16x32_bf16 v[126:129], v[138:141], v[162:165], v[126:129]
	v_mfma_f32_16x16x32_bf16 v[122:125], v[146:149], v[162:165], v[122:125]
	v_mfma_f32_16x16x32_bf16 v[102:105], v[138:141], v[170:173], v[102:105]
	v_mfma_f32_16x16x32_bf16 v[98:101], v[146:149], v[170:173], v[98:101]
	v_mfma_f32_16x16x32_bf16 v[86:89], v[138:141], v[178:181], v[86:89]
	v_mfma_f32_16x16x32_bf16 v[82:85], v[146:149], v[178:181], v[82:85]
	v_mfma_f32_16x16x32_bf16 v[70:73], v[138:141], v[186:189], v[70:73]
	v_mfma_f32_16x16x32_bf16 v[66:69], v[146:149], v[186:189], v[66:69]
	v_mfma_f32_16x16x32_bf16 v[126:129], v[142:145], v[166:169], v[126:129]
	v_mfma_f32_16x16x32_bf16 v[122:125], v[150:153], v[166:169], v[122:125]
	v_mfma_f32_16x16x32_bf16 v[102:105], v[142:145], v[174:177], v[102:105]
	v_mfma_f32_16x16x32_bf16 v[98:101], v[150:153], v[174:177], v[98:101]
	v_mfma_f32_16x16x32_bf16 v[86:89], v[142:145], v[182:185], v[86:89]
	v_mfma_f32_16x16x32_bf16 v[82:85], v[150:153], v[182:185], v[82:85]
	v_mfma_f32_16x16x32_bf16 v[70:73], v[142:145], v[190:193], v[70:73]
	v_mfma_f32_16x16x32_bf16 v[66:69], v[150:153], v[190:193], v[66:69]
	s_setprio 0
	s_barrier
	s_add_u32 vcc_lo, s82, 0xfff80080
	s_addc_u32 vcc_hi, s83, -1
	s_mov_b32 m0, s76
	s_nop 0
	global_load_lds_dwordx4 v206, vcc
	ds_read_b128 v[162:165], v244 offset:49152
	ds_read_b128 v[166:169], v244 offset:50176
	s_mov_b32 m0, s77
	s_add_i32 s82, s85, s69
	global_load_lds_dwordx4 v210, vcc
	ds_read_b128 v[170:173], v244 offset:51200
	ds_read_b128 v[174:177], v244 offset:52224
	s_add_u32 vcc_lo, s52, 0x80
	s_addc_u32 vcc_hi, s53, 0
	s_mov_b32 m0, s82
	s_nop 0
	global_load_lds_dwordx4 v208, vcc
	ds_read_b128 v[178:181], v244 offset:53248
	ds_read_b128 v[182:185], v244 offset:54272
	s_add_i32 m0, s82, 0x2000
	s_add_u32 s52, s52, 0x80080
	s_addc_u32 s53, s53, 0
	global_load_lds_dwordx4 v212, vcc
	ds_read_b128 v[186:189], v244 offset:55296
	ds_read_b128 v[190:193], v244 offset:56320
	s_add_i32 s82, s88, s69
	s_mov_b32 m0, s82
	s_nop 0
	global_load_lds_dwordx4 v208, s[52:53]
	s_add_i32 m0, s82, 0x2000
	s_nop 0
	global_load_lds_dwordx4 v212, s[52:53]
	s_waitcnt lgkmcnt(0)
	s_setprio 1
	v_mfma_f32_16x16x32_bf16 v[62:65], v[114:117], v[162:165], v[62:65]
	v_mfma_f32_16x16x32_bf16 v[58:61], v[130:133], v[162:165], v[58:61]
	v_mfma_f32_16x16x32_bf16 v[46:49], v[114:117], v[170:173], v[46:49]
	v_mfma_f32_16x16x32_bf16 v[42:45], v[130:133], v[170:173], v[42:45]
	s_waitcnt vmcnt(8)
	s_barrier
	v_mfma_f32_16x16x32_bf16 v[30:33], v[114:117], v[178:181], v[30:33]
	v_mfma_f32_16x16x32_bf16 v[26:29], v[130:133], v[178:181], v[26:29]
	v_mfma_f32_16x16x32_bf16 v[14:17], v[114:117], v[186:189], v[14:17]
	v_mfma_f32_16x16x32_bf16 v[10:13], v[130:133], v[186:189], v[10:13]
	v_mfma_f32_16x16x32_bf16 v[62:65], v[118:121], v[166:169], v[62:65]
	v_mfma_f32_16x16x32_bf16 v[58:61], v[134:137], v[166:169], v[58:61]
	v_mfma_f32_16x16x32_bf16 v[46:49], v[118:121], v[174:177], v[46:49]
	v_mfma_f32_16x16x32_bf16 v[42:45], v[134:137], v[174:177], v[42:45]
	v_mfma_f32_16x16x32_bf16 v[30:33], v[118:121], v[182:185], v[30:33]
	v_mfma_f32_16x16x32_bf16 v[26:29], v[134:137], v[182:185], v[26:29]
	v_mfma_f32_16x16x32_bf16 v[14:17], v[118:121], v[190:193], v[14:17]
	v_mfma_f32_16x16x32_bf16 v[10:13], v[134:137], v[190:193], v[10:13]
	s_setprio 0
	s_setprio 1
	v_mfma_f32_16x16x32_bf16 v[54:57], v[138:141], v[162:165], v[54:57]
	v_mfma_f32_16x16x32_bf16 v[50:53], v[146:149], v[162:165], v[50:53]
	v_mfma_f32_16x16x32_bf16 v[38:41], v[138:141], v[170:173], v[38:41]
	v_mfma_f32_16x16x32_bf16 v[34:37], v[146:149], v[170:173], v[34:37]
	v_mfma_f32_16x16x32_bf16 v[22:25], v[138:141], v[178:181], v[22:25]
	v_mfma_f32_16x16x32_bf16 v[18:21], v[146:149], v[178:181], v[18:21]
	v_mfma_f32_16x16x32_bf16 v[6:9], v[138:141], v[186:189], v[6:9]
	v_mfma_f32_16x16x32_bf16 v[2:5], v[146:149], v[186:189], v[2:5]
	v_mfma_f32_16x16x32_bf16 v[54:57], v[142:145], v[166:169], v[54:57]
	v_mfma_f32_16x16x32_bf16 v[50:53], v[150:153], v[166:169], v[50:53]
	v_mfma_f32_16x16x32_bf16 v[38:41], v[142:145], v[174:177], v[38:41]
	v_mfma_f32_16x16x32_bf16 v[34:37], v[150:153], v[174:177], v[34:37]
	v_mfma_f32_16x16x32_bf16 v[22:25], v[142:145], v[182:185], v[22:25]
	v_mfma_f32_16x16x32_bf16 v[18:21], v[150:153], v[182:185], v[18:21]
	v_mfma_f32_16x16x32_bf16 v[6:9], v[142:145], v[190:193], v[6:9]
	v_mfma_f32_16x16x32_bf16 v[2:5], v[150:153], v[190:193], v[2:5]
	s_setprio 0
	s_barrier
	s_add_i32 s84, s84, 2
	s_add_u32 s46, s46, 0x100
	s_addc_u32 s47, s47, 0
	s_add_u32 s80, s80, 0x100
	s_addc_u32 s81, s81, 0
	s_cmp_gt_u32 s84, 29
	s_cbranch_scc0 .LBB0_904
